# GEMM K-loops: the critical B(t+1) LDS-DMA pieces issued in the first 8 MFMA gaps after the barrier (one per two gaps, sharing them with the LDS reads)
# speedup vs baseline: 1.0343x; 1.0027x over previous
.Lgemm_p2_loop:
	v_mfma_f32_16x16x32_bf16 v[104:107], v[224:227], v[192:195], v[104:107]
	ds_read_b128 v[176:179], v172 offset:32768
	s_mov_b32 m0, s101
	v_mfma_f32_16x16x32_bf16 v[96:99], v[228:231], v[192:195], v[96:99]
	ds_read_b128 v[180:183], v172 offset:34816
	global_load_lds_dwordx4 v[138:139], off
	v_lshl_add_u64 v[138:139], v[138:139], 0, s[34:35]
	v_mfma_f32_16x16x32_bf16 v[108:111], v[232:235], v[192:195], v[108:111]
	ds_read_b128 v[184:187], v172 offset:36864
	s_add_u32 m0, s101, 0x2000
	v_mfma_f32_16x16x32_bf16 v[100:103], v[236:239], v[192:195], v[100:103]
	ds_read_b128 v[188:191], v172 offset:38912
	global_load_lds_dwordx4 v[140:141], off
	v_lshl_add_u64 v[140:141], v[140:141], 0, s[34:35]
	v_mfma_f32_16x16x32_bf16 v[72:75], v[224:227], v[196:199], v[72:75]
	ds_read_b128 v[208:211], v174 offset:32768
	s_add_u32 m0, s101, 0x4000
	v_mfma_f32_16x16x32_bf16 v[64:67], v[228:231], v[196:199], v[64:67]
	ds_read_b128 v[212:215], v174 offset:34816
	global_load_lds_dwordx4 v[250:251], off
	v_lshl_add_u64 v[250:251], v[250:251], 0, s[34:35]
	v_mfma_f32_16x16x32_bf16 v[76:79], v[232:235], v[196:199], v[76:79]
	ds_read_b128 v[216:219], v174 offset:36864
	s_add_u32 m0, s101, 0x6000
	v_mfma_f32_16x16x32_bf16 v[68:71], v[236:239], v[196:199], v[68:71]
	ds_read_b128 v[220:223], v174 offset:38912
	global_load_lds_dwordx4 v[252:253], off
	v_lshl_add_u64 v[252:253], v[252:253], 0, s[34:35]
	v_mfma_f32_16x16x32_bf16 v[40:43], v[224:227], v[200:203], v[40:43]
	v_mfma_f32_16x16x32_bf16 v[32:35], v[228:231], v[200:203], v[32:35]
	v_mfma_f32_16x16x32_bf16 v[44:47], v[232:235], v[200:203], v[44:47]
	v_mfma_f32_16x16x32_bf16 v[36:39], v[236:239], v[200:203], v[36:39]
	v_mfma_f32_16x16x32_bf16 v[8:11], v[224:227], v[204:207], v[8:11]
	v_mfma_f32_16x16x32_bf16 v[0:3], v[228:231], v[204:207], v[0:3]
	v_mfma_f32_16x16x32_bf16 v[12:15], v[232:235], v[204:207], v[12:15]
	v_mfma_f32_16x16x32_bf16 v[4:7], v[236:239], v[204:207], v[4:7]
	s_waitcnt lgkmcnt(0)
	v_mfma_f32_16x16x32_bf16 v[120:123], v[208:211], v[176:179], v[120:123]
	ds_read_b128 v[224:227], v174 offset:40960
	v_mfma_f32_16x16x32_bf16 v[112:115], v[212:215], v[176:179], v[112:115]
	ds_read_b128 v[228:231], v174 offset:43008
	v_mfma_f32_16x16x32_bf16 v[124:127], v[216:219], v[176:179], v[124:127]
	ds_read_b128 v[232:235], v174 offset:45056
	v_mfma_f32_16x16x32_bf16 v[116:119], v[220:223], v[176:179], v[116:119]
	ds_read_b128 v[236:239], v174 offset:47104
	v_mfma_f32_16x16x32_bf16 v[88:91], v[208:211], v[180:183], v[88:91]
	s_mov_b32 m0, s100
	v_mfma_f32_16x16x32_bf16 v[80:83], v[212:215], v[180:183], v[80:83]
	global_load_lds_dwordx4 v[240:241], off
	v_lshl_add_u64 v[240:241], v[240:241], 0, s[34:35]
	v_mfma_f32_16x16x32_bf16 v[92:95], v[216:219], v[180:183], v[92:95]
	s_add_u32 m0, s100, 0x2000
	v_mfma_f32_16x16x32_bf16 v[84:87], v[220:223], v[180:183], v[84:87]
	global_load_lds_dwordx4 v[242:243], off
	v_lshl_add_u64 v[242:243], v[242:243], 0, s[34:35]
	v_mfma_f32_16x16x32_bf16 v[56:59], v[208:211], v[184:187], v[56:59]
	s_add_u32 m0, s100, 0x4000
	v_mfma_f32_16x16x32_bf16 v[48:51], v[212:215], v[184:187], v[48:51]
	global_load_lds_dwordx4 v[244:245], off
	v_lshl_add_u64 v[244:245], v[244:245], 0, s[34:35]
	v_mfma_f32_16x16x32_bf16 v[60:63], v[216:219], v[184:187], v[60:63]
	s_add_u32 m0, s100, 0x6000
	v_mfma_f32_16x16x32_bf16 v[52:55], v[220:223], v[184:187], v[52:55]
	global_load_lds_dwordx4 v[246:247], off
	v_lshl_add_u64 v[246:247], v[246:247], 0, s[34:35]
	v_mfma_f32_16x16x32_bf16 v[24:27], v[208:211], v[188:191], v[24:27]
	v_mfma_f32_16x16x32_bf16 v[16:19], v[212:215], v[188:191], v[16:19]
	v_mfma_f32_16x16x32_bf16 v[28:31], v[216:219], v[188:191], v[28:31]
	v_mfma_f32_16x16x32_bf16 v[20:23], v[220:223], v[188:191], v[20:23]
	s_waitcnt lgkmcnt(0)
	v_mfma_f32_16x16x32_bf16 v[104:107], v[224:227], v[176:179], v[104:107]
	ds_read_b128 v[192:195], v173 offset:32768
	v_mfma_f32_16x16x32_bf16 v[96:99], v[228:231], v[176:179], v[96:99]
	ds_read_b128 v[196:199], v173 offset:34816
	v_mfma_f32_16x16x32_bf16 v[108:111], v[232:235], v[176:179], v[108:111]
	ds_read_b128 v[200:203], v173 offset:36864
	v_mfma_f32_16x16x32_bf16 v[100:103], v[236:239], v[176:179], v[100:103]
	ds_read_b128 v[204:207], v173 offset:38912
	v_mfma_f32_16x16x32_bf16 v[72:75], v[224:227], v[180:183], v[72:75]
	ds_read_b128 v[208:211], v175 offset:32768
	v_mfma_f32_16x16x32_bf16 v[64:67], v[228:231], v[180:183], v[64:67]
	ds_read_b128 v[212:215], v175 offset:34816
	v_mfma_f32_16x16x32_bf16 v[76:79], v[232:235], v[180:183], v[76:79]
	ds_read_b128 v[216:219], v175 offset:36864
	v_mfma_f32_16x16x32_bf16 v[68:71], v[236:239], v[180:183], v[68:71]
	ds_read_b128 v[220:223], v175 offset:38912
	v_mfma_f32_16x16x32_bf16 v[40:43], v[224:227], v[184:187], v[40:43]
	v_mfma_f32_16x16x32_bf16 v[32:35], v[228:231], v[184:187], v[32:35]
	v_mfma_f32_16x16x32_bf16 v[44:47], v[232:235], v[184:187], v[44:47]
	v_mfma_f32_16x16x32_bf16 v[36:39], v[236:239], v[184:187], v[36:39]
	v_mfma_f32_16x16x32_bf16 v[8:11], v[224:227], v[188:191], v[8:11]
	v_mfma_f32_16x16x32_bf16 v[0:3], v[228:231], v[188:191], v[0:3]
	v_mfma_f32_16x16x32_bf16 v[12:15], v[232:235], v[188:191], v[12:15]
	v_mfma_f32_16x16x32_bf16 v[4:7], v[236:239], v[188:191], v[4:7]
	s_waitcnt lgkmcnt(0)
	v_mfma_f32_16x16x32_bf16 v[120:123], v[208:211], v[192:195], v[120:123]
	ds_read_b128 v[224:227], v175 offset:40960
	v_mfma_f32_16x16x32_bf16 v[112:115], v[212:215], v[192:195], v[112:115]
	ds_read_b128 v[228:231], v175 offset:43008
	v_mfma_f32_16x16x32_bf16 v[124:127], v[216:219], v[192:195], v[124:127]
	ds_read_b128 v[232:235], v175 offset:45056
	v_mfma_f32_16x16x32_bf16 v[116:119], v[220:223], v[192:195], v[116:119]
	ds_read_b128 v[236:239], v175 offset:47104
	v_mfma_f32_16x16x32_bf16 v[88:91], v[208:211], v[196:199], v[88:91]
	v_mfma_f32_16x16x32_bf16 v[80:83], v[212:215], v[196:199], v[80:83]
	v_mfma_f32_16x16x32_bf16 v[92:95], v[216:219], v[196:199], v[92:95]
	v_mfma_f32_16x16x32_bf16 v[84:87], v[220:223], v[196:199], v[84:87]
	v_mfma_f32_16x16x32_bf16 v[56:59], v[208:211], v[200:203], v[56:59]
	v_mfma_f32_16x16x32_bf16 v[48:51], v[212:215], v[200:203], v[48:51]
	v_mfma_f32_16x16x32_bf16 v[60:63], v[216:219], v[200:203], v[60:63]
	v_mfma_f32_16x16x32_bf16 v[52:55], v[220:223], v[200:203], v[52:55]
	v_mfma_f32_16x16x32_bf16 v[24:27], v[208:211], v[204:207], v[24:27]
	v_mfma_f32_16x16x32_bf16 v[16:19], v[212:215], v[204:207], v[16:19]
	v_mfma_f32_16x16x32_bf16 v[28:31], v[216:219], v[204:207], v[28:31]
	v_mfma_f32_16x16x32_bf16 v[20:23], v[220:223], v[204:207], v[20:23]
	s_waitcnt lgkmcnt(0)
	s_waitcnt vmcnt(4)
	s_barrier
	v_mfma_f32_16x16x32_bf16 v[104:107], v[224:227], v[192:195], v[104:107]
	ds_read_b128 v[176:179], v254 offset:0
	s_add_u32 m0, s101, 0x8000
	v_mfma_f32_16x16x32_bf16 v[96:99], v[228:231], v[192:195], v[96:99]
	ds_read_b128 v[180:183], v254 offset:2048
	global_load_lds_dwordx4 v[138:139], off
	v_lshl_add_u64 v[138:139], v[138:139], 0, s[34:35]
	v_mfma_f32_16x16x32_bf16 v[108:111], v[232:235], v[192:195], v[108:111]
	ds_read_b128 v[184:187], v254 offset:4096
	s_add_u32 m0, s101, 0xa000
	v_mfma_f32_16x16x32_bf16 v[100:103], v[236:239], v[192:195], v[100:103]
	ds_read_b128 v[188:191], v254 offset:6144
	global_load_lds_dwordx4 v[140:141], off
	v_lshl_add_u64 v[140:141], v[140:141], 0, s[34:35]
	v_mfma_f32_16x16x32_bf16 v[72:75], v[224:227], v[196:199], v[72:75]
	ds_read_b128 v[208:211], v174 offset:0
	s_add_u32 m0, s101, 0xc000
	v_mfma_f32_16x16x32_bf16 v[64:67], v[228:231], v[196:199], v[64:67]
	ds_read_b128 v[212:215], v174 offset:2048
	global_load_lds_dwordx4 v[250:251], off
	v_lshl_add_u64 v[250:251], v[250:251], 0, s[34:35]
	v_mfma_f32_16x16x32_bf16 v[76:79], v[232:235], v[196:199], v[76:79]
	ds_read_b128 v[216:219], v174 offset:4096
	s_add_u32 m0, s101, 0xe000
	v_mfma_f32_16x16x32_bf16 v[68:71], v[236:239], v[196:199], v[68:71]
	ds_read_b128 v[220:223], v174 offset:6144
	global_load_lds_dwordx4 v[252:253], off
	v_lshl_add_u64 v[252:253], v[252:253], 0, s[34:35]
	v_mfma_f32_16x16x32_bf16 v[40:43], v[224:227], v[200:203], v[40:43]
	v_mfma_f32_16x16x32_bf16 v[32:35], v[228:231], v[200:203], v[32:35]
	v_mfma_f32_16x16x32_bf16 v[44:47], v[232:235], v[200:203], v[44:47]
	v_mfma_f32_16x16x32_bf16 v[36:39], v[236:239], v[200:203], v[36:39]
	v_mfma_f32_16x16x32_bf16 v[8:11], v[224:227], v[204:207], v[8:11]
	v_mfma_f32_16x16x32_bf16 v[0:3], v[228:231], v[204:207], v[0:3]
	v_mfma_f32_16x16x32_bf16 v[12:15], v[232:235], v[204:207], v[12:15]
	v_mfma_f32_16x16x32_bf16 v[4:7], v[236:239], v[204:207], v[4:7]
	s_waitcnt lgkmcnt(0)
	v_mfma_f32_16x16x32_bf16 v[120:123], v[208:211], v[176:179], v[120:123]
	ds_read_b128 v[224:227], v174 offset:8192
	v_mfma_f32_16x16x32_bf16 v[112:115], v[212:215], v[176:179], v[112:115]
	ds_read_b128 v[228:231], v174 offset:10240
	v_mfma_f32_16x16x32_bf16 v[124:127], v[216:219], v[176:179], v[124:127]
	ds_read_b128 v[232:235], v174 offset:12288
	v_mfma_f32_16x16x32_bf16 v[116:119], v[220:223], v[176:179], v[116:119]
	ds_read_b128 v[236:239], v174 offset:14336
	v_mfma_f32_16x16x32_bf16 v[88:91], v[208:211], v[180:183], v[88:91]
	s_add_u32 m0, s100, 0x8000
	v_mfma_f32_16x16x32_bf16 v[80:83], v[212:215], v[180:183], v[80:83]
	global_load_lds_dwordx4 v[240:241], off
	v_lshl_add_u64 v[240:241], v[240:241], 0, s[34:35]
	v_mfma_f32_16x16x32_bf16 v[92:95], v[216:219], v[180:183], v[92:95]
	s_add_u32 m0, s100, 0xa000
	v_mfma_f32_16x16x32_bf16 v[84:87], v[220:223], v[180:183], v[84:87]
	global_load_lds_dwordx4 v[242:243], off
	v_lshl_add_u64 v[242:243], v[242:243], 0, s[34:35]
	v_mfma_f32_16x16x32_bf16 v[56:59], v[208:211], v[184:187], v[56:59]
	s_add_u32 m0, s100, 0xc000
	v_mfma_f32_16x16x32_bf16 v[48:51], v[212:215], v[184:187], v[48:51]
	global_load_lds_dwordx4 v[244:245], off
	v_lshl_add_u64 v[244:245], v[244:245], 0, s[34:35]
	v_mfma_f32_16x16x32_bf16 v[60:63], v[216:219], v[184:187], v[60:63]
	s_add_u32 m0, s100, 0xe000
	v_mfma_f32_16x16x32_bf16 v[52:55], v[220:223], v[184:187], v[52:55]
	global_load_lds_dwordx4 v[246:247], off
	v_lshl_add_u64 v[246:247], v[246:247], 0, s[34:35]
	v_mfma_f32_16x16x32_bf16 v[24:27], v[208:211], v[188:191], v[24:27]
	v_mfma_f32_16x16x32_bf16 v[16:19], v[212:215], v[188:191], v[16:19]
	v_mfma_f32_16x16x32_bf16 v[28:31], v[216:219], v[188:191], v[28:31]
	v_mfma_f32_16x16x32_bf16 v[20:23], v[220:223], v[188:191], v[20:23]
	s_waitcnt lgkmcnt(0)
	v_mfma_f32_16x16x32_bf16 v[104:107], v[224:227], v[176:179], v[104:107]
	ds_read_b128 v[192:195], v255 offset:0
	v_mfma_f32_16x16x32_bf16 v[96:99], v[228:231], v[176:179], v[96:99]
	ds_read_b128 v[196:199], v255 offset:2048
	v_mfma_f32_16x16x32_bf16 v[108:111], v[232:235], v[176:179], v[108:111]
	ds_read_b128 v[200:203], v255 offset:4096
	v_mfma_f32_16x16x32_bf16 v[100:103], v[236:239], v[176:179], v[100:103]
	ds_read_b128 v[204:207], v255 offset:6144
	v_mfma_f32_16x16x32_bf16 v[72:75], v[224:227], v[180:183], v[72:75]
	ds_read_b128 v[208:211], v175 offset:0
	v_mfma_f32_16x16x32_bf16 v[64:67], v[228:231], v[180:183], v[64:67]
	ds_read_b128 v[212:215], v175 offset:2048
	v_mfma_f32_16x16x32_bf16 v[76:79], v[232:235], v[180:183], v[76:79]
	ds_read_b128 v[216:219], v175 offset:4096
	v_mfma_f32_16x16x32_bf16 v[68:71], v[236:239], v[180:183], v[68:71]
	ds_read_b128 v[220:223], v175 offset:6144
	v_mfma_f32_16x16x32_bf16 v[40:43], v[224:227], v[184:187], v[40:43]
	v_mfma_f32_16x16x32_bf16 v[32:35], v[228:231], v[184:187], v[32:35]
	v_mfma_f32_16x16x32_bf16 v[44:47], v[232:235], v[184:187], v[44:47]
	v_mfma_f32_16x16x32_bf16 v[36:39], v[236:239], v[184:187], v[36:39]
	v_mfma_f32_16x16x32_bf16 v[8:11], v[224:227], v[188:191], v[8:11]
	v_mfma_f32_16x16x32_bf16 v[0:3], v[228:231], v[188:191], v[0:3]
	v_mfma_f32_16x16x32_bf16 v[12:15], v[232:235], v[188:191], v[12:15]
	v_mfma_f32_16x16x32_bf16 v[4:7], v[236:239], v[188:191], v[4:7]
	s_waitcnt lgkmcnt(0)
	v_mfma_f32_16x16x32_bf16 v[120:123], v[208:211], v[192:195], v[120:123]
	ds_read_b128 v[224:227], v175 offset:8192
	v_mfma_f32_16x16x32_bf16 v[112:115], v[212:215], v[192:195], v[112:115]
	ds_read_b128 v[228:231], v175 offset:10240
	v_mfma_f32_16x16x32_bf16 v[124:127], v[216:219], v[192:195], v[124:127]
	ds_read_b128 v[232:235], v175 offset:12288
	v_mfma_f32_16x16x32_bf16 v[116:119], v[220:223], v[192:195], v[116:119]
	ds_read_b128 v[236:239], v175 offset:14336
	v_mfma_f32_16x16x32_bf16 v[88:91], v[208:211], v[196:199], v[88:91]
	v_mfma_f32_16x16x32_bf16 v[80:83], v[212:215], v[196:199], v[80:83]
	v_mfma_f32_16x16x32_bf16 v[92:95], v[216:219], v[196:199], v[92:95]
	v_mfma_f32_16x16x32_bf16 v[84:87], v[220:223], v[196:199], v[84:87]
	v_mfma_f32_16x16x32_bf16 v[56:59], v[208:211], v[200:203], v[56:59]
	v_mfma_f32_16x16x32_bf16 v[48:51], v[212:215], v[200:203], v[48:51]
	v_mfma_f32_16x16x32_bf16 v[60:63], v[216:219], v[200:203], v[60:63]
	v_mfma_f32_16x16x32_bf16 v[52:55], v[220:223], v[200:203], v[52:55]
	v_mfma_f32_16x16x32_bf16 v[24:27], v[208:211], v[204:207], v[24:27]
	v_mfma_f32_16x16x32_bf16 v[16:19], v[212:215], v[204:207], v[16:19]
	v_mfma_f32_16x16x32_bf16 v[28:31], v[216:219], v[204:207], v[28:31]
	v_mfma_f32_16x16x32_bf16 v[20:23], v[220:223], v[204:207], v[20:23]
	s_waitcnt lgkmcnt(0)
	s_waitcnt vmcnt(4)
	s_barrier
	v_mfma_f32_16x16x32_bf16 v[104:107], v[224:227], v[192:195], v[104:107]
	ds_read_b128 v[176:179], v172 offset:0
	s_mov_b32 m0, s101
	v_mfma_f32_16x16x32_bf16 v[96:99], v[228:231], v[192:195], v[96:99]
	ds_read_b128 v[180:183], v172 offset:2048
	global_load_lds_dwordx4 v[138:139], off
	v_lshl_add_u64 v[138:139], v[138:139], 0, s[34:35]
	v_mfma_f32_16x16x32_bf16 v[108:111], v[232:235], v[192:195], v[108:111]
	ds_read_b128 v[184:187], v172 offset:4096
	s_add_u32 m0, s101, 0x2000
	v_mfma_f32_16x16x32_bf16 v[100:103], v[236:239], v[192:195], v[100:103]
	ds_read_b128 v[188:191], v172 offset:6144
	global_load_lds_dwordx4 v[140:141], off
	v_lshl_add_u64 v[140:141], v[140:141], 0, s[34:35]
	v_mfma_f32_16x16x32_bf16 v[72:75], v[224:227], v[196:199], v[72:75]
	ds_read_b128 v[208:211], v174 offset:32768
	s_add_u32 m0, s101, 0x4000
	v_mfma_f32_16x16x32_bf16 v[64:67], v[228:231], v[196:199], v[64:67]
	ds_read_b128 v[212:215], v174 offset:34816
	global_load_lds_dwordx4 v[250:251], off
	v_lshl_add_u64 v[250:251], v[250:251], 0, s[34:35]
	v_mfma_f32_16x16x32_bf16 v[76:79], v[232:235], v[196:199], v[76:79]
	ds_read_b128 v[216:219], v174 offset:36864
	s_add_u32 m0, s101, 0x6000
	v_mfma_f32_16x16x32_bf16 v[68:71], v[236:239], v[196:199], v[68:71]
	ds_read_b128 v[220:223], v174 offset:38912
	global_load_lds_dwordx4 v[252:253], off
	v_lshl_add_u64 v[252:253], v[252:253], 0, s[34:35]
	v_mfma_f32_16x16x32_bf16 v[40:43], v[224:227], v[200:203], v[40:43]
	v_mfma_f32_16x16x32_bf16 v[32:35], v[228:231], v[200:203], v[32:35]
	v_mfma_f32_16x16x32_bf16 v[44:47], v[232:235], v[200:203], v[44:47]
	v_mfma_f32_16x16x32_bf16 v[36:39], v[236:239], v[200:203], v[36:39]
	v_mfma_f32_16x16x32_bf16 v[8:11], v[224:227], v[204:207], v[8:11]
	v_mfma_f32_16x16x32_bf16 v[0:3], v[228:231], v[204:207], v[0:3]
	v_mfma_f32_16x16x32_bf16 v[12:15], v[232:235], v[204:207], v[12:15]
	v_mfma_f32_16x16x32_bf16 v[4:7], v[236:239], v[204:207], v[4:7]
	s_waitcnt lgkmcnt(0)
	v_mfma_f32_16x16x32_bf16 v[120:123], v[208:211], v[176:179], v[120:123]
	ds_read_b128 v[224:227], v174 offset:40960
	v_mfma_f32_16x16x32_bf16 v[112:115], v[212:215], v[176:179], v[112:115]
	ds_read_b128 v[228:231], v174 offset:43008
	v_mfma_f32_16x16x32_bf16 v[124:127], v[216:219], v[176:179], v[124:127]
	ds_read_b128 v[232:235], v174 offset:45056
	v_mfma_f32_16x16x32_bf16 v[116:119], v[220:223], v[176:179], v[116:119]
	ds_read_b128 v[236:239], v174 offset:47104
	v_mfma_f32_16x16x32_bf16 v[88:91], v[208:211], v[180:183], v[88:91]
	s_add_u32 m0, s100, 0x20000
	v_mfma_f32_16x16x32_bf16 v[80:83], v[212:215], v[180:183], v[80:83]
	global_load_lds_dwordx4 v[240:241], off
	v_lshl_add_u64 v[240:241], v[240:241], 0, s[34:35]
	v_mfma_f32_16x16x32_bf16 v[92:95], v[216:219], v[180:183], v[92:95]
	s_add_u32 m0, s100, 0x22000
	v_mfma_f32_16x16x32_bf16 v[84:87], v[220:223], v[180:183], v[84:87]
	global_load_lds_dwordx4 v[242:243], off
	v_lshl_add_u64 v[242:243], v[242:243], 0, s[34:35]
	v_mfma_f32_16x16x32_bf16 v[56:59], v[208:211], v[184:187], v[56:59]
	s_add_u32 m0, s100, 0x24000
	v_mfma_f32_16x16x32_bf16 v[48:51], v[212:215], v[184:187], v[48:51]
	global_load_lds_dwordx4 v[244:245], off
	v_lshl_add_u64 v[244:245], v[244:245], 0, s[34:35]
	v_mfma_f32_16x16x32_bf16 v[60:63], v[216:219], v[184:187], v[60:63]
	s_add_u32 m0, s100, 0x26000
	v_mfma_f32_16x16x32_bf16 v[52:55], v[220:223], v[184:187], v[52:55]
	global_load_lds_dwordx4 v[246:247], off
	v_lshl_add_u64 v[246:247], v[246:247], 0, s[34:35]
	v_mfma_f32_16x16x32_bf16 v[24:27], v[208:211], v[188:191], v[24:27]
	v_mfma_f32_16x16x32_bf16 v[16:19], v[212:215], v[188:191], v[16:19]
	v_mfma_f32_16x16x32_bf16 v[28:31], v[216:219], v[188:191], v[28:31]
	v_mfma_f32_16x16x32_bf16 v[20:23], v[220:223], v[188:191], v[20:23]
	s_waitcnt lgkmcnt(0)
	v_mfma_f32_16x16x32_bf16 v[104:107], v[224:227], v[176:179], v[104:107]
	ds_read_b128 v[192:195], v173 offset:0
	v_mfma_f32_16x16x32_bf16 v[96:99], v[228:231], v[176:179], v[96:99]
	ds_read_b128 v[196:199], v173 offset:2048
	v_mfma_f32_16x16x32_bf16 v[108:111], v[232:235], v[176:179], v[108:111]
	ds_read_b128 v[200:203], v173 offset:4096
	v_mfma_f32_16x16x32_bf16 v[100:103], v[236:239], v[176:179], v[100:103]
	ds_read_b128 v[204:207], v173 offset:6144
	v_mfma_f32_16x16x32_bf16 v[72:75], v[224:227], v[180:183], v[72:75]
	ds_read_b128 v[208:211], v175 offset:32768
	v_mfma_f32_16x16x32_bf16 v[64:67], v[228:231], v[180:183], v[64:67]
	ds_read_b128 v[212:215], v175 offset:34816
	v_mfma_f32_16x16x32_bf16 v[76:79], v[232:235], v[180:183], v[76:79]
	ds_read_b128 v[216:219], v175 offset:36864
	v_mfma_f32_16x16x32_bf16 v[68:71], v[236:239], v[180:183], v[68:71]
	ds_read_b128 v[220:223], v175 offset:38912
	v_mfma_f32_16x16x32_bf16 v[40:43], v[224:227], v[184:187], v[40:43]
	v_mfma_f32_16x16x32_bf16 v[32:35], v[228:231], v[184:187], v[32:35]
	v_mfma_f32_16x16x32_bf16 v[44:47], v[232:235], v[184:187], v[44:47]
	v_mfma_f32_16x16x32_bf16 v[36:39], v[236:239], v[184:187], v[36:39]
	v_mfma_f32_16x16x32_bf16 v[8:11], v[224:227], v[188:191], v[8:11]
	v_mfma_f32_16x16x32_bf16 v[0:3], v[228:231], v[188:191], v[0:3]
	v_mfma_f32_16x16x32_bf16 v[12:15], v[232:235], v[188:191], v[12:15]
	v_mfma_f32_16x16x32_bf16 v[4:7], v[236:239], v[188:191], v[4:7]
	s_waitcnt lgkmcnt(0)
	v_mfma_f32_16x16x32_bf16 v[120:123], v[208:211], v[192:195], v[120:123]
	ds_read_b128 v[224:227], v175 offset:40960
	v_mfma_f32_16x16x32_bf16 v[112:115], v[212:215], v[192:195], v[112:115]
	ds_read_b128 v[228:231], v175 offset:43008
	v_mfma_f32_16x16x32_bf16 v[124:127], v[216:219], v[192:195], v[124:127]
	ds_read_b128 v[232:235], v175 offset:45056
	v_mfma_f32_16x16x32_bf16 v[116:119], v[220:223], v[192:195], v[116:119]
	ds_read_b128 v[236:239], v175 offset:47104
	v_mfma_f32_16x16x32_bf16 v[88:91], v[208:211], v[196:199], v[88:91]
	v_mfma_f32_16x16x32_bf16 v[80:83], v[212:215], v[196:199], v[80:83]
	v_mfma_f32_16x16x32_bf16 v[92:95], v[216:219], v[196:199], v[92:95]
	v_mfma_f32_16x16x32_bf16 v[84:87], v[220:223], v[196:199], v[84:87]
	v_mfma_f32_16x16x32_bf16 v[56:59], v[208:211], v[200:203], v[56:59]
	v_mfma_f32_16x16x32_bf16 v[48:51], v[212:215], v[200:203], v[48:51]
	v_mfma_f32_16x16x32_bf16 v[60:63], v[216:219], v[200:203], v[60:63]
	v_mfma_f32_16x16x32_bf16 v[52:55], v[220:223], v[200:203], v[52:55]
	v_mfma_f32_16x16x32_bf16 v[24:27], v[208:211], v[204:207], v[24:27]
	v_mfma_f32_16x16x32_bf16 v[16:19], v[212:215], v[204:207], v[16:19]
	v_mfma_f32_16x16x32_bf16 v[28:31], v[216:219], v[204:207], v[28:31]
	v_mfma_f32_16x16x32_bf16 v[20:23], v[220:223], v[204:207], v[20:23]
	s_waitcnt lgkmcnt(0)
	s_waitcnt vmcnt(4)
	s_barrier
	v_mfma_f32_16x16x32_bf16 v[104:107], v[224:227], v[192:195], v[104:107]
	ds_read_b128 v[176:179], v172 offset:32768
	s_add_u32 m0, s101, 0x8000
	v_mfma_f32_16x16x32_bf16 v[96:99], v[228:231], v[192:195], v[96:99]
	ds_read_b128 v[180:183], v172 offset:34816
	global_load_lds_dwordx4 v[138:139], off
	v_lshl_add_u64 v[138:139], v[138:139], 0, s[34:35]
	v_mfma_f32_16x16x32_bf16 v[108:111], v[232:235], v[192:195], v[108:111]
	ds_read_b128 v[184:187], v172 offset:36864
	s_add_u32 m0, s101, 0xa000
	v_mfma_f32_16x16x32_bf16 v[100:103], v[236:239], v[192:195], v[100:103]
	ds_read_b128 v[188:191], v172 offset:38912
	global_load_lds_dwordx4 v[140:141], off
	v_lshl_add_u64 v[140:141], v[140:141], 0, s[34:35]
	v_mfma_f32_16x16x32_bf16 v[72:75], v[224:227], v[196:199], v[72:75]
	ds_read_b128 v[208:211], v174 offset:0
	s_add_u32 m0, s101, 0xc000
	v_mfma_f32_16x16x32_bf16 v[64:67], v[228:231], v[196:199], v[64:67]
	ds_read_b128 v[212:215], v174 offset:2048
	global_load_lds_dwordx4 v[250:251], off
	v_lshl_add_u64 v[250:251], v[250:251], 0, s[34:35]
	v_mfma_f32_16x16x32_bf16 v[76:79], v[232:235], v[196:199], v[76:79]
	ds_read_b128 v[216:219], v174 offset:4096
	s_add_u32 m0, s101, 0xe000
	v_mfma_f32_16x16x32_bf16 v[68:71], v[236:239], v[196:199], v[68:71]
	ds_read_b128 v[220:223], v174 offset:6144
	global_load_lds_dwordx4 v[252:253], off
	v_lshl_add_u64 v[252:253], v[252:253], 0, s[34:35]
	v_mfma_f32_16x16x32_bf16 v[40:43], v[224:227], v[200:203], v[40:43]
	v_mfma_f32_16x16x32_bf16 v[32:35], v[228:231], v[200:203], v[32:35]
	v_mfma_f32_16x16x32_bf16 v[44:47], v[232:235], v[200:203], v[44:47]
	v_mfma_f32_16x16x32_bf16 v[36:39], v[236:239], v[200:203], v[36:39]
	v_mfma_f32_16x16x32_bf16 v[8:11], v[224:227], v[204:207], v[8:11]
	v_mfma_f32_16x16x32_bf16 v[0:3], v[228:231], v[204:207], v[0:3]
	v_mfma_f32_16x16x32_bf16 v[12:15], v[232:235], v[204:207], v[12:15]
	v_mfma_f32_16x16x32_bf16 v[4:7], v[236:239], v[204:207], v[4:7]
	s_waitcnt lgkmcnt(0)
	v_mfma_f32_16x16x32_bf16 v[120:123], v[208:211], v[176:179], v[120:123]
	ds_read_b128 v[224:227], v174 offset:8192
	v_mfma_f32_16x16x32_bf16 v[112:115], v[212:215], v[176:179], v[112:115]
	ds_read_b128 v[228:231], v174 offset:10240
	v_mfma_f32_16x16x32_bf16 v[124:127], v[216:219], v[176:179], v[124:127]
	ds_read_b128 v[232:235], v174 offset:12288
	v_mfma_f32_16x16x32_bf16 v[116:119], v[220:223], v[176:179], v[116:119]
	ds_read_b128 v[236:239], v174 offset:14336
	v_mfma_f32_16x16x32_bf16 v[88:91], v[208:211], v[180:183], v[88:91]
	s_mov_b32 m0, s100
	v_mfma_f32_16x16x32_bf16 v[80:83], v[212:215], v[180:183], v[80:83]
	global_load_lds_dwordx4 v[240:241], off
	v_lshl_add_u64 v[240:241], v[240:241], 0, s[34:35]
	v_mfma_f32_16x16x32_bf16 v[92:95], v[216:219], v[180:183], v[92:95]
	s_add_u32 m0, s100, 0x2000
	v_mfma_f32_16x16x32_bf16 v[84:87], v[220:223], v[180:183], v[84:87]
	global_load_lds_dwordx4 v[242:243], off
	v_lshl_add_u64 v[242:243], v[242:243], 0, s[34:35]
	v_mfma_f32_16x16x32_bf16 v[56:59], v[208:211], v[184:187], v[56:59]
	s_add_u32 m0, s100, 0x4000
	v_mfma_f32_16x16x32_bf16 v[48:51], v[212:215], v[184:187], v[48:51]
	global_load_lds_dwordx4 v[244:245], off
	v_lshl_add_u64 v[244:245], v[244:245], 0, s[34:35]
	v_mfma_f32_16x16x32_bf16 v[60:63], v[216:219], v[184:187], v[60:63]
	s_add_u32 m0, s100, 0x6000
	v_mfma_f32_16x16x32_bf16 v[52:55], v[220:223], v[184:187], v[52:55]
	global_load_lds_dwordx4 v[246:247], off
	v_lshl_add_u64 v[246:247], v[246:247], 0, s[34:35]
	v_mfma_f32_16x16x32_bf16 v[24:27], v[208:211], v[188:191], v[24:27]
	v_mfma_f32_16x16x32_bf16 v[16:19], v[212:215], v[188:191], v[16:19]
	v_mfma_f32_16x16x32_bf16 v[28:31], v[216:219], v[188:191], v[28:31]
	v_mfma_f32_16x16x32_bf16 v[20:23], v[220:223], v[188:191], v[20:23]
	s_waitcnt lgkmcnt(0)
	v_mfma_f32_16x16x32_bf16 v[104:107], v[224:227], v[176:179], v[104:107]
	ds_read_b128 v[192:195], v173 offset:32768
	v_mfma_f32_16x16x32_bf16 v[96:99], v[228:231], v[176:179], v[96:99]
	ds_read_b128 v[196:199], v173 offset:34816
	v_mfma_f32_16x16x32_bf16 v[108:111], v[232:235], v[176:179], v[108:111]
	ds_read_b128 v[200:203], v173 offset:36864
	v_mfma_f32_16x16x32_bf16 v[100:103], v[236:239], v[176:179], v[100:103]
	ds_read_b128 v[204:207], v173 offset:38912
	v_mfma_f32_16x16x32_bf16 v[72:75], v[224:227], v[180:183], v[72:75]
	ds_read_b128 v[208:211], v175 offset:0
	v_mfma_f32_16x16x32_bf16 v[64:67], v[228:231], v[180:183], v[64:67]
	ds_read_b128 v[212:215], v175 offset:2048
	v_mfma_f32_16x16x32_bf16 v[76:79], v[232:235], v[180:183], v[76:79]
	ds_read_b128 v[216:219], v175 offset:4096
	v_mfma_f32_16x16x32_bf16 v[68:71], v[236:239], v[180:183], v[68:71]
	ds_read_b128 v[220:223], v175 offset:6144
	v_mfma_f32_16x16x32_bf16 v[40:43], v[224:227], v[184:187], v[40:43]
	v_mfma_f32_16x16x32_bf16 v[32:35], v[228:231], v[184:187], v[32:35]
	v_mfma_f32_16x16x32_bf16 v[44:47], v[232:235], v[184:187], v[44:47]
	v_mfma_f32_16x16x32_bf16 v[36:39], v[236:239], v[184:187], v[36:39]
	v_mfma_f32_16x16x32_bf16 v[8:11], v[224:227], v[188:191], v[8:11]
	v_mfma_f32_16x16x32_bf16 v[0:3], v[228:231], v[188:191], v[0:3]
	v_mfma_f32_16x16x32_bf16 v[12:15], v[232:235], v[188:191], v[12:15]
	v_mfma_f32_16x16x32_bf16 v[4:7], v[236:239], v[188:191], v[4:7]
	s_waitcnt lgkmcnt(0)
	v_mfma_f32_16x16x32_bf16 v[120:123], v[208:211], v[192:195], v[120:123]
	ds_read_b128 v[224:227], v175 offset:8192
	v_mfma_f32_16x16x32_bf16 v[112:115], v[212:215], v[192:195], v[112:115]
	ds_read_b128 v[228:231], v175 offset:10240
	v_mfma_f32_16x16x32_bf16 v[124:127], v[216:219], v[192:195], v[124:127]
	ds_read_b128 v[232:235], v175 offset:12288
	v_mfma_f32_16x16x32_bf16 v[116:119], v[220:223], v[192:195], v[116:119]
	ds_read_b128 v[236:239], v175 offset:14336
	v_mfma_f32_16x16x32_bf16 v[88:91], v[208:211], v[196:199], v[88:91]
	v_mfma_f32_16x16x32_bf16 v[80:83], v[212:215], v[196:199], v[80:83]
	v_mfma_f32_16x16x32_bf16 v[92:95], v[216:219], v[196:199], v[92:95]
	v_mfma_f32_16x16x32_bf16 v[84:87], v[220:223], v[196:199], v[84:87]
	v_mfma_f32_16x16x32_bf16 v[56:59], v[208:211], v[200:203], v[56:59]
	v_mfma_f32_16x16x32_bf16 v[48:51], v[212:215], v[200:203], v[48:51]
	v_mfma_f32_16x16x32_bf16 v[60:63], v[216:219], v[200:203], v[60:63]
	v_mfma_f32_16x16x32_bf16 v[52:55], v[220:223], v[200:203], v[52:55]
	v_mfma_f32_16x16x32_bf16 v[24:27], v[208:211], v[204:207], v[24:27]
	v_mfma_f32_16x16x32_bf16 v[16:19], v[212:215], v[204:207], v[16:19]
	v_mfma_f32_16x16x32_bf16 v[28:31], v[216:219], v[204:207], v[28:31]
	v_mfma_f32_16x16x32_bf16 v[20:23], v[220:223], v[204:207], v[20:23]
	s_waitcnt lgkmcnt(0)
	s_waitcnt vmcnt(4)
	s_barrier
	v_mfma_f32_16x16x32_bf16 v[104:107], v[224:227], v[192:195], v[104:107]
	ds_read_b128 v[176:179], v254 offset:0
	s_mov_b32 m0, s101
	v_mfma_f32_16x16x32_bf16 v[96:99], v[228:231], v[192:195], v[96:99]
	ds_read_b128 v[180:183], v254 offset:2048
	global_load_lds_dwordx4 v[138:139], off
	v_lshl_add_u64 v[138:139], v[138:139], 0, s[34:35]
	v_mfma_f32_16x16x32_bf16 v[108:111], v[232:235], v[192:195], v[108:111]
	ds_read_b128 v[184:187], v254 offset:4096
	s_add_u32 m0, s101, 0x2000
	v_mfma_f32_16x16x32_bf16 v[100:103], v[236:239], v[192:195], v[100:103]
	ds_read_b128 v[188:191], v254 offset:6144
	global_load_lds_dwordx4 v[140:141], off
	v_lshl_add_u64 v[140:141], v[140:141], 0, s[34:35]
	v_mfma_f32_16x16x32_bf16 v[72:75], v[224:227], v[196:199], v[72:75]
	ds_read_b128 v[208:211], v174 offset:32768
	s_add_u32 m0, s101, 0x4000
	v_mfma_f32_16x16x32_bf16 v[64:67], v[228:231], v[196:199], v[64:67]
	ds_read_b128 v[212:215], v174 offset:34816
	global_load_lds_dwordx4 v[250:251], off
	v_lshl_add_u64 v[250:251], v[250:251], 0, s[34:35]
	v_mfma_f32_16x16x32_bf16 v[76:79], v[232:235], v[196:199], v[76:79]
	ds_read_b128 v[216:219], v174 offset:36864
	s_add_u32 m0, s101, 0x6000
	v_mfma_f32_16x16x32_bf16 v[68:71], v[236:239], v[196:199], v[68:71]
	ds_read_b128 v[220:223], v174 offset:38912
	global_load_lds_dwordx4 v[252:253], off
	v_lshl_add_u64 v[252:253], v[252:253], 0, s[34:35]
	v_mfma_f32_16x16x32_bf16 v[40:43], v[224:227], v[200:203], v[40:43]
	v_mfma_f32_16x16x32_bf16 v[32:35], v[228:231], v[200:203], v[32:35]
	v_mfma_f32_16x16x32_bf16 v[44:47], v[232:235], v[200:203], v[44:47]
	v_mfma_f32_16x16x32_bf16 v[36:39], v[236:239], v[200:203], v[36:39]
	v_mfma_f32_16x16x32_bf16 v[8:11], v[224:227], v[204:207], v[8:11]
	v_mfma_f32_16x16x32_bf16 v[0:3], v[228:231], v[204:207], v[0:3]
	v_mfma_f32_16x16x32_bf16 v[12:15], v[232:235], v[204:207], v[12:15]
	v_mfma_f32_16x16x32_bf16 v[4:7], v[236:239], v[204:207], v[4:7]
	s_waitcnt lgkmcnt(0)
	v_mfma_f32_16x16x32_bf16 v[120:123], v[208:211], v[176:179], v[120:123]
	ds_read_b128 v[224:227], v174 offset:40960
	v_mfma_f32_16x16x32_bf16 v[112:115], v[212:215], v[176:179], v[112:115]
	ds_read_b128 v[228:231], v174 offset:43008
	v_mfma_f32_16x16x32_bf16 v[124:127], v[216:219], v[176:179], v[124:127]
	ds_read_b128 v[232:235], v174 offset:45056
	v_mfma_f32_16x16x32_bf16 v[116:119], v[220:223], v[176:179], v[116:119]
	ds_read_b128 v[236:239], v174 offset:47104
	v_mfma_f32_16x16x32_bf16 v[88:91], v[208:211], v[180:183], v[88:91]
	s_add_u32 m0, s100, 0x8000
	v_mfma_f32_16x16x32_bf16 v[80:83], v[212:215], v[180:183], v[80:83]
	global_load_lds_dwordx4 v[240:241], off
	v_lshl_add_u64 v[240:241], v[240:241], 0, s[34:35]
	v_mfma_f32_16x16x32_bf16 v[92:95], v[216:219], v[180:183], v[92:95]
	s_add_u32 m0, s100, 0xa000
	v_mfma_f32_16x16x32_bf16 v[84:87], v[220:223], v[180:183], v[84:87]
	global_load_lds_dwordx4 v[242:243], off
	v_lshl_add_u64 v[242:243], v[242:243], 0, s[34:35]
	v_mfma_f32_16x16x32_bf16 v[56:59], v[208:211], v[184:187], v[56:59]
	s_add_u32 m0, s100, 0xc000
	v_mfma_f32_16x16x32_bf16 v[48:51], v[212:215], v[184:187], v[48:51]
	global_load_lds_dwordx4 v[244:245], off
	v_lshl_add_u64 v[244:245], v[244:245], 0, s[34:35]
	v_mfma_f32_16x16x32_bf16 v[60:63], v[216:219], v[184:187], v[60:63]
	s_add_u32 m0, s100, 0xe000
	v_mfma_f32_16x16x32_bf16 v[52:55], v[220:223], v[184:187], v[52:55]
	global_load_lds_dwordx4 v[246:247], off
	v_lshl_add_u64 v[246:247], v[246:247], 0, s[34:35]
	v_mfma_f32_16x16x32_bf16 v[24:27], v[208:211], v[188:191], v[24:27]
	v_mfma_f32_16x16x32_bf16 v[16:19], v[212:215], v[188:191], v[16:19]
	v_mfma_f32_16x16x32_bf16 v[28:31], v[216:219], v[188:191], v[28:31]
	v_mfma_f32_16x16x32_bf16 v[20:23], v[220:223], v[188:191], v[20:23]
	s_waitcnt lgkmcnt(0)
	v_mfma_f32_16x16x32_bf16 v[104:107], v[224:227], v[176:179], v[104:107]
	ds_read_b128 v[192:195], v255 offset:0
	v_mfma_f32_16x16x32_bf16 v[96:99], v[228:231], v[176:179], v[96:99]
	ds_read_b128 v[196:199], v255 offset:2048
	v_mfma_f32_16x16x32_bf16 v[108:111], v[232:235], v[176:179], v[108:111]
	ds_read_b128 v[200:203], v255 offset:4096
	v_mfma_f32_16x16x32_bf16 v[100:103], v[236:239], v[176:179], v[100:103]
	ds_read_b128 v[204:207], v255 offset:6144
	v_mfma_f32_16x16x32_bf16 v[72:75], v[224:227], v[180:183], v[72:75]
	ds_read_b128 v[208:211], v175 offset:32768
	v_mfma_f32_16x16x32_bf16 v[64:67], v[228:231], v[180:183], v[64:67]
	ds_read_b128 v[212:215], v175 offset:34816
	v_mfma_f32_16x16x32_bf16 v[76:79], v[232:235], v[180:183], v[76:79]
	ds_read_b128 v[216:219], v175 offset:36864
	v_mfma_f32_16x16x32_bf16 v[68:71], v[236:239], v[180:183], v[68:71]
	ds_read_b128 v[220:223], v175 offset:38912
	v_mfma_f32_16x16x32_bf16 v[40:43], v[224:227], v[184:187], v[40:43]
	v_mfma_f32_16x16x32_bf16 v[32:35], v[228:231], v[184:187], v[32:35]
	v_mfma_f32_16x16x32_bf16 v[44:47], v[232:235], v[184:187], v[44:47]
	v_mfma_f32_16x16x32_bf16 v[36:39], v[236:239], v[184:187], v[36:39]
	v_mfma_f32_16x16x32_bf16 v[8:11], v[224:227], v[188:191], v[8:11]
	v_mfma_f32_16x16x32_bf16 v[0:3], v[228:231], v[188:191], v[0:3]
	v_mfma_f32_16x16x32_bf16 v[12:15], v[232:235], v[188:191], v[12:15]
	v_mfma_f32_16x16x32_bf16 v[4:7], v[236:239], v[188:191], v[4:7]
	s_waitcnt lgkmcnt(0)
	v_mfma_f32_16x16x32_bf16 v[120:123], v[208:211], v[192:195], v[120:123]
	ds_read_b128 v[224:227], v175 offset:40960
	v_mfma_f32_16x16x32_bf16 v[112:115], v[212:215], v[192:195], v[112:115]
	ds_read_b128 v[228:231], v175 offset:43008
	v_mfma_f32_16x16x32_bf16 v[124:127], v[216:219], v[192:195], v[124:127]
	ds_read_b128 v[232:235], v175 offset:45056
	v_mfma_f32_16x16x32_bf16 v[116:119], v[220:223], v[192:195], v[116:119]
	ds_read_b128 v[236:239], v175 offset:47104
	v_mfma_f32_16x16x32_bf16 v[88:91], v[208:211], v[196:199], v[88:91]
	v_mfma_f32_16x16x32_bf16 v[80:83], v[212:215], v[196:199], v[80:83]
	v_mfma_f32_16x16x32_bf16 v[92:95], v[216:219], v[196:199], v[92:95]
	v_mfma_f32_16x16x32_bf16 v[84:87], v[220:223], v[196:199], v[84:87]
	v_mfma_f32_16x16x32_bf16 v[56:59], v[208:211], v[200:203], v[56:59]
	v_mfma_f32_16x16x32_bf16 v[48:51], v[212:215], v[200:203], v[48:51]
	v_mfma_f32_16x16x32_bf16 v[60:63], v[216:219], v[200:203], v[60:63]
	v_mfma_f32_16x16x32_bf16 v[52:55], v[220:223], v[200:203], v[52:55]
	v_mfma_f32_16x16x32_bf16 v[24:27], v[208:211], v[204:207], v[24:27]
	v_mfma_f32_16x16x32_bf16 v[16:19], v[212:215], v[204:207], v[16:19]
	v_mfma_f32_16x16x32_bf16 v[28:31], v[216:219], v[204:207], v[28:31]
	v_mfma_f32_16x16x32_bf16 v[20:23], v[220:223], v[204:207], v[20:23]
	s_waitcnt lgkmcnt(0)
	s_waitcnt vmcnt(4)
	s_barrier
	v_mfma_f32_16x16x32_bf16 v[104:107], v[224:227], v[192:195], v[104:107]
	ds_read_b128 v[176:179], v172 offset:0
	s_add_u32 m0, s101, 0x8000
	v_mfma_f32_16x16x32_bf16 v[96:99], v[228:231], v[192:195], v[96:99]
	ds_read_b128 v[180:183], v172 offset:2048
	global_load_lds_dwordx4 v[138:139], off
	v_lshl_add_u64 v[138:139], v[138:139], 0, s[34:35]
	v_mfma_f32_16x16x32_bf16 v[108:111], v[232:235], v[192:195], v[108:111]
	ds_read_b128 v[184:187], v172 offset:4096
	s_add_u32 m0, s101, 0xa000
	v_mfma_f32_16x16x32_bf16 v[100:103], v[236:239], v[192:195], v[100:103]
	ds_read_b128 v[188:191], v172 offset:6144
	global_load_lds_dwordx4 v[140:141], off
	v_lshl_add_u64 v[140:141], v[140:141], 0, s[34:35]
	v_mfma_f32_16x16x32_bf16 v[72:75], v[224:227], v[196:199], v[72:75]
	ds_read_b128 v[208:211], v174 offset:0
	s_add_u32 m0, s101, 0xc000
	v_mfma_f32_16x16x32_bf16 v[64:67], v[228:231], v[196:199], v[64:67]
	ds_read_b128 v[212:215], v174 offset:2048
	global_load_lds_dwordx4 v[250:251], off
	v_lshl_add_u64 v[250:251], v[250:251], 0, s[34:35]
	v_mfma_f32_16x16x32_bf16 v[76:79], v[232:235], v[196:199], v[76:79]
	ds_read_b128 v[216:219], v174 offset:4096
	s_add_u32 m0, s101, 0xe000
	v_mfma_f32_16x16x32_bf16 v[68:71], v[236:239], v[196:199], v[68:71]
	ds_read_b128 v[220:223], v174 offset:6144
	global_load_lds_dwordx4 v[252:253], off
	v_lshl_add_u64 v[252:253], v[252:253], 0, s[34:35]
	v_mfma_f32_16x16x32_bf16 v[40:43], v[224:227], v[200:203], v[40:43]
	v_mfma_f32_16x16x32_bf16 v[32:35], v[228:231], v[200:203], v[32:35]
	v_mfma_f32_16x16x32_bf16 v[44:47], v[232:235], v[200:203], v[44:47]
	v_mfma_f32_16x16x32_bf16 v[36:39], v[236:239], v[200:203], v[36:39]
	v_mfma_f32_16x16x32_bf16 v[8:11], v[224:227], v[204:207], v[8:11]
	v_mfma_f32_16x16x32_bf16 v[0:3], v[228:231], v[204:207], v[0:3]
	v_mfma_f32_16x16x32_bf16 v[12:15], v[232:235], v[204:207], v[12:15]
	v_mfma_f32_16x16x32_bf16 v[4:7], v[236:239], v[204:207], v[4:7]
	s_waitcnt lgkmcnt(0)
	v_mfma_f32_16x16x32_bf16 v[120:123], v[208:211], v[176:179], v[120:123]
	ds_read_b128 v[224:227], v174 offset:8192
	v_mfma_f32_16x16x32_bf16 v[112:115], v[212:215], v[176:179], v[112:115]
	ds_read_b128 v[228:231], v174 offset:10240
	v_mfma_f32_16x16x32_bf16 v[124:127], v[216:219], v[176:179], v[124:127]
	ds_read_b128 v[232:235], v174 offset:12288
	v_mfma_f32_16x16x32_bf16 v[116:119], v[220:223], v[176:179], v[116:119]
	ds_read_b128 v[236:239], v174 offset:14336
	v_mfma_f32_16x16x32_bf16 v[88:91], v[208:211], v[180:183], v[88:91]
	s_add_u32 m0, s100, 0x20000
	v_mfma_f32_16x16x32_bf16 v[80:83], v[212:215], v[180:183], v[80:83]
	global_load_lds_dwordx4 v[240:241], off
	v_lshl_add_u64 v[240:241], v[240:241], 0, s[34:35]
	v_mfma_f32_16x16x32_bf16 v[92:95], v[216:219], v[180:183], v[92:95]
	s_add_u32 m0, s100, 0x22000
	v_mfma_f32_16x16x32_bf16 v[84:87], v[220:223], v[180:183], v[84:87]
	global_load_lds_dwordx4 v[242:243], off
	v_lshl_add_u64 v[242:243], v[242:243], 0, s[34:35]
	v_mfma_f32_16x16x32_bf16 v[56:59], v[208:211], v[184:187], v[56:59]
	s_add_u32 m0, s100, 0x24000
	v_mfma_f32_16x16x32_bf16 v[48:51], v[212:215], v[184:187], v[48:51]
	global_load_lds_dwordx4 v[244:245], off
	v_lshl_add_u64 v[244:245], v[244:245], 0, s[34:35]
	v_mfma_f32_16x16x32_bf16 v[60:63], v[216:219], v[184:187], v[60:63]
	s_add_u32 m0, s100, 0x26000
	v_mfma_f32_16x16x32_bf16 v[52:55], v[220:223], v[184:187], v[52:55]
	global_load_lds_dwordx4 v[246:247], off
	v_lshl_add_u64 v[246:247], v[246:247], 0, s[34:35]
	v_mfma_f32_16x16x32_bf16 v[24:27], v[208:211], v[188:191], v[24:27]
	v_mfma_f32_16x16x32_bf16 v[16:19], v[212:215], v[188:191], v[16:19]
	v_mfma_f32_16x16x32_bf16 v[28:31], v[216:219], v[188:191], v[28:31]
	v_mfma_f32_16x16x32_bf16 v[20:23], v[220:223], v[188:191], v[20:23]
	s_waitcnt lgkmcnt(0)
	v_mfma_f32_16x16x32_bf16 v[104:107], v[224:227], v[176:179], v[104:107]
	ds_read_b128 v[192:195], v173 offset:0
	v_mfma_f32_16x16x32_bf16 v[96:99], v[228:231], v[176:179], v[96:99]
	ds_read_b128 v[196:199], v173 offset:2048
	v_mfma_f32_16x16x32_bf16 v[108:111], v[232:235], v[176:179], v[108:111]
	ds_read_b128 v[200:203], v173 offset:4096
	v_mfma_f32_16x16x32_bf16 v[100:103], v[236:239], v[176:179], v[100:103]
	ds_read_b128 v[204:207], v173 offset:6144
	v_mfma_f32_16x16x32_bf16 v[72:75], v[224:227], v[180:183], v[72:75]
	ds_read_b128 v[208:211], v175 offset:0
	v_mfma_f32_16x16x32_bf16 v[64:67], v[228:231], v[180:183], v[64:67]
	ds_read_b128 v[212:215], v175 offset:2048
	v_mfma_f32_16x16x32_bf16 v[76:79], v[232:235], v[180:183], v[76:79]
	ds_read_b128 v[216:219], v175 offset:4096
	v_mfma_f32_16x16x32_bf16 v[68:71], v[236:239], v[180:183], v[68:71]
	ds_read_b128 v[220:223], v175 offset:6144
	v_mfma_f32_16x16x32_bf16 v[40:43], v[224:227], v[184:187], v[40:43]
	v_mfma_f32_16x16x32_bf16 v[32:35], v[228:231], v[184:187], v[32:35]
	v_mfma_f32_16x16x32_bf16 v[44:47], v[232:235], v[184:187], v[44:47]
	v_mfma_f32_16x16x32_bf16 v[36:39], v[236:239], v[184:187], v[36:39]
	v_mfma_f32_16x16x32_bf16 v[8:11], v[224:227], v[188:191], v[8:11]
	v_mfma_f32_16x16x32_bf16 v[0:3], v[228:231], v[188:191], v[0:3]
	v_mfma_f32_16x16x32_bf16 v[12:15], v[232:235], v[188:191], v[12:15]
	v_mfma_f32_16x16x32_bf16 v[4:7], v[236:239], v[188:191], v[4:7]
	s_waitcnt lgkmcnt(0)
	v_mfma_f32_16x16x32_bf16 v[120:123], v[208:211], v[192:195], v[120:123]
	ds_read_b128 v[224:227], v175 offset:8192
	v_mfma_f32_16x16x32_bf16 v[112:115], v[212:215], v[192:195], v[112:115]
	ds_read_b128 v[228:231], v175 offset:10240
	v_mfma_f32_16x16x32_bf16 v[124:127], v[216:219], v[192:195], v[124:127]
	ds_read_b128 v[232:235], v175 offset:12288
	v_mfma_f32_16x16x32_bf16 v[116:119], v[220:223], v[192:195], v[116:119]
	ds_read_b128 v[236:239], v175 offset:14336
	v_mfma_f32_16x16x32_bf16 v[88:91], v[208:211], v[196:199], v[88:91]
	v_mfma_f32_16x16x32_bf16 v[80:83], v[212:215], v[196:199], v[80:83]
	v_mfma_f32_16x16x32_bf16 v[92:95], v[216:219], v[196:199], v[92:95]
	v_mfma_f32_16x16x32_bf16 v[84:87], v[220:223], v[196:199], v[84:87]
	v_mfma_f32_16x16x32_bf16 v[56:59], v[208:211], v[200:203], v[56:59]
	v_mfma_f32_16x16x32_bf16 v[48:51], v[212:215], v[200:203], v[48:51]
	v_mfma_f32_16x16x32_bf16 v[60:63], v[216:219], v[200:203], v[60:63]
	v_mfma_f32_16x16x32_bf16 v[52:55], v[220:223], v[200:203], v[52:55]
	v_mfma_f32_16x16x32_bf16 v[24:27], v[208:211], v[204:207], v[24:27]
	v_mfma_f32_16x16x32_bf16 v[16:19], v[212:215], v[204:207], v[16:19]
	v_mfma_f32_16x16x32_bf16 v[28:31], v[216:219], v[204:207], v[28:31]
	v_mfma_f32_16x16x32_bf16 v[20:23], v[220:223], v[204:207], v[20:23]
	s_waitcnt lgkmcnt(0)
	s_waitcnt vmcnt(4)
	s_barrier
	s_add_i32 s7, s7, -1
	s_cmp_lg_u32 s7, 0
	s_cbranch_scc1 .Lgemm_p2_loop
	v_mfma_f32_16x16x32_bf16 v[104:107], v[224:227], v[192:195], v[104:107]
	ds_read_b128 v[176:179], v172 offset:32768
	s_mov_b32 m0, s101
	v_mfma_f32_16x16x32_bf16 v[96:99], v[228:231], v[192:195], v[96:99]
	ds_read_b128 v[180:183], v172 offset:34816
	global_load_lds_dwordx4 v[138:139], off
	v_lshl_add_u64 v[138:139], v[138:139], 0, s[34:35]
	v_mfma_f32_16x16x32_bf16 v[108:111], v[232:235], v[192:195], v[108:111]
	ds_read_b128 v[184:187], v172 offset:36864
	s_add_u32 m0, s101, 0x2000
	v_mfma_f32_16x16x32_bf16 v[100:103], v[236:239], v[192:195], v[100:103]
	ds_read_b128 v[188:191], v172 offset:38912
	global_load_lds_dwordx4 v[140:141], off
	v_lshl_add_u64 v[140:141], v[140:141], 0, s[34:35]
	v_mfma_f32_16x16x32_bf16 v[72:75], v[224:227], v[196:199], v[72:75]
	ds_read_b128 v[208:211], v174 offset:32768
	s_add_u32 m0, s101, 0x4000
	v_mfma_f32_16x16x32_bf16 v[64:67], v[228:231], v[196:199], v[64:67]
	ds_read_b128 v[212:215], v174 offset:34816
	global_load_lds_dwordx4 v[250:251], off
	v_lshl_add_u64 v[250:251], v[250:251], 0, s[34:35]
	v_mfma_f32_16x16x32_bf16 v[76:79], v[232:235], v[196:199], v[76:79]
	ds_read_b128 v[216:219], v174 offset:36864
	s_add_u32 m0, s101, 0x6000
	v_mfma_f32_16x16x32_bf16 v[68:71], v[236:239], v[196:199], v[68:71]
	ds_read_b128 v[220:223], v174 offset:38912
	global_load_lds_dwordx4 v[252:253], off
	v_lshl_add_u64 v[252:253], v[252:253], 0, s[34:35]
	v_mfma_f32_16x16x32_bf16 v[40:43], v[224:227], v[200:203], v[40:43]
	v_mfma_f32_16x16x32_bf16 v[32:35], v[228:231], v[200:203], v[32:35]
	v_mfma_f32_16x16x32_bf16 v[44:47], v[232:235], v[200:203], v[44:47]
	v_mfma_f32_16x16x32_bf16 v[36:39], v[236:239], v[200:203], v[36:39]
	v_mfma_f32_16x16x32_bf16 v[8:11], v[224:227], v[204:207], v[8:11]
	v_mfma_f32_16x16x32_bf16 v[0:3], v[228:231], v[204:207], v[0:3]
	v_mfma_f32_16x16x32_bf16 v[12:15], v[232:235], v[204:207], v[12:15]
	v_mfma_f32_16x16x32_bf16 v[4:7], v[236:239], v[204:207], v[4:7]
	s_waitcnt lgkmcnt(0)
	v_mfma_f32_16x16x32_bf16 v[120:123], v[208:211], v[176:179], v[120:123]
	ds_read_b128 v[224:227], v174 offset:40960
	v_mfma_f32_16x16x32_bf16 v[112:115], v[212:215], v[176:179], v[112:115]
	ds_read_b128 v[228:231], v174 offset:43008
	v_mfma_f32_16x16x32_bf16 v[124:127], v[216:219], v[176:179], v[124:127]
	ds_read_b128 v[232:235], v174 offset:45056
	v_mfma_f32_16x16x32_bf16 v[116:119], v[220:223], v[176:179], v[116:119]
	ds_read_b128 v[236:239], v174 offset:47104
	v_mfma_f32_16x16x32_bf16 v[88:91], v[208:211], v[180:183], v[88:91]
	s_mov_b32 m0, s100
	v_mfma_f32_16x16x32_bf16 v[80:83], v[212:215], v[180:183], v[80:83]
	global_load_lds_dwordx4 v[240:241], off
	v_lshl_add_u64 v[240:241], v[240:241], 0, s[34:35]
	v_mfma_f32_16x16x32_bf16 v[92:95], v[216:219], v[180:183], v[92:95]
	s_add_u32 m0, s100, 0x2000
	v_mfma_f32_16x16x32_bf16 v[84:87], v[220:223], v[180:183], v[84:87]
	global_load_lds_dwordx4 v[242:243], off
	v_lshl_add_u64 v[242:243], v[242:243], 0, s[34:35]
	v_mfma_f32_16x16x32_bf16 v[56:59], v[208:211], v[184:187], v[56:59]
	s_add_u32 m0, s100, 0x4000
	v_mfma_f32_16x16x32_bf16 v[48:51], v[212:215], v[184:187], v[48:51]
	global_load_lds_dwordx4 v[244:245], off
	v_lshl_add_u64 v[244:245], v[244:245], 0, s[34:35]
	v_mfma_f32_16x16x32_bf16 v[60:63], v[216:219], v[184:187], v[60:63]
	s_add_u32 m0, s100, 0x6000
	v_mfma_f32_16x16x32_bf16 v[52:55], v[220:223], v[184:187], v[52:55]
	global_load_lds_dwordx4 v[246:247], off
	v_lshl_add_u64 v[246:247], v[246:247], 0, s[34:35]
	v_mfma_f32_16x16x32_bf16 v[24:27], v[208:211], v[188:191], v[24:27]
	v_mfma_f32_16x16x32_bf16 v[16:19], v[212:215], v[188:191], v[16:19]
	v_mfma_f32_16x16x32_bf16 v[28:31], v[216:219], v[188:191], v[28:31]
	v_mfma_f32_16x16x32_bf16 v[20:23], v[220:223], v[188:191], v[20:23]
	s_waitcnt lgkmcnt(0)
	v_mfma_f32_16x16x32_bf16 v[104:107], v[224:227], v[176:179], v[104:107]
	ds_read_b128 v[192:195], v173 offset:32768
	v_mfma_f32_16x16x32_bf16 v[96:99], v[228:231], v[176:179], v[96:99]
	ds_read_b128 v[196:199], v173 offset:34816
	v_mfma_f32_16x16x32_bf16 v[108:111], v[232:235], v[176:179], v[108:111]
	ds_read_b128 v[200:203], v173 offset:36864
	v_mfma_f32_16x16x32_bf16 v[100:103], v[236:239], v[176:179], v[100:103]
	ds_read_b128 v[204:207], v173 offset:38912
	v_mfma_f32_16x16x32_bf16 v[72:75], v[224:227], v[180:183], v[72:75]
	ds_read_b128 v[208:211], v175 offset:32768
	v_mfma_f32_16x16x32_bf16 v[64:67], v[228:231], v[180:183], v[64:67]
	ds_read_b128 v[212:215], v175 offset:34816
	v_mfma_f32_16x16x32_bf16 v[76:79], v[232:235], v[180:183], v[76:79]
	ds_read_b128 v[216:219], v175 offset:36864
	v_mfma_f32_16x16x32_bf16 v[68:71], v[236:239], v[180:183], v[68:71]
	ds_read_b128 v[220:223], v175 offset:38912
	v_mfma_f32_16x16x32_bf16 v[40:43], v[224:227], v[184:187], v[40:43]
	v_mfma_f32_16x16x32_bf16 v[32:35], v[228:231], v[184:187], v[32:35]
	v_mfma_f32_16x16x32_bf16 v[44:47], v[232:235], v[184:187], v[44:47]
	v_mfma_f32_16x16x32_bf16 v[36:39], v[236:239], v[184:187], v[36:39]
	v_mfma_f32_16x16x32_bf16 v[8:11], v[224:227], v[188:191], v[8:11]
	v_mfma_f32_16x16x32_bf16 v[0:3], v[228:231], v[188:191], v[0:3]
	v_mfma_f32_16x16x32_bf16 v[12:15], v[232:235], v[188:191], v[12:15]
	v_mfma_f32_16x16x32_bf16 v[4:7], v[236:239], v[188:191], v[4:7]
	s_waitcnt lgkmcnt(0)
	v_mfma_f32_16x16x32_bf16 v[120:123], v[208:211], v[192:195], v[120:123]
	ds_read_b128 v[224:227], v175 offset:40960
	v_mfma_f32_16x16x32_bf16 v[112:115], v[212:215], v[192:195], v[112:115]
	ds_read_b128 v[228:231], v175 offset:43008
	v_mfma_f32_16x16x32_bf16 v[124:127], v[216:219], v[192:195], v[124:127]
	ds_read_b128 v[232:235], v175 offset:45056
	v_mfma_f32_16x16x32_bf16 v[116:119], v[220:223], v[192:195], v[116:119]
	ds_read_b128 v[236:239], v175 offset:47104
	v_mfma_f32_16x16x32_bf16 v[88:91], v[208:211], v[196:199], v[88:91]
	v_mfma_f32_16x16x32_bf16 v[80:83], v[212:215], v[196:199], v[80:83]
	v_mfma_f32_16x16x32_bf16 v[92:95], v[216:219], v[196:199], v[92:95]
	v_mfma_f32_16x16x32_bf16 v[84:87], v[220:223], v[196:199], v[84:87]
	v_mfma_f32_16x16x32_bf16 v[56:59], v[208:211], v[200:203], v[56:59]
	v_mfma_f32_16x16x32_bf16 v[48:51], v[212:215], v[200:203], v[48:51]
	v_mfma_f32_16x16x32_bf16 v[60:63], v[216:219], v[200:203], v[60:63]
	v_mfma_f32_16x16x32_bf16 v[52:55], v[220:223], v[200:203], v[52:55]
	v_mfma_f32_16x16x32_bf16 v[24:27], v[208:211], v[204:207], v[24:27]
	v_mfma_f32_16x16x32_bf16 v[16:19], v[212:215], v[204:207], v[16:19]
	v_mfma_f32_16x16x32_bf16 v[28:31], v[216:219], v[204:207], v[28:31]
	v_mfma_f32_16x16x32_bf16 v[20:23], v[220:223], v[204:207], v[20:23]
	s_waitcnt lgkmcnt(0)
	s_waitcnt vmcnt(4)
	s_barrier
	v_mfma_f32_16x16x32_bf16 v[104:107], v[224:227], v[192:195], v[104:107]
	ds_read_b128 v[176:179], v254 offset:0
	s_add_u32 m0, s101, 0x8000
	v_mfma_f32_16x16x32_bf16 v[96:99], v[228:231], v[192:195], v[96:99]
	ds_read_b128 v[180:183], v254 offset:2048
	global_load_lds_dwordx4 v[138:139], off
	v_lshl_add_u64 v[138:139], v[138:139], 0, s[34:35]
	v_mfma_f32_16x16x32_bf16 v[108:111], v[232:235], v[192:195], v[108:111]
	ds_read_b128 v[184:187], v254 offset:4096
	s_add_u32 m0, s101, 0xa000
	v_mfma_f32_16x16x32_bf16 v[100:103], v[236:239], v[192:195], v[100:103]
	ds_read_b128 v[188:191], v254 offset:6144
	global_load_lds_dwordx4 v[140:141], off
	v_lshl_add_u64 v[140:141], v[140:141], 0, s[34:35]
	v_mfma_f32_16x16x32_bf16 v[72:75], v[224:227], v[196:199], v[72:75]
	ds_read_b128 v[208:211], v174 offset:0
	s_add_u32 m0, s101, 0xc000
	v_mfma_f32_16x16x32_bf16 v[64:67], v[228:231], v[196:199], v[64:67]
	ds_read_b128 v[212:215], v174 offset:2048
	global_load_lds_dwordx4 v[250:251], off
	v_lshl_add_u64 v[250:251], v[250:251], 0, s[34:35]
	v_mfma_f32_16x16x32_bf16 v[76:79], v[232:235], v[196:199], v[76:79]
	ds_read_b128 v[216:219], v174 offset:4096
	s_add_u32 m0, s101, 0xe000
	v_mfma_f32_16x16x32_bf16 v[68:71], v[236:239], v[196:199], v[68:71]
	ds_read_b128 v[220:223], v174 offset:6144
	global_load_lds_dwordx4 v[252:253], off
	v_lshl_add_u64 v[252:253], v[252:253], 0, s[34:35]
	v_mfma_f32_16x16x32_bf16 v[40:43], v[224:227], v[200:203], v[40:43]
	v_mfma_f32_16x16x32_bf16 v[32:35], v[228:231], v[200:203], v[32:35]
	v_mfma_f32_16x16x32_bf16 v[44:47], v[232:235], v[200:203], v[44:47]
	v_mfma_f32_16x16x32_bf16 v[36:39], v[236:239], v[200:203], v[36:39]
	v_mfma_f32_16x16x32_bf16 v[8:11], v[224:227], v[204:207], v[8:11]
	v_mfma_f32_16x16x32_bf16 v[0:3], v[228:231], v[204:207], v[0:3]
	v_mfma_f32_16x16x32_bf16 v[12:15], v[232:235], v[204:207], v[12:15]
	v_mfma_f32_16x16x32_bf16 v[4:7], v[236:239], v[204:207], v[4:7]
	s_waitcnt lgkmcnt(0)
	v_mfma_f32_16x16x32_bf16 v[120:123], v[208:211], v[176:179], v[120:123]
	ds_read_b128 v[224:227], v174 offset:8192
	v_mfma_f32_16x16x32_bf16 v[112:115], v[212:215], v[176:179], v[112:115]
	ds_read_b128 v[228:231], v174 offset:10240
	v_mfma_f32_16x16x32_bf16 v[124:127], v[216:219], v[176:179], v[124:127]
	ds_read_b128 v[232:235], v174 offset:12288
	v_mfma_f32_16x16x32_bf16 v[116:119], v[220:223], v[176:179], v[116:119]
	ds_read_b128 v[236:239], v174 offset:14336
	v_mfma_f32_16x16x32_bf16 v[88:91], v[208:211], v[180:183], v[88:91]
	v_mfma_f32_16x16x32_bf16 v[80:83], v[212:215], v[180:183], v[80:83]
	v_mfma_f32_16x16x32_bf16 v[92:95], v[216:219], v[180:183], v[92:95]
	v_mfma_f32_16x16x32_bf16 v[84:87], v[220:223], v[180:183], v[84:87]
	v_mfma_f32_16x16x32_bf16 v[56:59], v[208:211], v[184:187], v[56:59]
	v_mfma_f32_16x16x32_bf16 v[48:51], v[212:215], v[184:187], v[48:51]
	v_mfma_f32_16x16x32_bf16 v[60:63], v[216:219], v[184:187], v[60:63]
	v_mfma_f32_16x16x32_bf16 v[52:55], v[220:223], v[184:187], v[52:55]
	v_mfma_f32_16x16x32_bf16 v[24:27], v[208:211], v[188:191], v[24:27]
	v_mfma_f32_16x16x32_bf16 v[16:19], v[212:215], v[188:191], v[16:19]
	v_mfma_f32_16x16x32_bf16 v[28:31], v[216:219], v[188:191], v[28:31]
	v_mfma_f32_16x16x32_bf16 v[20:23], v[220:223], v[188:191], v[20:23]
	s_waitcnt lgkmcnt(0)
	v_mfma_f32_16x16x32_bf16 v[104:107], v[224:227], v[176:179], v[104:107]
	ds_read_b128 v[192:195], v255 offset:0
	v_mfma_f32_16x16x32_bf16 v[96:99], v[228:231], v[176:179], v[96:99]
	ds_read_b128 v[196:199], v255 offset:2048
	v_mfma_f32_16x16x32_bf16 v[108:111], v[232:235], v[176:179], v[108:111]
	ds_read_b128 v[200:203], v255 offset:4096
	v_mfma_f32_16x16x32_bf16 v[100:103], v[236:239], v[176:179], v[100:103]
	ds_read_b128 v[204:207], v255 offset:6144
	v_mfma_f32_16x16x32_bf16 v[72:75], v[224:227], v[180:183], v[72:75]
	ds_read_b128 v[208:211], v175 offset:0
	v_mfma_f32_16x16x32_bf16 v[64:67], v[228:231], v[180:183], v[64:67]
	ds_read_b128 v[212:215], v175 offset:2048
	v_mfma_f32_16x16x32_bf16 v[76:79], v[232:235], v[180:183], v[76:79]
	ds_read_b128 v[216:219], v175 offset:4096
	v_mfma_f32_16x16x32_bf16 v[68:71], v[236:239], v[180:183], v[68:71]
	ds_read_b128 v[220:223], v175 offset:6144
	v_mfma_f32_16x16x32_bf16 v[40:43], v[224:227], v[184:187], v[40:43]
	v_mfma_f32_16x16x32_bf16 v[32:35], v[228:231], v[184:187], v[32:35]
	v_mfma_f32_16x16x32_bf16 v[44:47], v[232:235], v[184:187], v[44:47]
	v_mfma_f32_16x16x32_bf16 v[36:39], v[236:239], v[184:187], v[36:39]
	v_mfma_f32_16x16x32_bf16 v[8:11], v[224:227], v[188:191], v[8:11]
	v_mfma_f32_16x16x32_bf16 v[0:3], v[228:231], v[188:191], v[0:3]
	v_mfma_f32_16x16x32_bf16 v[12:15], v[232:235], v[188:191], v[12:15]
	v_mfma_f32_16x16x32_bf16 v[4:7], v[236:239], v[188:191], v[4:7]
	s_waitcnt lgkmcnt(0)
	v_mfma_f32_16x16x32_bf16 v[120:123], v[208:211], v[192:195], v[120:123]
	ds_read_b128 v[224:227], v175 offset:8192
	v_mfma_f32_16x16x32_bf16 v[112:115], v[212:215], v[192:195], v[112:115]
	ds_read_b128 v[228:231], v175 offset:10240
	v_mfma_f32_16x16x32_bf16 v[124:127], v[216:219], v[192:195], v[124:127]
	ds_read_b128 v[232:235], v175 offset:12288
	v_mfma_f32_16x16x32_bf16 v[116:119], v[220:223], v[192:195], v[116:119]
	ds_read_b128 v[236:239], v175 offset:14336
	v_mfma_f32_16x16x32_bf16 v[88:91], v[208:211], v[196:199], v[88:91]
	v_mfma_f32_16x16x32_bf16 v[80:83], v[212:215], v[196:199], v[80:83]
	v_mfma_f32_16x16x32_bf16 v[92:95], v[216:219], v[196:199], v[92:95]
	v_mfma_f32_16x16x32_bf16 v[84:87], v[220:223], v[196:199], v[84:87]
	v_mfma_f32_16x16x32_bf16 v[56:59], v[208:211], v[200:203], v[56:59]
	v_mfma_f32_16x16x32_bf16 v[48:51], v[212:215], v[200:203], v[48:51]
	v_mfma_f32_16x16x32_bf16 v[60:63], v[216:219], v[200:203], v[60:63]
	v_mfma_f32_16x16x32_bf16 v[52:55], v[220:223], v[200:203], v[52:55]
	v_mfma_f32_16x16x32_bf16 v[24:27], v[208:211], v[204:207], v[24:27]
	v_mfma_f32_16x16x32_bf16 v[16:19], v[212:215], v[204:207], v[16:19]
	v_mfma_f32_16x16x32_bf16 v[28:31], v[216:219], v[204:207], v[28:31]
	v_mfma_f32_16x16x32_bf16 v[20:23], v[220:223], v[204:207], v[20:23]
	s_waitcnt lgkmcnt(0)
	s_waitcnt vmcnt(0)
	s_barrier
	v_mfma_f32_16x16x32_bf16 v[104:107], v[224:227], v[192:195], v[104:107]
	ds_read_b128 v[176:179], v172 offset:0
	v_mfma_f32_16x16x32_bf16 v[96:99], v[228:231], v[192:195], v[96:99]
	ds_read_b128 v[180:183], v172 offset:2048
	v_mfma_f32_16x16x32_bf16 v[108:111], v[232:235], v[192:195], v[108:111]
	ds_read_b128 v[184:187], v172 offset:4096
	v_mfma_f32_16x16x32_bf16 v[100:103], v[236:239], v[192:195], v[100:103]
	ds_read_b128 v[188:191], v172 offset:6144
	v_mfma_f32_16x16x32_bf16 v[72:75], v[224:227], v[196:199], v[72:75]
	ds_read_b128 v[208:211], v174 offset:32768
	v_mfma_f32_16x16x32_bf16 v[64:67], v[228:231], v[196:199], v[64:67]
	ds_read_b128 v[212:215], v174 offset:34816
	v_mfma_f32_16x16x32_bf16 v[76:79], v[232:235], v[196:199], v[76:79]
	ds_read_b128 v[216:219], v174 offset:36864
	v_mfma_f32_16x16x32_bf16 v[68:71], v[236:239], v[196:199], v[68:71]
	ds_read_b128 v[220:223], v174 offset:38912
	v_mfma_f32_16x16x32_bf16 v[40:43], v[224:227], v[200:203], v[40:43]
	v_mfma_f32_16x16x32_bf16 v[32:35], v[228:231], v[200:203], v[32:35]
	v_mfma_f32_16x16x32_bf16 v[44:47], v[232:235], v[200:203], v[44:47]
	v_mfma_f32_16x16x32_bf16 v[36:39], v[236:239], v[200:203], v[36:39]
	v_mfma_f32_16x16x32_bf16 v[8:11], v[224:227], v[204:207], v[8:11]
	v_mfma_f32_16x16x32_bf16 v[0:3], v[228:231], v[204:207], v[0:3]
	v_mfma_f32_16x16x32_bf16 v[12:15], v[232:235], v[204:207], v[12:15]
	v_mfma_f32_16x16x32_bf16 v[4:7], v[236:239], v[204:207], v[4:7]
	s_waitcnt lgkmcnt(0)
	v_mfma_f32_16x16x32_bf16 v[120:123], v[208:211], v[176:179], v[120:123]
	ds_read_b128 v[224:227], v174 offset:40960
	v_mfma_f32_16x16x32_bf16 v[112:115], v[212:215], v[176:179], v[112:115]
	ds_read_b128 v[228:231], v174 offset:43008
	v_mfma_f32_16x16x32_bf16 v[124:127], v[216:219], v[176:179], v[124:127]
	ds_read_b128 v[232:235], v174 offset:45056
	v_mfma_f32_16x16x32_bf16 v[116:119], v[220:223], v[176:179], v[116:119]
	ds_read_b128 v[236:239], v174 offset:47104
	v_mfma_f32_16x16x32_bf16 v[88:91], v[208:211], v[180:183], v[88:91]
	v_mfma_f32_16x16x32_bf16 v[80:83], v[212:215], v[180:183], v[80:83]
	v_mfma_f32_16x16x32_bf16 v[92:95], v[216:219], v[180:183], v[92:95]
	v_mfma_f32_16x16x32_bf16 v[84:87], v[220:223], v[180:183], v[84:87]
	v_mfma_f32_16x16x32_bf16 v[56:59], v[208:211], v[184:187], v[56:59]
	v_mfma_f32_16x16x32_bf16 v[48:51], v[212:215], v[184:187], v[48:51]
	v_mfma_f32_16x16x32_bf16 v[60:63], v[216:219], v[184:187], v[60:63]
	v_mfma_f32_16x16x32_bf16 v[52:55], v[220:223], v[184:187], v[52:55]
	v_mfma_f32_16x16x32_bf16 v[24:27], v[208:211], v[188:191], v[24:27]
	v_mfma_f32_16x16x32_bf16 v[16:19], v[212:215], v[188:191], v[16:19]
	v_mfma_f32_16x16x32_bf16 v[28:31], v[216:219], v[188:191], v[28:31]
	v_mfma_f32_16x16x32_bf16 v[20:23], v[220:223], v[188:191], v[20:23]
	s_waitcnt lgkmcnt(0)
	v_mfma_f32_16x16x32_bf16 v[104:107], v[224:227], v[176:179], v[104:107]
	ds_read_b128 v[192:195], v173 offset:0
	v_mfma_f32_16x16x32_bf16 v[96:99], v[228:231], v[176:179], v[96:99]
	ds_read_b128 v[196:199], v173 offset:2048
	v_mfma_f32_16x16x32_bf16 v[108:111], v[232:235], v[176:179], v[108:111]
	ds_read_b128 v[200:203], v173 offset:4096
	v_mfma_f32_16x16x32_bf16 v[100:103], v[236:239], v[176:179], v[100:103]
	ds_read_b128 v[204:207], v173 offset:6144
	v_mfma_f32_16x16x32_bf16 v[72:75], v[224:227], v[180:183], v[72:75]
	ds_read_b128 v[208:211], v175 offset:32768
	v_mfma_f32_16x16x32_bf16 v[64:67], v[228:231], v[180:183], v[64:67]
	ds_read_b128 v[212:215], v175 offset:34816
	v_mfma_f32_16x16x32_bf16 v[76:79], v[232:235], v[180:183], v[76:79]
	ds_read_b128 v[216:219], v175 offset:36864
	v_mfma_f32_16x16x32_bf16 v[68:71], v[236:239], v[180:183], v[68:71]
	ds_read_b128 v[220:223], v175 offset:38912
	v_mfma_f32_16x16x32_bf16 v[40:43], v[224:227], v[184:187], v[40:43]
	v_mfma_f32_16x16x32_bf16 v[32:35], v[228:231], v[184:187], v[32:35]
	v_mfma_f32_16x16x32_bf16 v[44:47], v[232:235], v[184:187], v[44:47]
	v_mfma_f32_16x16x32_bf16 v[36:39], v[236:239], v[184:187], v[36:39]
	v_mfma_f32_16x16x32_bf16 v[8:11], v[224:227], v[188:191], v[8:11]
	v_mfma_f32_16x16x32_bf16 v[0:3], v[228:231], v[188:191], v[0:3]
	v_mfma_f32_16x16x32_bf16 v[12:15], v[232:235], v[188:191], v[12:15]
	v_mfma_f32_16x16x32_bf16 v[4:7], v[236:239], v[188:191], v[4:7]
	s_waitcnt lgkmcnt(0)
	v_mfma_f32_16x16x32_bf16 v[120:123], v[208:211], v[192:195], v[120:123]
	ds_read_b128 v[224:227], v175 offset:40960
	v_mfma_f32_16x16x32_bf16 v[112:115], v[212:215], v[192:195], v[112:115]
	ds_read_b128 v[228:231], v175 offset:43008
	v_mfma_f32_16x16x32_bf16 v[124:127], v[216:219], v[192:195], v[124:127]
	ds_read_b128 v[232:235], v175 offset:45056
	v_mfma_f32_16x16x32_bf16 v[116:119], v[220:223], v[192:195], v[116:119]
	ds_read_b128 v[236:239], v175 offset:47104
	v_mfma_f32_16x16x32_bf16 v[88:91], v[208:211], v[196:199], v[88:91]
	v_mfma_f32_16x16x32_bf16 v[80:83], v[212:215], v[196:199], v[80:83]
	v_mfma_f32_16x16x32_bf16 v[92:95], v[216:219], v[196:199], v[92:95]
	v_mfma_f32_16x16x32_bf16 v[84:87], v[220:223], v[196:199], v[84:87]
	v_mfma_f32_16x16x32_bf16 v[56:59], v[208:211], v[200:203], v[56:59]
	v_mfma_f32_16x16x32_bf16 v[48:51], v[212:215], v[200:203], v[48:51]
	v_mfma_f32_16x16x32_bf16 v[60:63], v[216:219], v[200:203], v[60:63]
	v_mfma_f32_16x16x32_bf16 v[52:55], v[220:223], v[200:203], v[52:55]
	v_mfma_f32_16x16x32_bf16 v[24:27], v[208:211], v[204:207], v[24:27]
	v_mfma_f32_16x16x32_bf16 v[16:19], v[212:215], v[204:207], v[16:19]
	v_mfma_f32_16x16x32_bf16 v[28:31], v[216:219], v[204:207], v[28:31]
	v_mfma_f32_16x16x32_bf16 v[20:23], v[220:223], v[204:207], v[20:23]
	s_waitcnt lgkmcnt(0)
	s_barrier
	v_mfma_f32_16x16x32_bf16 v[104:107], v[224:227], v[192:195], v[104:107]
	v_mfma_f32_16x16x32_bf16 v[96:99], v[228:231], v[192:195], v[96:99]
	v_mfma_f32_16x16x32_bf16 v[108:111], v[232:235], v[192:195], v[108:111]
	v_mfma_f32_16x16x32_bf16 v[100:103], v[236:239], v[192:195], v[100:103]
	v_mfma_f32_16x16x32_bf16 v[72:75], v[224:227], v[196:199], v[72:75]
	v_mfma_f32_16x16x32_bf16 v[64:67], v[228:231], v[196:199], v[64:67]
	v_mfma_f32_16x16x32_bf16 v[76:79], v[232:235], v[196:199], v[76:79]
	v_mfma_f32_16x16x32_bf16 v[68:71], v[236:239], v[196:199], v[68:71]
	v_mfma_f32_16x16x32_bf16 v[40:43], v[224:227], v[200:203], v[40:43]
	v_mfma_f32_16x16x32_bf16 v[32:35], v[228:231], v[200:203], v[32:35]
	v_mfma_f32_16x16x32_bf16 v[44:47], v[232:235], v[200:203], v[44:47]
	v_mfma_f32_16x16x32_bf16 v[36:39], v[236:239], v[200:203], v[36:39]
	v_mfma_f32_16x16x32_bf16 v[8:11], v[224:227], v[204:207], v[8:11]
	v_mfma_f32_16x16x32_bf16 v[0:3], v[228:231], v[204:207], v[0:3]
	v_mfma_f32_16x16x32_bf16 v[12:15], v[232:235], v[204:207], v[12:15]
	v_mfma_f32_16x16x32_bf16 v[4:7], v[236:239], v[204:207], v[4:7]
	s_nop 7
	s_nop 3
	s_branch .LBB0_115

.Lgemm_p7_loop:
	v_mfma_f32_16x16x32_bf16 v[108:111], v[224:227], v[192:195], v[108:111]
	ds_read_b128 v[176:179], v172 offset:32768
	s_mov_b32 m0, s101
	v_mfma_f32_16x16x32_bf16 v[104:107], v[228:231], v[192:195], v[104:107]
	ds_read_b128 v[180:183], v172 offset:34816
	global_load_lds_dwordx4 v[138:139], off
	v_lshl_add_u64 v[138:139], v[138:139], 0, s[34:35]
	v_mfma_f32_16x16x32_bf16 v[100:103], v[232:235], v[192:195], v[100:103]
	ds_read_b128 v[184:187], v172 offset:36864
	s_add_u32 m0, s101, 0x2000
	v_mfma_f32_16x16x32_bf16 v[96:99], v[236:239], v[192:195], v[96:99]
	ds_read_b128 v[188:191], v172 offset:38912
	global_load_lds_dwordx4 v[140:141], off
	v_lshl_add_u64 v[140:141], v[140:141], 0, s[34:35]
	v_mfma_f32_16x16x32_bf16 v[76:79], v[224:227], v[196:199], v[76:79]
	ds_read_b128 v[208:211], v174 offset:32768
	s_add_u32 m0, s101, 0x4000
	v_mfma_f32_16x16x32_bf16 v[72:75], v[228:231], v[196:199], v[72:75]
	ds_read_b128 v[212:215], v174 offset:34816
	global_load_lds_dwordx4 v[250:251], off
	v_lshl_add_u64 v[250:251], v[250:251], 0, s[34:35]
	v_mfma_f32_16x16x32_bf16 v[68:71], v[232:235], v[196:199], v[68:71]
	ds_read_b128 v[216:219], v174 offset:36864
	s_add_u32 m0, s101, 0x6000
	v_mfma_f32_16x16x32_bf16 v[64:67], v[236:239], v[196:199], v[64:67]
	ds_read_b128 v[220:223], v174 offset:38912
	global_load_lds_dwordx4 v[252:253], off
	v_lshl_add_u64 v[252:253], v[252:253], 0, s[34:35]
	v_mfma_f32_16x16x32_bf16 v[44:47], v[224:227], v[200:203], v[44:47]
	v_mfma_f32_16x16x32_bf16 v[40:43], v[228:231], v[200:203], v[40:43]
	v_mfma_f32_16x16x32_bf16 v[36:39], v[232:235], v[200:203], v[36:39]
	v_mfma_f32_16x16x32_bf16 v[32:35], v[236:239], v[200:203], v[32:35]
	v_mfma_f32_16x16x32_bf16 v[12:15], v[224:227], v[204:207], v[12:15]
	v_mfma_f32_16x16x32_bf16 v[8:11], v[228:231], v[204:207], v[8:11]
	v_mfma_f32_16x16x32_bf16 v[4:7], v[232:235], v[204:207], v[4:7]
	v_mfma_f32_16x16x32_bf16 v[0:3], v[236:239], v[204:207], v[0:3]
	s_waitcnt lgkmcnt(0)
	v_mfma_f32_16x16x32_bf16 v[124:127], v[208:211], v[176:179], v[124:127]
	ds_read_b128 v[224:227], v174 offset:40960
	v_mfma_f32_16x16x32_bf16 v[120:123], v[212:215], v[176:179], v[120:123]
	ds_read_b128 v[228:231], v174 offset:43008
	v_mfma_f32_16x16x32_bf16 v[116:119], v[216:219], v[176:179], v[116:119]
	ds_read_b128 v[232:235], v174 offset:45056
	v_mfma_f32_16x16x32_bf16 v[112:115], v[220:223], v[176:179], v[112:115]
	ds_read_b128 v[236:239], v174 offset:47104
	v_mfma_f32_16x16x32_bf16 v[92:95], v[208:211], v[180:183], v[92:95]
	s_mov_b32 m0, s100
	v_mfma_f32_16x16x32_bf16 v[88:91], v[212:215], v[180:183], v[88:91]
	global_load_lds_dwordx4 v[240:241], off
	v_lshl_add_u64 v[240:241], v[240:241], 0, s[34:35]
	v_mfma_f32_16x16x32_bf16 v[84:87], v[216:219], v[180:183], v[84:87]
	s_add_u32 m0, s100, 0x2000
	v_mfma_f32_16x16x32_bf16 v[80:83], v[220:223], v[180:183], v[80:83]
	global_load_lds_dwordx4 v[242:243], off
	v_lshl_add_u64 v[242:243], v[242:243], 0, s[34:35]
	v_mfma_f32_16x16x32_bf16 v[60:63], v[208:211], v[184:187], v[60:63]
	s_add_u32 m0, s100, 0x4000
	v_mfma_f32_16x16x32_bf16 v[56:59], v[212:215], v[184:187], v[56:59]
	global_load_lds_dwordx4 v[244:245], off
	v_lshl_add_u64 v[244:245], v[244:245], 0, s[34:35]
	v_mfma_f32_16x16x32_bf16 v[52:55], v[216:219], v[184:187], v[52:55]
	s_add_u32 m0, s100, 0x6000
	v_mfma_f32_16x16x32_bf16 v[48:51], v[220:223], v[184:187], v[48:51]
	global_load_lds_dwordx4 v[246:247], off
	v_lshl_add_u64 v[246:247], v[246:247], 0, s[34:35]
	v_mfma_f32_16x16x32_bf16 v[28:31], v[208:211], v[188:191], v[28:31]
	v_mfma_f32_16x16x32_bf16 v[24:27], v[212:215], v[188:191], v[24:27]
	v_mfma_f32_16x16x32_bf16 v[20:23], v[216:219], v[188:191], v[20:23]
	v_mfma_f32_16x16x32_bf16 v[16:19], v[220:223], v[188:191], v[16:19]
	s_waitcnt lgkmcnt(0)
	v_mfma_f32_16x16x32_bf16 v[108:111], v[224:227], v[176:179], v[108:111]
	ds_read_b128 v[192:195], v173 offset:32768
	v_mfma_f32_16x16x32_bf16 v[104:107], v[228:231], v[176:179], v[104:107]
	ds_read_b128 v[196:199], v173 offset:34816
	v_mfma_f32_16x16x32_bf16 v[100:103], v[232:235], v[176:179], v[100:103]
	ds_read_b128 v[200:203], v173 offset:36864
	v_mfma_f32_16x16x32_bf16 v[96:99], v[236:239], v[176:179], v[96:99]
	ds_read_b128 v[204:207], v173 offset:38912
	v_mfma_f32_16x16x32_bf16 v[76:79], v[224:227], v[180:183], v[76:79]
	ds_read_b128 v[208:211], v175 offset:32768
	v_mfma_f32_16x16x32_bf16 v[72:75], v[228:231], v[180:183], v[72:75]
	ds_read_b128 v[212:215], v175 offset:34816
	v_mfma_f32_16x16x32_bf16 v[68:71], v[232:235], v[180:183], v[68:71]
	ds_read_b128 v[216:219], v175 offset:36864
	v_mfma_f32_16x16x32_bf16 v[64:67], v[236:239], v[180:183], v[64:67]
	ds_read_b128 v[220:223], v175 offset:38912
	v_mfma_f32_16x16x32_bf16 v[44:47], v[224:227], v[184:187], v[44:47]
	v_mfma_f32_16x16x32_bf16 v[40:43], v[228:231], v[184:187], v[40:43]
	v_mfma_f32_16x16x32_bf16 v[36:39], v[232:235], v[184:187], v[36:39]
	v_mfma_f32_16x16x32_bf16 v[32:35], v[236:239], v[184:187], v[32:35]
	v_mfma_f32_16x16x32_bf16 v[12:15], v[224:227], v[188:191], v[12:15]
	v_mfma_f32_16x16x32_bf16 v[8:11], v[228:231], v[188:191], v[8:11]
	v_mfma_f32_16x16x32_bf16 v[4:7], v[232:235], v[188:191], v[4:7]
	v_mfma_f32_16x16x32_bf16 v[0:3], v[236:239], v[188:191], v[0:3]
	s_waitcnt lgkmcnt(0)
	v_mfma_f32_16x16x32_bf16 v[124:127], v[208:211], v[192:195], v[124:127]
	ds_read_b128 v[224:227], v175 offset:40960
	v_mfma_f32_16x16x32_bf16 v[120:123], v[212:215], v[192:195], v[120:123]
	ds_read_b128 v[228:231], v175 offset:43008
	v_mfma_f32_16x16x32_bf16 v[116:119], v[216:219], v[192:195], v[116:119]
	ds_read_b128 v[232:235], v175 offset:45056
	v_mfma_f32_16x16x32_bf16 v[112:115], v[220:223], v[192:195], v[112:115]
	ds_read_b128 v[236:239], v175 offset:47104
	v_mfma_f32_16x16x32_bf16 v[92:95], v[208:211], v[196:199], v[92:95]
	v_mfma_f32_16x16x32_bf16 v[88:91], v[212:215], v[196:199], v[88:91]
	v_mfma_f32_16x16x32_bf16 v[84:87], v[216:219], v[196:199], v[84:87]
	v_mfma_f32_16x16x32_bf16 v[80:83], v[220:223], v[196:199], v[80:83]
	v_mfma_f32_16x16x32_bf16 v[60:63], v[208:211], v[200:203], v[60:63]
	v_mfma_f32_16x16x32_bf16 v[56:59], v[212:215], v[200:203], v[56:59]
	v_mfma_f32_16x16x32_bf16 v[52:55], v[216:219], v[200:203], v[52:55]
	v_mfma_f32_16x16x32_bf16 v[48:51], v[220:223], v[200:203], v[48:51]
	v_mfma_f32_16x16x32_bf16 v[28:31], v[208:211], v[204:207], v[28:31]
	v_mfma_f32_16x16x32_bf16 v[24:27], v[212:215], v[204:207], v[24:27]
	v_mfma_f32_16x16x32_bf16 v[20:23], v[216:219], v[204:207], v[20:23]
	v_mfma_f32_16x16x32_bf16 v[16:19], v[220:223], v[204:207], v[16:19]
	s_waitcnt lgkmcnt(0)
	s_waitcnt vmcnt(4)
	s_barrier
	v_mfma_f32_16x16x32_bf16 v[108:111], v[224:227], v[192:195], v[108:111]
	ds_read_b128 v[176:179], v254 offset:0
	s_add_u32 m0, s101, 0x8000
	v_mfma_f32_16x16x32_bf16 v[104:107], v[228:231], v[192:195], v[104:107]
	ds_read_b128 v[180:183], v254 offset:2048
	global_load_lds_dwordx4 v[138:139], off
	v_lshl_add_u64 v[138:139], v[138:139], 0, s[34:35]
	v_mfma_f32_16x16x32_bf16 v[100:103], v[232:235], v[192:195], v[100:103]
	ds_read_b128 v[184:187], v254 offset:4096
	s_add_u32 m0, s101, 0xa000
	v_mfma_f32_16x16x32_bf16 v[96:99], v[236:239], v[192:195], v[96:99]
	ds_read_b128 v[188:191], v254 offset:6144
	global_load_lds_dwordx4 v[140:141], off
	v_lshl_add_u64 v[140:141], v[140:141], 0, s[34:35]
	v_mfma_f32_16x16x32_bf16 v[76:79], v[224:227], v[196:199], v[76:79]
	ds_read_b128 v[208:211], v174 offset:0
	s_add_u32 m0, s101, 0xc000
	v_mfma_f32_16x16x32_bf16 v[72:75], v[228:231], v[196:199], v[72:75]
	ds_read_b128 v[212:215], v174 offset:2048
	global_load_lds_dwordx4 v[250:251], off
	v_lshl_add_u64 v[250:251], v[250:251], 0, s[34:35]
	v_mfma_f32_16x16x32_bf16 v[68:71], v[232:235], v[196:199], v[68:71]
	ds_read_b128 v[216:219], v174 offset:4096
	s_add_u32 m0, s101, 0xe000
	v_mfma_f32_16x16x32_bf16 v[64:67], v[236:239], v[196:199], v[64:67]
	ds_read_b128 v[220:223], v174 offset:6144
	global_load_lds_dwordx4 v[252:253], off
	v_lshl_add_u64 v[252:253], v[252:253], 0, s[34:35]
	v_mfma_f32_16x16x32_bf16 v[44:47], v[224:227], v[200:203], v[44:47]
	v_mfma_f32_16x16x32_bf16 v[40:43], v[228:231], v[200:203], v[40:43]
	v_mfma_f32_16x16x32_bf16 v[36:39], v[232:235], v[200:203], v[36:39]
	v_mfma_f32_16x16x32_bf16 v[32:35], v[236:239], v[200:203], v[32:35]
	v_mfma_f32_16x16x32_bf16 v[12:15], v[224:227], v[204:207], v[12:15]
	v_mfma_f32_16x16x32_bf16 v[8:11], v[228:231], v[204:207], v[8:11]
	v_mfma_f32_16x16x32_bf16 v[4:7], v[232:235], v[204:207], v[4:7]
	v_mfma_f32_16x16x32_bf16 v[0:3], v[236:239], v[204:207], v[0:3]
	s_waitcnt lgkmcnt(0)
	v_mfma_f32_16x16x32_bf16 v[124:127], v[208:211], v[176:179], v[124:127]
	ds_read_b128 v[224:227], v174 offset:8192
	v_mfma_f32_16x16x32_bf16 v[120:123], v[212:215], v[176:179], v[120:123]
	ds_read_b128 v[228:231], v174 offset:10240
	v_mfma_f32_16x16x32_bf16 v[116:119], v[216:219], v[176:179], v[116:119]
	ds_read_b128 v[232:235], v174 offset:12288
	v_mfma_f32_16x16x32_bf16 v[112:115], v[220:223], v[176:179], v[112:115]
	ds_read_b128 v[236:239], v174 offset:14336
	v_mfma_f32_16x16x32_bf16 v[92:95], v[208:211], v[180:183], v[92:95]
	s_add_u32 m0, s100, 0x8000
	v_mfma_f32_16x16x32_bf16 v[88:91], v[212:215], v[180:183], v[88:91]
	global_load_lds_dwordx4 v[240:241], off
	v_lshl_add_u64 v[240:241], v[240:241], 0, s[34:35]
	v_mfma_f32_16x16x32_bf16 v[84:87], v[216:219], v[180:183], v[84:87]
	s_add_u32 m0, s100, 0xa000
	v_mfma_f32_16x16x32_bf16 v[80:83], v[220:223], v[180:183], v[80:83]
	global_load_lds_dwordx4 v[242:243], off
	v_lshl_add_u64 v[242:243], v[242:243], 0, s[34:35]
	v_mfma_f32_16x16x32_bf16 v[60:63], v[208:211], v[184:187], v[60:63]
	s_add_u32 m0, s100, 0xc000
	v_mfma_f32_16x16x32_bf16 v[56:59], v[212:215], v[184:187], v[56:59]
	global_load_lds_dwordx4 v[244:245], off
	v_lshl_add_u64 v[244:245], v[244:245], 0, s[34:35]
	v_mfma_f32_16x16x32_bf16 v[52:55], v[216:219], v[184:187], v[52:55]
	s_add_u32 m0, s100, 0xe000
	v_mfma_f32_16x16x32_bf16 v[48:51], v[220:223], v[184:187], v[48:51]
	global_load_lds_dwordx4 v[246:247], off
	v_lshl_add_u64 v[246:247], v[246:247], 0, s[34:35]
	v_mfma_f32_16x16x32_bf16 v[28:31], v[208:211], v[188:191], v[28:31]
	v_mfma_f32_16x16x32_bf16 v[24:27], v[212:215], v[188:191], v[24:27]
	v_mfma_f32_16x16x32_bf16 v[20:23], v[216:219], v[188:191], v[20:23]
	v_mfma_f32_16x16x32_bf16 v[16:19], v[220:223], v[188:191], v[16:19]
	s_waitcnt lgkmcnt(0)
	v_mfma_f32_16x16x32_bf16 v[108:111], v[224:227], v[176:179], v[108:111]
	ds_read_b128 v[192:195], v255 offset:0
	v_mfma_f32_16x16x32_bf16 v[104:107], v[228:231], v[176:179], v[104:107]
	ds_read_b128 v[196:199], v255 offset:2048
	v_mfma_f32_16x16x32_bf16 v[100:103], v[232:235], v[176:179], v[100:103]
	ds_read_b128 v[200:203], v255 offset:4096
	v_mfma_f32_16x16x32_bf16 v[96:99], v[236:239], v[176:179], v[96:99]
	ds_read_b128 v[204:207], v255 offset:6144
	v_mfma_f32_16x16x32_bf16 v[76:79], v[224:227], v[180:183], v[76:79]
	ds_read_b128 v[208:211], v175 offset:0
	v_mfma_f32_16x16x32_bf16 v[72:75], v[228:231], v[180:183], v[72:75]
	ds_read_b128 v[212:215], v175 offset:2048
	v_mfma_f32_16x16x32_bf16 v[68:71], v[232:235], v[180:183], v[68:71]
	ds_read_b128 v[216:219], v175 offset:4096
	v_mfma_f32_16x16x32_bf16 v[64:67], v[236:239], v[180:183], v[64:67]
	ds_read_b128 v[220:223], v175 offset:6144
	v_mfma_f32_16x16x32_bf16 v[44:47], v[224:227], v[184:187], v[44:47]
	v_mfma_f32_16x16x32_bf16 v[40:43], v[228:231], v[184:187], v[40:43]
	v_mfma_f32_16x16x32_bf16 v[36:39], v[232:235], v[184:187], v[36:39]
	v_mfma_f32_16x16x32_bf16 v[32:35], v[236:239], v[184:187], v[32:35]
	v_mfma_f32_16x16x32_bf16 v[12:15], v[224:227], v[188:191], v[12:15]
	v_mfma_f32_16x16x32_bf16 v[8:11], v[228:231], v[188:191], v[8:11]
	v_mfma_f32_16x16x32_bf16 v[4:7], v[232:235], v[188:191], v[4:7]
	v_mfma_f32_16x16x32_bf16 v[0:3], v[236:239], v[188:191], v[0:3]
	s_waitcnt lgkmcnt(0)
	v_mfma_f32_16x16x32_bf16 v[124:127], v[208:211], v[192:195], v[124:127]
	ds_read_b128 v[224:227], v175 offset:8192
	v_mfma_f32_16x16x32_bf16 v[120:123], v[212:215], v[192:195], v[120:123]
	ds_read_b128 v[228:231], v175 offset:10240
	v_mfma_f32_16x16x32_bf16 v[116:119], v[216:219], v[192:195], v[116:119]
	ds_read_b128 v[232:235], v175 offset:12288
	v_mfma_f32_16x16x32_bf16 v[112:115], v[220:223], v[192:195], v[112:115]
	ds_read_b128 v[236:239], v175 offset:14336
	v_mfma_f32_16x16x32_bf16 v[92:95], v[208:211], v[196:199], v[92:95]
	v_mfma_f32_16x16x32_bf16 v[88:91], v[212:215], v[196:199], v[88:91]
	v_mfma_f32_16x16x32_bf16 v[84:87], v[216:219], v[196:199], v[84:87]
	v_mfma_f32_16x16x32_bf16 v[80:83], v[220:223], v[196:199], v[80:83]
	v_mfma_f32_16x16x32_bf16 v[60:63], v[208:211], v[200:203], v[60:63]
	v_mfma_f32_16x16x32_bf16 v[56:59], v[212:215], v[200:203], v[56:59]
	v_mfma_f32_16x16x32_bf16 v[52:55], v[216:219], v[200:203], v[52:55]
	v_mfma_f32_16x16x32_bf16 v[48:51], v[220:223], v[200:203], v[48:51]
	v_mfma_f32_16x16x32_bf16 v[28:31], v[208:211], v[204:207], v[28:31]
	v_mfma_f32_16x16x32_bf16 v[24:27], v[212:215], v[204:207], v[24:27]
	v_mfma_f32_16x16x32_bf16 v[20:23], v[216:219], v[204:207], v[20:23]
	v_mfma_f32_16x16x32_bf16 v[16:19], v[220:223], v[204:207], v[16:19]
	s_waitcnt lgkmcnt(0)
	s_waitcnt vmcnt(4)
	s_barrier
	v_mfma_f32_16x16x32_bf16 v[108:111], v[224:227], v[192:195], v[108:111]
	ds_read_b128 v[176:179], v172 offset:0
	s_mov_b32 m0, s101
	v_mfma_f32_16x16x32_bf16 v[104:107], v[228:231], v[192:195], v[104:107]
	ds_read_b128 v[180:183], v172 offset:2048
	global_load_lds_dwordx4 v[138:139], off
	v_lshl_add_u64 v[138:139], v[138:139], 0, s[34:35]
	v_mfma_f32_16x16x32_bf16 v[100:103], v[232:235], v[192:195], v[100:103]
	ds_read_b128 v[184:187], v172 offset:4096
	s_add_u32 m0, s101, 0x2000
	v_mfma_f32_16x16x32_bf16 v[96:99], v[236:239], v[192:195], v[96:99]
	ds_read_b128 v[188:191], v172 offset:6144
	global_load_lds_dwordx4 v[140:141], off
	v_lshl_add_u64 v[140:141], v[140:141], 0, s[34:35]
	v_mfma_f32_16x16x32_bf16 v[76:79], v[224:227], v[196:199], v[76:79]
	ds_read_b128 v[208:211], v174 offset:32768
	s_add_u32 m0, s101, 0x4000
	v_mfma_f32_16x16x32_bf16 v[72:75], v[228:231], v[196:199], v[72:75]
	ds_read_b128 v[212:215], v174 offset:34816
	global_load_lds_dwordx4 v[250:251], off
	v_lshl_add_u64 v[250:251], v[250:251], 0, s[34:35]
	v_mfma_f32_16x16x32_bf16 v[68:71], v[232:235], v[196:199], v[68:71]
	ds_read_b128 v[216:219], v174 offset:36864
	s_add_u32 m0, s101, 0x6000
	v_mfma_f32_16x16x32_bf16 v[64:67], v[236:239], v[196:199], v[64:67]
	ds_read_b128 v[220:223], v174 offset:38912
	global_load_lds_dwordx4 v[252:253], off
	v_lshl_add_u64 v[252:253], v[252:253], 0, s[34:35]
	v_mfma_f32_16x16x32_bf16 v[44:47], v[224:227], v[200:203], v[44:47]
	v_mfma_f32_16x16x32_bf16 v[40:43], v[228:231], v[200:203], v[40:43]
	v_mfma_f32_16x16x32_bf16 v[36:39], v[232:235], v[200:203], v[36:39]
	v_mfma_f32_16x16x32_bf16 v[32:35], v[236:239], v[200:203], v[32:35]
	v_mfma_f32_16x16x32_bf16 v[12:15], v[224:227], v[204:207], v[12:15]
	v_mfma_f32_16x16x32_bf16 v[8:11], v[228:231], v[204:207], v[8:11]
	v_mfma_f32_16x16x32_bf16 v[4:7], v[232:235], v[204:207], v[4:7]
	v_mfma_f32_16x16x32_bf16 v[0:3], v[236:239], v[204:207], v[0:3]
	s_waitcnt lgkmcnt(0)
	v_mfma_f32_16x16x32_bf16 v[124:127], v[208:211], v[176:179], v[124:127]
	ds_read_b128 v[224:227], v174 offset:40960
	v_mfma_f32_16x16x32_bf16 v[120:123], v[212:215], v[176:179], v[120:123]
	ds_read_b128 v[228:231], v174 offset:43008
	v_mfma_f32_16x16x32_bf16 v[116:119], v[216:219], v[176:179], v[116:119]
	ds_read_b128 v[232:235], v174 offset:45056
	v_mfma_f32_16x16x32_bf16 v[112:115], v[220:223], v[176:179], v[112:115]
	ds_read_b128 v[236:239], v174 offset:47104
	v_mfma_f32_16x16x32_bf16 v[92:95], v[208:211], v[180:183], v[92:95]
	s_add_u32 m0, s100, 0x20000
	v_mfma_f32_16x16x32_bf16 v[88:91], v[212:215], v[180:183], v[88:91]
	global_load_lds_dwordx4 v[240:241], off
	v_lshl_add_u64 v[240:241], v[240:241], 0, s[34:35]
	v_mfma_f32_16x16x32_bf16 v[84:87], v[216:219], v[180:183], v[84:87]
	s_add_u32 m0, s100, 0x22000
	v_mfma_f32_16x16x32_bf16 v[80:83], v[220:223], v[180:183], v[80:83]
	global_load_lds_dwordx4 v[242:243], off
	v_lshl_add_u64 v[242:243], v[242:243], 0, s[34:35]
	v_mfma_f32_16x16x32_bf16 v[60:63], v[208:211], v[184:187], v[60:63]
	s_add_u32 m0, s100, 0x24000
	v_mfma_f32_16x16x32_bf16 v[56:59], v[212:215], v[184:187], v[56:59]
	global_load_lds_dwordx4 v[244:245], off
	v_lshl_add_u64 v[244:245], v[244:245], 0, s[34:35]
	v_mfma_f32_16x16x32_bf16 v[52:55], v[216:219], v[184:187], v[52:55]
	s_add_u32 m0, s100, 0x26000
	v_mfma_f32_16x16x32_bf16 v[48:51], v[220:223], v[184:187], v[48:51]
	global_load_lds_dwordx4 v[246:247], off
	v_lshl_add_u64 v[246:247], v[246:247], 0, s[34:35]
	v_mfma_f32_16x16x32_bf16 v[28:31], v[208:211], v[188:191], v[28:31]
	v_mfma_f32_16x16x32_bf16 v[24:27], v[212:215], v[188:191], v[24:27]
	v_mfma_f32_16x16x32_bf16 v[20:23], v[216:219], v[188:191], v[20:23]
	v_mfma_f32_16x16x32_bf16 v[16:19], v[220:223], v[188:191], v[16:19]
	s_waitcnt lgkmcnt(0)
	v_mfma_f32_16x16x32_bf16 v[108:111], v[224:227], v[176:179], v[108:111]
	ds_read_b128 v[192:195], v173 offset:0
	v_mfma_f32_16x16x32_bf16 v[104:107], v[228:231], v[176:179], v[104:107]
	ds_read_b128 v[196:199], v173 offset:2048
	v_mfma_f32_16x16x32_bf16 v[100:103], v[232:235], v[176:179], v[100:103]
	ds_read_b128 v[200:203], v173 offset:4096
	v_mfma_f32_16x16x32_bf16 v[96:99], v[236:239], v[176:179], v[96:99]
	ds_read_b128 v[204:207], v173 offset:6144
	v_mfma_f32_16x16x32_bf16 v[76:79], v[224:227], v[180:183], v[76:79]
	ds_read_b128 v[208:211], v175 offset:32768
	v_mfma_f32_16x16x32_bf16 v[72:75], v[228:231], v[180:183], v[72:75]
	ds_read_b128 v[212:215], v175 offset:34816
	v_mfma_f32_16x16x32_bf16 v[68:71], v[232:235], v[180:183], v[68:71]
	ds_read_b128 v[216:219], v175 offset:36864
	v_mfma_f32_16x16x32_bf16 v[64:67], v[236:239], v[180:183], v[64:67]
	ds_read_b128 v[220:223], v175 offset:38912
	v_mfma_f32_16x16x32_bf16 v[44:47], v[224:227], v[184:187], v[44:47]
	v_mfma_f32_16x16x32_bf16 v[40:43], v[228:231], v[184:187], v[40:43]
	v_mfma_f32_16x16x32_bf16 v[36:39], v[232:235], v[184:187], v[36:39]
	v_mfma_f32_16x16x32_bf16 v[32:35], v[236:239], v[184:187], v[32:35]
	v_mfma_f32_16x16x32_bf16 v[12:15], v[224:227], v[188:191], v[12:15]
	v_mfma_f32_16x16x32_bf16 v[8:11], v[228:231], v[188:191], v[8:11]
	v_mfma_f32_16x16x32_bf16 v[4:7], v[232:235], v[188:191], v[4:7]
	v_mfma_f32_16x16x32_bf16 v[0:3], v[236:239], v[188:191], v[0:3]
	s_waitcnt lgkmcnt(0)
	v_mfma_f32_16x16x32_bf16 v[124:127], v[208:211], v[192:195], v[124:127]
	ds_read_b128 v[224:227], v175 offset:40960
	v_mfma_f32_16x16x32_bf16 v[120:123], v[212:215], v[192:195], v[120:123]
	ds_read_b128 v[228:231], v175 offset:43008
	v_mfma_f32_16x16x32_bf16 v[116:119], v[216:219], v[192:195], v[116:119]
	ds_read_b128 v[232:235], v175 offset:45056
	v_mfma_f32_16x16x32_bf16 v[112:115], v[220:223], v[192:195], v[112:115]
	ds_read_b128 v[236:239], v175 offset:47104
	v_mfma_f32_16x16x32_bf16 v[92:95], v[208:211], v[196:199], v[92:95]
	v_mfma_f32_16x16x32_bf16 v[88:91], v[212:215], v[196:199], v[88:91]
	v_mfma_f32_16x16x32_bf16 v[84:87], v[216:219], v[196:199], v[84:87]
	v_mfma_f32_16x16x32_bf16 v[80:83], v[220:223], v[196:199], v[80:83]
	v_mfma_f32_16x16x32_bf16 v[60:63], v[208:211], v[200:203], v[60:63]
	v_mfma_f32_16x16x32_bf16 v[56:59], v[212:215], v[200:203], v[56:59]
	v_mfma_f32_16x16x32_bf16 v[52:55], v[216:219], v[200:203], v[52:55]
	v_mfma_f32_16x16x32_bf16 v[48:51], v[220:223], v[200:203], v[48:51]
	v_mfma_f32_16x16x32_bf16 v[28:31], v[208:211], v[204:207], v[28:31]
	v_mfma_f32_16x16x32_bf16 v[24:27], v[212:215], v[204:207], v[24:27]
	v_mfma_f32_16x16x32_bf16 v[20:23], v[216:219], v[204:207], v[20:23]
	v_mfma_f32_16x16x32_bf16 v[16:19], v[220:223], v[204:207], v[16:19]
	s_waitcnt lgkmcnt(0)
	s_waitcnt vmcnt(4)
	s_barrier
	v_mfma_f32_16x16x32_bf16 v[108:111], v[224:227], v[192:195], v[108:111]
	ds_read_b128 v[176:179], v172 offset:32768
	s_add_u32 m0, s101, 0x8000
	v_mfma_f32_16x16x32_bf16 v[104:107], v[228:231], v[192:195], v[104:107]
	ds_read_b128 v[180:183], v172 offset:34816
	global_load_lds_dwordx4 v[138:139], off
	v_lshl_add_u64 v[138:139], v[138:139], 0, s[34:35]
	v_mfma_f32_16x16x32_bf16 v[100:103], v[232:235], v[192:195], v[100:103]
	ds_read_b128 v[184:187], v172 offset:36864
	s_add_u32 m0, s101, 0xa000
	v_mfma_f32_16x16x32_bf16 v[96:99], v[236:239], v[192:195], v[96:99]
	ds_read_b128 v[188:191], v172 offset:38912
	global_load_lds_dwordx4 v[140:141], off
	v_lshl_add_u64 v[140:141], v[140:141], 0, s[34:35]
	v_mfma_f32_16x16x32_bf16 v[76:79], v[224:227], v[196:199], v[76:79]
	ds_read_b128 v[208:211], v174 offset:0
	s_add_u32 m0, s101, 0xc000
	v_mfma_f32_16x16x32_bf16 v[72:75], v[228:231], v[196:199], v[72:75]
	ds_read_b128 v[212:215], v174 offset:2048
	global_load_lds_dwordx4 v[250:251], off
	v_lshl_add_u64 v[250:251], v[250:251], 0, s[34:35]
	v_mfma_f32_16x16x32_bf16 v[68:71], v[232:235], v[196:199], v[68:71]
	ds_read_b128 v[216:219], v174 offset:4096
	s_add_u32 m0, s101, 0xe000
	v_mfma_f32_16x16x32_bf16 v[64:67], v[236:239], v[196:199], v[64:67]
	ds_read_b128 v[220:223], v174 offset:6144
	global_load_lds_dwordx4 v[252:253], off
	v_lshl_add_u64 v[252:253], v[252:253], 0, s[34:35]
	v_mfma_f32_16x16x32_bf16 v[44:47], v[224:227], v[200:203], v[44:47]
	v_mfma_f32_16x16x32_bf16 v[40:43], v[228:231], v[200:203], v[40:43]
	v_mfma_f32_16x16x32_bf16 v[36:39], v[232:235], v[200:203], v[36:39]
	v_mfma_f32_16x16x32_bf16 v[32:35], v[236:239], v[200:203], v[32:35]
	v_mfma_f32_16x16x32_bf16 v[12:15], v[224:227], v[204:207], v[12:15]
	v_mfma_f32_16x16x32_bf16 v[8:11], v[228:231], v[204:207], v[8:11]
	v_mfma_f32_16x16x32_bf16 v[4:7], v[232:235], v[204:207], v[4:7]
	v_mfma_f32_16x16x32_bf16 v[0:3], v[236:239], v[204:207], v[0:3]
	s_waitcnt lgkmcnt(0)
	v_mfma_f32_16x16x32_bf16 v[124:127], v[208:211], v[176:179], v[124:127]
	ds_read_b128 v[224:227], v174 offset:8192
	v_mfma_f32_16x16x32_bf16 v[120:123], v[212:215], v[176:179], v[120:123]
	ds_read_b128 v[228:231], v174 offset:10240
	v_mfma_f32_16x16x32_bf16 v[116:119], v[216:219], v[176:179], v[116:119]
	ds_read_b128 v[232:235], v174 offset:12288
	v_mfma_f32_16x16x32_bf16 v[112:115], v[220:223], v[176:179], v[112:115]
	ds_read_b128 v[236:239], v174 offset:14336
	v_mfma_f32_16x16x32_bf16 v[92:95], v[208:211], v[180:183], v[92:95]
	s_mov_b32 m0, s100
	v_mfma_f32_16x16x32_bf16 v[88:91], v[212:215], v[180:183], v[88:91]
	global_load_lds_dwordx4 v[240:241], off
	v_lshl_add_u64 v[240:241], v[240:241], 0, s[34:35]
	v_mfma_f32_16x16x32_bf16 v[84:87], v[216:219], v[180:183], v[84:87]
	s_add_u32 m0, s100, 0x2000
	v_mfma_f32_16x16x32_bf16 v[80:83], v[220:223], v[180:183], v[80:83]
	global_load_lds_dwordx4 v[242:243], off
	v_lshl_add_u64 v[242:243], v[242:243], 0, s[34:35]
	v_mfma_f32_16x16x32_bf16 v[60:63], v[208:211], v[184:187], v[60:63]
	s_add_u32 m0, s100, 0x4000
	v_mfma_f32_16x16x32_bf16 v[56:59], v[212:215], v[184:187], v[56:59]
	global_load_lds_dwordx4 v[244:245], off
	v_lshl_add_u64 v[244:245], v[244:245], 0, s[34:35]
	v_mfma_f32_16x16x32_bf16 v[52:55], v[216:219], v[184:187], v[52:55]
	s_add_u32 m0, s100, 0x6000
	v_mfma_f32_16x16x32_bf16 v[48:51], v[220:223], v[184:187], v[48:51]
	global_load_lds_dwordx4 v[246:247], off
	v_lshl_add_u64 v[246:247], v[246:247], 0, s[34:35]
	v_mfma_f32_16x16x32_bf16 v[28:31], v[208:211], v[188:191], v[28:31]
	v_mfma_f32_16x16x32_bf16 v[24:27], v[212:215], v[188:191], v[24:27]
	v_mfma_f32_16x16x32_bf16 v[20:23], v[216:219], v[188:191], v[20:23]
	v_mfma_f32_16x16x32_bf16 v[16:19], v[220:223], v[188:191], v[16:19]
	s_waitcnt lgkmcnt(0)
	v_mfma_f32_16x16x32_bf16 v[108:111], v[224:227], v[176:179], v[108:111]
	ds_read_b128 v[192:195], v173 offset:32768
	v_mfma_f32_16x16x32_bf16 v[104:107], v[228:231], v[176:179], v[104:107]
	ds_read_b128 v[196:199], v173 offset:34816
	v_mfma_f32_16x16x32_bf16 v[100:103], v[232:235], v[176:179], v[100:103]
	ds_read_b128 v[200:203], v173 offset:36864
	v_mfma_f32_16x16x32_bf16 v[96:99], v[236:239], v[176:179], v[96:99]
	ds_read_b128 v[204:207], v173 offset:38912
	v_mfma_f32_16x16x32_bf16 v[76:79], v[224:227], v[180:183], v[76:79]
	ds_read_b128 v[208:211], v175 offset:0
	v_mfma_f32_16x16x32_bf16 v[72:75], v[228:231], v[180:183], v[72:75]
	ds_read_b128 v[212:215], v175 offset:2048
	v_mfma_f32_16x16x32_bf16 v[68:71], v[232:235], v[180:183], v[68:71]
	ds_read_b128 v[216:219], v175 offset:4096
	v_mfma_f32_16x16x32_bf16 v[64:67], v[236:239], v[180:183], v[64:67]
	ds_read_b128 v[220:223], v175 offset:6144
	v_mfma_f32_16x16x32_bf16 v[44:47], v[224:227], v[184:187], v[44:47]
	v_mfma_f32_16x16x32_bf16 v[40:43], v[228:231], v[184:187], v[40:43]
	v_mfma_f32_16x16x32_bf16 v[36:39], v[232:235], v[184:187], v[36:39]
	v_mfma_f32_16x16x32_bf16 v[32:35], v[236:239], v[184:187], v[32:35]
	v_mfma_f32_16x16x32_bf16 v[12:15], v[224:227], v[188:191], v[12:15]
	v_mfma_f32_16x16x32_bf16 v[8:11], v[228:231], v[188:191], v[8:11]
	v_mfma_f32_16x16x32_bf16 v[4:7], v[232:235], v[188:191], v[4:7]
	v_mfma_f32_16x16x32_bf16 v[0:3], v[236:239], v[188:191], v[0:3]
	s_waitcnt lgkmcnt(0)
	v_mfma_f32_16x16x32_bf16 v[124:127], v[208:211], v[192:195], v[124:127]
	ds_read_b128 v[224:227], v175 offset:8192
	v_mfma_f32_16x16x32_bf16 v[120:123], v[212:215], v[192:195], v[120:123]
	ds_read_b128 v[228:231], v175 offset:10240
	v_mfma_f32_16x16x32_bf16 v[116:119], v[216:219], v[192:195], v[116:119]
	ds_read_b128 v[232:235], v175 offset:12288
	v_mfma_f32_16x16x32_bf16 v[112:115], v[220:223], v[192:195], v[112:115]
	ds_read_b128 v[236:239], v175 offset:14336
	v_mfma_f32_16x16x32_bf16 v[92:95], v[208:211], v[196:199], v[92:95]
	v_mfma_f32_16x16x32_bf16 v[88:91], v[212:215], v[196:199], v[88:91]
	v_mfma_f32_16x16x32_bf16 v[84:87], v[216:219], v[196:199], v[84:87]
	v_mfma_f32_16x16x32_bf16 v[80:83], v[220:223], v[196:199], v[80:83]
	v_mfma_f32_16x16x32_bf16 v[60:63], v[208:211], v[200:203], v[60:63]
	v_mfma_f32_16x16x32_bf16 v[56:59], v[212:215], v[200:203], v[56:59]
	v_mfma_f32_16x16x32_bf16 v[52:55], v[216:219], v[200:203], v[52:55]
	v_mfma_f32_16x16x32_bf16 v[48:51], v[220:223], v[200:203], v[48:51]
	v_mfma_f32_16x16x32_bf16 v[28:31], v[208:211], v[204:207], v[28:31]
	v_mfma_f32_16x16x32_bf16 v[24:27], v[212:215], v[204:207], v[24:27]
	v_mfma_f32_16x16x32_bf16 v[20:23], v[216:219], v[204:207], v[20:23]
	v_mfma_f32_16x16x32_bf16 v[16:19], v[220:223], v[204:207], v[16:19]
	s_waitcnt lgkmcnt(0)
	s_waitcnt vmcnt(4)
	s_barrier
	v_mfma_f32_16x16x32_bf16 v[108:111], v[224:227], v[192:195], v[108:111]
	ds_read_b128 v[176:179], v254 offset:0
	s_mov_b32 m0, s101
	v_mfma_f32_16x16x32_bf16 v[104:107], v[228:231], v[192:195], v[104:107]
	ds_read_b128 v[180:183], v254 offset:2048
	global_load_lds_dwordx4 v[138:139], off
	v_lshl_add_u64 v[138:139], v[138:139], 0, s[34:35]
	v_mfma_f32_16x16x32_bf16 v[100:103], v[232:235], v[192:195], v[100:103]
	ds_read_b128 v[184:187], v254 offset:4096
	s_add_u32 m0, s101, 0x2000
	v_mfma_f32_16x16x32_bf16 v[96:99], v[236:239], v[192:195], v[96:99]
	ds_read_b128 v[188:191], v254 offset:6144
	global_load_lds_dwordx4 v[140:141], off
	v_lshl_add_u64 v[140:141], v[140:141], 0, s[34:35]
	v_mfma_f32_16x16x32_bf16 v[76:79], v[224:227], v[196:199], v[76:79]
	ds_read_b128 v[208:211], v174 offset:32768
	s_add_u32 m0, s101, 0x4000
	v_mfma_f32_16x16x32_bf16 v[72:75], v[228:231], v[196:199], v[72:75]
	ds_read_b128 v[212:215], v174 offset:34816
	global_load_lds_dwordx4 v[250:251], off
	v_lshl_add_u64 v[250:251], v[250:251], 0, s[34:35]
	v_mfma_f32_16x16x32_bf16 v[68:71], v[232:235], v[196:199], v[68:71]
	ds_read_b128 v[216:219], v174 offset:36864
	s_add_u32 m0, s101, 0x6000
	v_mfma_f32_16x16x32_bf16 v[64:67], v[236:239], v[196:199], v[64:67]
	ds_read_b128 v[220:223], v174 offset:38912
	global_load_lds_dwordx4 v[252:253], off
	v_lshl_add_u64 v[252:253], v[252:253], 0, s[34:35]
	v_mfma_f32_16x16x32_bf16 v[44:47], v[224:227], v[200:203], v[44:47]
	v_mfma_f32_16x16x32_bf16 v[40:43], v[228:231], v[200:203], v[40:43]
	v_mfma_f32_16x16x32_bf16 v[36:39], v[232:235], v[200:203], v[36:39]
	v_mfma_f32_16x16x32_bf16 v[32:35], v[236:239], v[200:203], v[32:35]
	v_mfma_f32_16x16x32_bf16 v[12:15], v[224:227], v[204:207], v[12:15]
	v_mfma_f32_16x16x32_bf16 v[8:11], v[228:231], v[204:207], v[8:11]
	v_mfma_f32_16x16x32_bf16 v[4:7], v[232:235], v[204:207], v[4:7]
	v_mfma_f32_16x16x32_bf16 v[0:3], v[236:239], v[204:207], v[0:3]
	s_waitcnt lgkmcnt(0)
	v_mfma_f32_16x16x32_bf16 v[124:127], v[208:211], v[176:179], v[124:127]
	ds_read_b128 v[224:227], v174 offset:40960
	v_mfma_f32_16x16x32_bf16 v[120:123], v[212:215], v[176:179], v[120:123]
	ds_read_b128 v[228:231], v174 offset:43008
	v_mfma_f32_16x16x32_bf16 v[116:119], v[216:219], v[176:179], v[116:119]
	ds_read_b128 v[232:235], v174 offset:45056
	v_mfma_f32_16x16x32_bf16 v[112:115], v[220:223], v[176:179], v[112:115]
	ds_read_b128 v[236:239], v174 offset:47104
	v_mfma_f32_16x16x32_bf16 v[92:95], v[208:211], v[180:183], v[92:95]
	s_add_u32 m0, s100, 0x8000
	v_mfma_f32_16x16x32_bf16 v[88:91], v[212:215], v[180:183], v[88:91]
	global_load_lds_dwordx4 v[240:241], off
	v_lshl_add_u64 v[240:241], v[240:241], 0, s[34:35]
	v_mfma_f32_16x16x32_bf16 v[84:87], v[216:219], v[180:183], v[84:87]
	s_add_u32 m0, s100, 0xa000
	v_mfma_f32_16x16x32_bf16 v[80:83], v[220:223], v[180:183], v[80:83]
	global_load_lds_dwordx4 v[242:243], off
	v_lshl_add_u64 v[242:243], v[242:243], 0, s[34:35]
	v_mfma_f32_16x16x32_bf16 v[60:63], v[208:211], v[184:187], v[60:63]
	s_add_u32 m0, s100, 0xc000
	v_mfma_f32_16x16x32_bf16 v[56:59], v[212:215], v[184:187], v[56:59]
	global_load_lds_dwordx4 v[244:245], off
	v_lshl_add_u64 v[244:245], v[244:245], 0, s[34:35]
	v_mfma_f32_16x16x32_bf16 v[52:55], v[216:219], v[184:187], v[52:55]
	s_add_u32 m0, s100, 0xe000
	v_mfma_f32_16x16x32_bf16 v[48:51], v[220:223], v[184:187], v[48:51]
	global_load_lds_dwordx4 v[246:247], off
	v_lshl_add_u64 v[246:247], v[246:247], 0, s[34:35]
	v_mfma_f32_16x16x32_bf16 v[28:31], v[208:211], v[188:191], v[28:31]
	v_mfma_f32_16x16x32_bf16 v[24:27], v[212:215], v[188:191], v[24:27]
	v_mfma_f32_16x16x32_bf16 v[20:23], v[216:219], v[188:191], v[20:23]
	v_mfma_f32_16x16x32_bf16 v[16:19], v[220:223], v[188:191], v[16:19]
	s_waitcnt lgkmcnt(0)
	v_mfma_f32_16x16x32_bf16 v[108:111], v[224:227], v[176:179], v[108:111]
	ds_read_b128 v[192:195], v255 offset:0
	v_mfma_f32_16x16x32_bf16 v[104:107], v[228:231], v[176:179], v[104:107]
	ds_read_b128 v[196:199], v255 offset:2048
	v_mfma_f32_16x16x32_bf16 v[100:103], v[232:235], v[176:179], v[100:103]
	ds_read_b128 v[200:203], v255 offset:4096
	v_mfma_f32_16x16x32_bf16 v[96:99], v[236:239], v[176:179], v[96:99]
	ds_read_b128 v[204:207], v255 offset:6144
	v_mfma_f32_16x16x32_bf16 v[76:79], v[224:227], v[180:183], v[76:79]
	ds_read_b128 v[208:211], v175 offset:32768
	v_mfma_f32_16x16x32_bf16 v[72:75], v[228:231], v[180:183], v[72:75]
	ds_read_b128 v[212:215], v175 offset:34816
	v_mfma_f32_16x16x32_bf16 v[68:71], v[232:235], v[180:183], v[68:71]
	ds_read_b128 v[216:219], v175 offset:36864
	v_mfma_f32_16x16x32_bf16 v[64:67], v[236:239], v[180:183], v[64:67]
	ds_read_b128 v[220:223], v175 offset:38912
	v_mfma_f32_16x16x32_bf16 v[44:47], v[224:227], v[184:187], v[44:47]
	v_mfma_f32_16x16x32_bf16 v[40:43], v[228:231], v[184:187], v[40:43]
	v_mfma_f32_16x16x32_bf16 v[36:39], v[232:235], v[184:187], v[36:39]
	v_mfma_f32_16x16x32_bf16 v[32:35], v[236:239], v[184:187], v[32:35]
	v_mfma_f32_16x16x32_bf16 v[12:15], v[224:227], v[188:191], v[12:15]
	v_mfma_f32_16x16x32_bf16 v[8:11], v[228:231], v[188:191], v[8:11]
	v_mfma_f32_16x16x32_bf16 v[4:7], v[232:235], v[188:191], v[4:7]
	v_mfma_f32_16x16x32_bf16 v[0:3], v[236:239], v[188:191], v[0:3]
	s_waitcnt lgkmcnt(0)
	v_mfma_f32_16x16x32_bf16 v[124:127], v[208:211], v[192:195], v[124:127]
	ds_read_b128 v[224:227], v175 offset:40960
	v_mfma_f32_16x16x32_bf16 v[120:123], v[212:215], v[192:195], v[120:123]
	ds_read_b128 v[228:231], v175 offset:43008
	v_mfma_f32_16x16x32_bf16 v[116:119], v[216:219], v[192:195], v[116:119]
	ds_read_b128 v[232:235], v175 offset:45056
	v_mfma_f32_16x16x32_bf16 v[112:115], v[220:223], v[192:195], v[112:115]
	ds_read_b128 v[236:239], v175 offset:47104
	v_mfma_f32_16x16x32_bf16 v[92:95], v[208:211], v[196:199], v[92:95]
	v_mfma_f32_16x16x32_bf16 v[88:91], v[212:215], v[196:199], v[88:91]
	v_mfma_f32_16x16x32_bf16 v[84:87], v[216:219], v[196:199], v[84:87]
	v_mfma_f32_16x16x32_bf16 v[80:83], v[220:223], v[196:199], v[80:83]
	v_mfma_f32_16x16x32_bf16 v[60:63], v[208:211], v[200:203], v[60:63]
	v_mfma_f32_16x16x32_bf16 v[56:59], v[212:215], v[200:203], v[56:59]
	v_mfma_f32_16x16x32_bf16 v[52:55], v[216:219], v[200:203], v[52:55]
	v_mfma_f32_16x16x32_bf16 v[48:51], v[220:223], v[200:203], v[48:51]
	v_mfma_f32_16x16x32_bf16 v[28:31], v[208:211], v[204:207], v[28:31]
	v_mfma_f32_16x16x32_bf16 v[24:27], v[212:215], v[204:207], v[24:27]
	v_mfma_f32_16x16x32_bf16 v[20:23], v[216:219], v[204:207], v[20:23]
	v_mfma_f32_16x16x32_bf16 v[16:19], v[220:223], v[204:207], v[16:19]
	s_waitcnt lgkmcnt(0)
	s_waitcnt vmcnt(4)
	s_barrier
	v_mfma_f32_16x16x32_bf16 v[108:111], v[224:227], v[192:195], v[108:111]
	ds_read_b128 v[176:179], v172 offset:0
	s_add_u32 m0, s101, 0x8000
	v_mfma_f32_16x16x32_bf16 v[104:107], v[228:231], v[192:195], v[104:107]
	ds_read_b128 v[180:183], v172 offset:2048
	global_load_lds_dwordx4 v[138:139], off
	v_lshl_add_u64 v[138:139], v[138:139], 0, s[34:35]
	v_mfma_f32_16x16x32_bf16 v[100:103], v[232:235], v[192:195], v[100:103]
	ds_read_b128 v[184:187], v172 offset:4096
	s_add_u32 m0, s101, 0xa000
	v_mfma_f32_16x16x32_bf16 v[96:99], v[236:239], v[192:195], v[96:99]
	ds_read_b128 v[188:191], v172 offset:6144
	global_load_lds_dwordx4 v[140:141], off
	v_lshl_add_u64 v[140:141], v[140:141], 0, s[34:35]
	v_mfma_f32_16x16x32_bf16 v[76:79], v[224:227], v[196:199], v[76:79]
	ds_read_b128 v[208:211], v174 offset:0
	s_add_u32 m0, s101, 0xc000
	v_mfma_f32_16x16x32_bf16 v[72:75], v[228:231], v[196:199], v[72:75]
	ds_read_b128 v[212:215], v174 offset:2048
	global_load_lds_dwordx4 v[250:251], off
	v_lshl_add_u64 v[250:251], v[250:251], 0, s[34:35]
	v_mfma_f32_16x16x32_bf16 v[68:71], v[232:235], v[196:199], v[68:71]
	ds_read_b128 v[216:219], v174 offset:4096
	s_add_u32 m0, s101, 0xe000
	v_mfma_f32_16x16x32_bf16 v[64:67], v[236:239], v[196:199], v[64:67]
	ds_read_b128 v[220:223], v174 offset:6144
	global_load_lds_dwordx4 v[252:253], off
	v_lshl_add_u64 v[252:253], v[252:253], 0, s[34:35]
	v_mfma_f32_16x16x32_bf16 v[44:47], v[224:227], v[200:203], v[44:47]
	v_mfma_f32_16x16x32_bf16 v[40:43], v[228:231], v[200:203], v[40:43]
	v_mfma_f32_16x16x32_bf16 v[36:39], v[232:235], v[200:203], v[36:39]
	v_mfma_f32_16x16x32_bf16 v[32:35], v[236:239], v[200:203], v[32:35]
	v_mfma_f32_16x16x32_bf16 v[12:15], v[224:227], v[204:207], v[12:15]
	v_mfma_f32_16x16x32_bf16 v[8:11], v[228:231], v[204:207], v[8:11]
	v_mfma_f32_16x16x32_bf16 v[4:7], v[232:235], v[204:207], v[4:7]
	v_mfma_f32_16x16x32_bf16 v[0:3], v[236:239], v[204:207], v[0:3]
	s_waitcnt lgkmcnt(0)
	v_mfma_f32_16x16x32_bf16 v[124:127], v[208:211], v[176:179], v[124:127]
	ds_read_b128 v[224:227], v174 offset:8192
	v_mfma_f32_16x16x32_bf16 v[120:123], v[212:215], v[176:179], v[120:123]
	ds_read_b128 v[228:231], v174 offset:10240
	v_mfma_f32_16x16x32_bf16 v[116:119], v[216:219], v[176:179], v[116:119]
	ds_read_b128 v[232:235], v174 offset:12288
	v_mfma_f32_16x16x32_bf16 v[112:115], v[220:223], v[176:179], v[112:115]
	ds_read_b128 v[236:239], v174 offset:14336
	v_mfma_f32_16x16x32_bf16 v[92:95], v[208:211], v[180:183], v[92:95]
	s_add_u32 m0, s100, 0x20000
	v_mfma_f32_16x16x32_bf16 v[88:91], v[212:215], v[180:183], v[88:91]
	global_load_lds_dwordx4 v[240:241], off
	v_lshl_add_u64 v[240:241], v[240:241], 0, s[34:35]
	v_mfma_f32_16x16x32_bf16 v[84:87], v[216:219], v[180:183], v[84:87]
	s_add_u32 m0, s100, 0x22000
	v_mfma_f32_16x16x32_bf16 v[80:83], v[220:223], v[180:183], v[80:83]
	global_load_lds_dwordx4 v[242:243], off
	v_lshl_add_u64 v[242:243], v[242:243], 0, s[34:35]
	v_mfma_f32_16x16x32_bf16 v[60:63], v[208:211], v[184:187], v[60:63]
	s_add_u32 m0, s100, 0x24000
	v_mfma_f32_16x16x32_bf16 v[56:59], v[212:215], v[184:187], v[56:59]
	global_load_lds_dwordx4 v[244:245], off
	v_lshl_add_u64 v[244:245], v[244:245], 0, s[34:35]
	v_mfma_f32_16x16x32_bf16 v[52:55], v[216:219], v[184:187], v[52:55]
	s_add_u32 m0, s100, 0x26000
	v_mfma_f32_16x16x32_bf16 v[48:51], v[220:223], v[184:187], v[48:51]
	global_load_lds_dwordx4 v[246:247], off
	v_lshl_add_u64 v[246:247], v[246:247], 0, s[34:35]
	v_mfma_f32_16x16x32_bf16 v[28:31], v[208:211], v[188:191], v[28:31]
	v_mfma_f32_16x16x32_bf16 v[24:27], v[212:215], v[188:191], v[24:27]
	v_mfma_f32_16x16x32_bf16 v[20:23], v[216:219], v[188:191], v[20:23]
	v_mfma_f32_16x16x32_bf16 v[16:19], v[220:223], v[188:191], v[16:19]
	s_waitcnt lgkmcnt(0)
	v_mfma_f32_16x16x32_bf16 v[108:111], v[224:227], v[176:179], v[108:111]
	ds_read_b128 v[192:195], v173 offset:0
	v_mfma_f32_16x16x32_bf16 v[104:107], v[228:231], v[176:179], v[104:107]
	ds_read_b128 v[196:199], v173 offset:2048
	v_mfma_f32_16x16x32_bf16 v[100:103], v[232:235], v[176:179], v[100:103]
	ds_read_b128 v[200:203], v173 offset:4096
	v_mfma_f32_16x16x32_bf16 v[96:99], v[236:239], v[176:179], v[96:99]
	ds_read_b128 v[204:207], v173 offset:6144
	v_mfma_f32_16x16x32_bf16 v[76:79], v[224:227], v[180:183], v[76:79]
	ds_read_b128 v[208:211], v175 offset:0
	v_mfma_f32_16x16x32_bf16 v[72:75], v[228:231], v[180:183], v[72:75]
	ds_read_b128 v[212:215], v175 offset:2048
	v_mfma_f32_16x16x32_bf16 v[68:71], v[232:235], v[180:183], v[68:71]
	ds_read_b128 v[216:219], v175 offset:4096
	v_mfma_f32_16x16x32_bf16 v[64:67], v[236:239], v[180:183], v[64:67]
	ds_read_b128 v[220:223], v175 offset:6144
	v_mfma_f32_16x16x32_bf16 v[44:47], v[224:227], v[184:187], v[44:47]
	v_mfma_f32_16x16x32_bf16 v[40:43], v[228:231], v[184:187], v[40:43]
	v_mfma_f32_16x16x32_bf16 v[36:39], v[232:235], v[184:187], v[36:39]
	v_mfma_f32_16x16x32_bf16 v[32:35], v[236:239], v[184:187], v[32:35]
	v_mfma_f32_16x16x32_bf16 v[12:15], v[224:227], v[188:191], v[12:15]
	v_mfma_f32_16x16x32_bf16 v[8:11], v[228:231], v[188:191], v[8:11]
	v_mfma_f32_16x16x32_bf16 v[4:7], v[232:235], v[188:191], v[4:7]
	v_mfma_f32_16x16x32_bf16 v[0:3], v[236:239], v[188:191], v[0:3]
	s_waitcnt lgkmcnt(0)
	v_mfma_f32_16x16x32_bf16 v[124:127], v[208:211], v[192:195], v[124:127]
	ds_read_b128 v[224:227], v175 offset:8192
	v_mfma_f32_16x16x32_bf16 v[120:123], v[212:215], v[192:195], v[120:123]
	ds_read_b128 v[228:231], v175 offset:10240
	v_mfma_f32_16x16x32_bf16 v[116:119], v[216:219], v[192:195], v[116:119]
	ds_read_b128 v[232:235], v175 offset:12288
	v_mfma_f32_16x16x32_bf16 v[112:115], v[220:223], v[192:195], v[112:115]
	ds_read_b128 v[236:239], v175 offset:14336
	v_mfma_f32_16x16x32_bf16 v[92:95], v[208:211], v[196:199], v[92:95]
	v_mfma_f32_16x16x32_bf16 v[88:91], v[212:215], v[196:199], v[88:91]
	v_mfma_f32_16x16x32_bf16 v[84:87], v[216:219], v[196:199], v[84:87]
	v_mfma_f32_16x16x32_bf16 v[80:83], v[220:223], v[196:199], v[80:83]
	v_mfma_f32_16x16x32_bf16 v[60:63], v[208:211], v[200:203], v[60:63]
	v_mfma_f32_16x16x32_bf16 v[56:59], v[212:215], v[200:203], v[56:59]
	v_mfma_f32_16x16x32_bf16 v[52:55], v[216:219], v[200:203], v[52:55]
	v_mfma_f32_16x16x32_bf16 v[48:51], v[220:223], v[200:203], v[48:51]
	v_mfma_f32_16x16x32_bf16 v[28:31], v[208:211], v[204:207], v[28:31]
	v_mfma_f32_16x16x32_bf16 v[24:27], v[212:215], v[204:207], v[24:27]
	v_mfma_f32_16x16x32_bf16 v[20:23], v[216:219], v[204:207], v[20:23]
	v_mfma_f32_16x16x32_bf16 v[16:19], v[220:223], v[204:207], v[16:19]
	s_waitcnt lgkmcnt(0)
	s_waitcnt vmcnt(4)
	s_barrier
	s_add_i32 s46, s46, -1
	s_cmp_lg_u32 s46, 0
	s_cbranch_scc1 .Lgemm_p7_loop
	v_mfma_f32_16x16x32_bf16 v[108:111], v[224:227], v[192:195], v[108:111]
	ds_read_b128 v[176:179], v172 offset:32768
	s_mov_b32 m0, s101
	v_mfma_f32_16x16x32_bf16 v[104:107], v[228:231], v[192:195], v[104:107]
	ds_read_b128 v[180:183], v172 offset:34816
	global_load_lds_dwordx4 v[138:139], off
	v_lshl_add_u64 v[138:139], v[138:139], 0, s[34:35]
	v_mfma_f32_16x16x32_bf16 v[100:103], v[232:235], v[192:195], v[100:103]
	ds_read_b128 v[184:187], v172 offset:36864
	s_add_u32 m0, s101, 0x2000
	v_mfma_f32_16x16x32_bf16 v[96:99], v[236:239], v[192:195], v[96:99]
	ds_read_b128 v[188:191], v172 offset:38912
	global_load_lds_dwordx4 v[140:141], off
	v_lshl_add_u64 v[140:141], v[140:141], 0, s[34:35]
	v_mfma_f32_16x16x32_bf16 v[76:79], v[224:227], v[196:199], v[76:79]
	ds_read_b128 v[208:211], v174 offset:32768
	s_add_u32 m0, s101, 0x4000
	v_mfma_f32_16x16x32_bf16 v[72:75], v[228:231], v[196:199], v[72:75]
	ds_read_b128 v[212:215], v174 offset:34816
	global_load_lds_dwordx4 v[250:251], off
	v_lshl_add_u64 v[250:251], v[250:251], 0, s[34:35]
	v_mfma_f32_16x16x32_bf16 v[68:71], v[232:235], v[196:199], v[68:71]
	ds_read_b128 v[216:219], v174 offset:36864
	s_add_u32 m0, s101, 0x6000
	v_mfma_f32_16x16x32_bf16 v[64:67], v[236:239], v[196:199], v[64:67]
	ds_read_b128 v[220:223], v174 offset:38912
	global_load_lds_dwordx4 v[252:253], off
	v_lshl_add_u64 v[252:253], v[252:253], 0, s[34:35]
	v_mfma_f32_16x16x32_bf16 v[44:47], v[224:227], v[200:203], v[44:47]
	v_mfma_f32_16x16x32_bf16 v[40:43], v[228:231], v[200:203], v[40:43]
	v_mfma_f32_16x16x32_bf16 v[36:39], v[232:235], v[200:203], v[36:39]
	v_mfma_f32_16x16x32_bf16 v[32:35], v[236:239], v[200:203], v[32:35]
	v_mfma_f32_16x16x32_bf16 v[12:15], v[224:227], v[204:207], v[12:15]
	v_mfma_f32_16x16x32_bf16 v[8:11], v[228:231], v[204:207], v[8:11]
	v_mfma_f32_16x16x32_bf16 v[4:7], v[232:235], v[204:207], v[4:7]
	v_mfma_f32_16x16x32_bf16 v[0:3], v[236:239], v[204:207], v[0:3]
	s_waitcnt lgkmcnt(0)
	v_mfma_f32_16x16x32_bf16 v[124:127], v[208:211], v[176:179], v[124:127]
	ds_read_b128 v[224:227], v174 offset:40960
	v_mfma_f32_16x16x32_bf16 v[120:123], v[212:215], v[176:179], v[120:123]
	ds_read_b128 v[228:231], v174 offset:43008
	v_mfma_f32_16x16x32_bf16 v[116:119], v[216:219], v[176:179], v[116:119]
	ds_read_b128 v[232:235], v174 offset:45056
	v_mfma_f32_16x16x32_bf16 v[112:115], v[220:223], v[176:179], v[112:115]
	ds_read_b128 v[236:239], v174 offset:47104
	v_mfma_f32_16x16x32_bf16 v[92:95], v[208:211], v[180:183], v[92:95]
	s_mov_b32 m0, s100
	v_mfma_f32_16x16x32_bf16 v[88:91], v[212:215], v[180:183], v[88:91]
	global_load_lds_dwordx4 v[240:241], off
	v_lshl_add_u64 v[240:241], v[240:241], 0, s[34:35]
	v_mfma_f32_16x16x32_bf16 v[84:87], v[216:219], v[180:183], v[84:87]
	s_add_u32 m0, s100, 0x2000
	v_mfma_f32_16x16x32_bf16 v[80:83], v[220:223], v[180:183], v[80:83]
	global_load_lds_dwordx4 v[242:243], off
	v_lshl_add_u64 v[242:243], v[242:243], 0, s[34:35]
	v_mfma_f32_16x16x32_bf16 v[60:63], v[208:211], v[184:187], v[60:63]
	s_add_u32 m0, s100, 0x4000
	v_mfma_f32_16x16x32_bf16 v[56:59], v[212:215], v[184:187], v[56:59]
	global_load_lds_dwordx4 v[244:245], off
	v_lshl_add_u64 v[244:245], v[244:245], 0, s[34:35]
	v_mfma_f32_16x16x32_bf16 v[52:55], v[216:219], v[184:187], v[52:55]
	s_add_u32 m0, s100, 0x6000
	v_mfma_f32_16x16x32_bf16 v[48:51], v[220:223], v[184:187], v[48:51]
	global_load_lds_dwordx4 v[246:247], off
	v_lshl_add_u64 v[246:247], v[246:247], 0, s[34:35]
	v_mfma_f32_16x16x32_bf16 v[28:31], v[208:211], v[188:191], v[28:31]
	v_mfma_f32_16x16x32_bf16 v[24:27], v[212:215], v[188:191], v[24:27]
	v_mfma_f32_16x16x32_bf16 v[20:23], v[216:219], v[188:191], v[20:23]
	v_mfma_f32_16x16x32_bf16 v[16:19], v[220:223], v[188:191], v[16:19]
	s_waitcnt lgkmcnt(0)
	v_mfma_f32_16x16x32_bf16 v[108:111], v[224:227], v[176:179], v[108:111]
	ds_read_b128 v[192:195], v173 offset:32768
	v_mfma_f32_16x16x32_bf16 v[104:107], v[228:231], v[176:179], v[104:107]
	ds_read_b128 v[196:199], v173 offset:34816
	v_mfma_f32_16x16x32_bf16 v[100:103], v[232:235], v[176:179], v[100:103]
	ds_read_b128 v[200:203], v173 offset:36864
	v_mfma_f32_16x16x32_bf16 v[96:99], v[236:239], v[176:179], v[96:99]
	ds_read_b128 v[204:207], v173 offset:38912
	v_mfma_f32_16x16x32_bf16 v[76:79], v[224:227], v[180:183], v[76:79]
	ds_read_b128 v[208:211], v175 offset:32768
	v_mfma_f32_16x16x32_bf16 v[72:75], v[228:231], v[180:183], v[72:75]
	ds_read_b128 v[212:215], v175 offset:34816
	v_mfma_f32_16x16x32_bf16 v[68:71], v[232:235], v[180:183], v[68:71]
	ds_read_b128 v[216:219], v175 offset:36864
	v_mfma_f32_16x16x32_bf16 v[64:67], v[236:239], v[180:183], v[64:67]
	ds_read_b128 v[220:223], v175 offset:38912
	v_mfma_f32_16x16x32_bf16 v[44:47], v[224:227], v[184:187], v[44:47]
	v_mfma_f32_16x16x32_bf16 v[40:43], v[228:231], v[184:187], v[40:43]
	v_mfma_f32_16x16x32_bf16 v[36:39], v[232:235], v[184:187], v[36:39]
	v_mfma_f32_16x16x32_bf16 v[32:35], v[236:239], v[184:187], v[32:35]
	v_mfma_f32_16x16x32_bf16 v[12:15], v[224:227], v[188:191], v[12:15]
	v_mfma_f32_16x16x32_bf16 v[8:11], v[228:231], v[188:191], v[8:11]
	v_mfma_f32_16x16x32_bf16 v[4:7], v[232:235], v[188:191], v[4:7]
	v_mfma_f32_16x16x32_bf16 v[0:3], v[236:239], v[188:191], v[0:3]
	s_waitcnt lgkmcnt(0)
	v_mfma_f32_16x16x32_bf16 v[124:127], v[208:211], v[192:195], v[124:127]
	ds_read_b128 v[224:227], v175 offset:40960
	v_mfma_f32_16x16x32_bf16 v[120:123], v[212:215], v[192:195], v[120:123]
	ds_read_b128 v[228:231], v175 offset:43008
	v_mfma_f32_16x16x32_bf16 v[116:119], v[216:219], v[192:195], v[116:119]
	ds_read_b128 v[232:235], v175 offset:45056
	v_mfma_f32_16x16x32_bf16 v[112:115], v[220:223], v[192:195], v[112:115]
	ds_read_b128 v[236:239], v175 offset:47104
	v_mfma_f32_16x16x32_bf16 v[92:95], v[208:211], v[196:199], v[92:95]
	v_mfma_f32_16x16x32_bf16 v[88:91], v[212:215], v[196:199], v[88:91]
	v_mfma_f32_16x16x32_bf16 v[84:87], v[216:219], v[196:199], v[84:87]
	v_mfma_f32_16x16x32_bf16 v[80:83], v[220:223], v[196:199], v[80:83]
	v_mfma_f32_16x16x32_bf16 v[60:63], v[208:211], v[200:203], v[60:63]
	v_mfma_f32_16x16x32_bf16 v[56:59], v[212:215], v[200:203], v[56:59]
	v_mfma_f32_16x16x32_bf16 v[52:55], v[216:219], v[200:203], v[52:55]
	v_mfma_f32_16x16x32_bf16 v[48:51], v[220:223], v[200:203], v[48:51]
	v_mfma_f32_16x16x32_bf16 v[28:31], v[208:211], v[204:207], v[28:31]
	v_mfma_f32_16x16x32_bf16 v[24:27], v[212:215], v[204:207], v[24:27]
	v_mfma_f32_16x16x32_bf16 v[20:23], v[216:219], v[204:207], v[20:23]
	v_mfma_f32_16x16x32_bf16 v[16:19], v[220:223], v[204:207], v[16:19]
	s_waitcnt lgkmcnt(0)
	s_waitcnt vmcnt(4)
	s_barrier
	v_mfma_f32_16x16x32_bf16 v[108:111], v[224:227], v[192:195], v[108:111]
	ds_read_b128 v[176:179], v254 offset:0
	s_add_u32 m0, s101, 0x8000
	v_mfma_f32_16x16x32_bf16 v[104:107], v[228:231], v[192:195], v[104:107]
	ds_read_b128 v[180:183], v254 offset:2048
	global_load_lds_dwordx4 v[138:139], off
	v_lshl_add_u64 v[138:139], v[138:139], 0, s[34:35]
	v_mfma_f32_16x16x32_bf16 v[100:103], v[232:235], v[192:195], v[100:103]
	ds_read_b128 v[184:187], v254 offset:4096
	s_add_u32 m0, s101, 0xa000
	v_mfma_f32_16x16x32_bf16 v[96:99], v[236:239], v[192:195], v[96:99]
	ds_read_b128 v[188:191], v254 offset:6144
	global_load_lds_dwordx4 v[140:141], off
	v_lshl_add_u64 v[140:141], v[140:141], 0, s[34:35]
	v_mfma_f32_16x16x32_bf16 v[76:79], v[224:227], v[196:199], v[76:79]
	ds_read_b128 v[208:211], v174 offset:0
	s_add_u32 m0, s101, 0xc000
	v_mfma_f32_16x16x32_bf16 v[72:75], v[228:231], v[196:199], v[72:75]
	ds_read_b128 v[212:215], v174 offset:2048
	global_load_lds_dwordx4 v[250:251], off
	v_lshl_add_u64 v[250:251], v[250:251], 0, s[34:35]
	v_mfma_f32_16x16x32_bf16 v[68:71], v[232:235], v[196:199], v[68:71]
	ds_read_b128 v[216:219], v174 offset:4096
	s_add_u32 m0, s101, 0xe000
	v_mfma_f32_16x16x32_bf16 v[64:67], v[236:239], v[196:199], v[64:67]
	ds_read_b128 v[220:223], v174 offset:6144
	global_load_lds_dwordx4 v[252:253], off
	v_lshl_add_u64 v[252:253], v[252:253], 0, s[34:35]
	v_mfma_f32_16x16x32_bf16 v[44:47], v[224:227], v[200:203], v[44:47]
	v_mfma_f32_16x16x32_bf16 v[40:43], v[228:231], v[200:203], v[40:43]
	v_mfma_f32_16x16x32_bf16 v[36:39], v[232:235], v[200:203], v[36:39]
	v_mfma_f32_16x16x32_bf16 v[32:35], v[236:239], v[200:203], v[32:35]
	v_mfma_f32_16x16x32_bf16 v[12:15], v[224:227], v[204:207], v[12:15]
	v_mfma_f32_16x16x32_bf16 v[8:11], v[228:231], v[204:207], v[8:11]
	v_mfma_f32_16x16x32_bf16 v[4:7], v[232:235], v[204:207], v[4:7]
	v_mfma_f32_16x16x32_bf16 v[0:3], v[236:239], v[204:207], v[0:3]
	s_waitcnt lgkmcnt(0)
	v_mfma_f32_16x16x32_bf16 v[124:127], v[208:211], v[176:179], v[124:127]
	ds_read_b128 v[224:227], v174 offset:8192
	v_mfma_f32_16x16x32_bf16 v[120:123], v[212:215], v[176:179], v[120:123]
	ds_read_b128 v[228:231], v174 offset:10240
	v_mfma_f32_16x16x32_bf16 v[116:119], v[216:219], v[176:179], v[116:119]
	ds_read_b128 v[232:235], v174 offset:12288
	v_mfma_f32_16x16x32_bf16 v[112:115], v[220:223], v[176:179], v[112:115]
	ds_read_b128 v[236:239], v174 offset:14336
	v_mfma_f32_16x16x32_bf16 v[92:95], v[208:211], v[180:183], v[92:95]
	v_mfma_f32_16x16x32_bf16 v[88:91], v[212:215], v[180:183], v[88:91]
	v_mfma_f32_16x16x32_bf16 v[84:87], v[216:219], v[180:183], v[84:87]
	v_mfma_f32_16x16x32_bf16 v[80:83], v[220:223], v[180:183], v[80:83]
	v_mfma_f32_16x16x32_bf16 v[60:63], v[208:211], v[184:187], v[60:63]
	v_mfma_f32_16x16x32_bf16 v[56:59], v[212:215], v[184:187], v[56:59]
	v_mfma_f32_16x16x32_bf16 v[52:55], v[216:219], v[184:187], v[52:55]
	v_mfma_f32_16x16x32_bf16 v[48:51], v[220:223], v[184:187], v[48:51]
	v_mfma_f32_16x16x32_bf16 v[28:31], v[208:211], v[188:191], v[28:31]
	v_mfma_f32_16x16x32_bf16 v[24:27], v[212:215], v[188:191], v[24:27]
	v_mfma_f32_16x16x32_bf16 v[20:23], v[216:219], v[188:191], v[20:23]
	v_mfma_f32_16x16x32_bf16 v[16:19], v[220:223], v[188:191], v[16:19]
	s_waitcnt lgkmcnt(0)
	v_mfma_f32_16x16x32_bf16 v[108:111], v[224:227], v[176:179], v[108:111]
	ds_read_b128 v[192:195], v255 offset:0
	v_mfma_f32_16x16x32_bf16 v[104:107], v[228:231], v[176:179], v[104:107]
	ds_read_b128 v[196:199], v255 offset:2048
	v_mfma_f32_16x16x32_bf16 v[100:103], v[232:235], v[176:179], v[100:103]
	ds_read_b128 v[200:203], v255 offset:4096
	v_mfma_f32_16x16x32_bf16 v[96:99], v[236:239], v[176:179], v[96:99]
	ds_read_b128 v[204:207], v255 offset:6144
	v_mfma_f32_16x16x32_bf16 v[76:79], v[224:227], v[180:183], v[76:79]
	ds_read_b128 v[208:211], v175 offset:0
	v_mfma_f32_16x16x32_bf16 v[72:75], v[228:231], v[180:183], v[72:75]
	ds_read_b128 v[212:215], v175 offset:2048
	v_mfma_f32_16x16x32_bf16 v[68:71], v[232:235], v[180:183], v[68:71]
	ds_read_b128 v[216:219], v175 offset:4096
	v_mfma_f32_16x16x32_bf16 v[64:67], v[236:239], v[180:183], v[64:67]
	ds_read_b128 v[220:223], v175 offset:6144
	v_mfma_f32_16x16x32_bf16 v[44:47], v[224:227], v[184:187], v[44:47]
	v_mfma_f32_16x16x32_bf16 v[40:43], v[228:231], v[184:187], v[40:43]
	v_mfma_f32_16x16x32_bf16 v[36:39], v[232:235], v[184:187], v[36:39]
	v_mfma_f32_16x16x32_bf16 v[32:35], v[236:239], v[184:187], v[32:35]
	v_mfma_f32_16x16x32_bf16 v[12:15], v[224:227], v[188:191], v[12:15]
	v_mfma_f32_16x16x32_bf16 v[8:11], v[228:231], v[188:191], v[8:11]
	v_mfma_f32_16x16x32_bf16 v[4:7], v[232:235], v[188:191], v[4:7]
	v_mfma_f32_16x16x32_bf16 v[0:3], v[236:239], v[188:191], v[0:3]
	s_waitcnt lgkmcnt(0)
	v_mfma_f32_16x16x32_bf16 v[124:127], v[208:211], v[192:195], v[124:127]
	ds_read_b128 v[224:227], v175 offset:8192
	v_mfma_f32_16x16x32_bf16 v[120:123], v[212:215], v[192:195], v[120:123]
	ds_read_b128 v[228:231], v175 offset:10240
	v_mfma_f32_16x16x32_bf16 v[116:119], v[216:219], v[192:195], v[116:119]
	ds_read_b128 v[232:235], v175 offset:12288
	v_mfma_f32_16x16x32_bf16 v[112:115], v[220:223], v[192:195], v[112:115]
	ds_read_b128 v[236:239], v175 offset:14336
	v_mfma_f32_16x16x32_bf16 v[92:95], v[208:211], v[196:199], v[92:95]
	v_mfma_f32_16x16x32_bf16 v[88:91], v[212:215], v[196:199], v[88:91]
	v_mfma_f32_16x16x32_bf16 v[84:87], v[216:219], v[196:199], v[84:87]
	v_mfma_f32_16x16x32_bf16 v[80:83], v[220:223], v[196:199], v[80:83]
	v_mfma_f32_16x16x32_bf16 v[60:63], v[208:211], v[200:203], v[60:63]
	v_mfma_f32_16x16x32_bf16 v[56:59], v[212:215], v[200:203], v[56:59]
	v_mfma_f32_16x16x32_bf16 v[52:55], v[216:219], v[200:203], v[52:55]
	v_mfma_f32_16x16x32_bf16 v[48:51], v[220:223], v[200:203], v[48:51]
	v_mfma_f32_16x16x32_bf16 v[28:31], v[208:211], v[204:207], v[28:31]
	v_mfma_f32_16x16x32_bf16 v[24:27], v[212:215], v[204:207], v[24:27]
	v_mfma_f32_16x16x32_bf16 v[20:23], v[216:219], v[204:207], v[20:23]
	v_mfma_f32_16x16x32_bf16 v[16:19], v[220:223], v[204:207], v[16:19]
	s_waitcnt lgkmcnt(0)
	s_waitcnt vmcnt(0)
	s_barrier
	v_mfma_f32_16x16x32_bf16 v[108:111], v[224:227], v[192:195], v[108:111]
	ds_read_b128 v[176:179], v172 offset:0
	v_mfma_f32_16x16x32_bf16 v[104:107], v[228:231], v[192:195], v[104:107]
	ds_read_b128 v[180:183], v172 offset:2048
	v_mfma_f32_16x16x32_bf16 v[100:103], v[232:235], v[192:195], v[100:103]
	ds_read_b128 v[184:187], v172 offset:4096
	v_mfma_f32_16x16x32_bf16 v[96:99], v[236:239], v[192:195], v[96:99]
	ds_read_b128 v[188:191], v172 offset:6144
	v_mfma_f32_16x16x32_bf16 v[76:79], v[224:227], v[196:199], v[76:79]
	ds_read_b128 v[208:211], v174 offset:32768
	v_mfma_f32_16x16x32_bf16 v[72:75], v[228:231], v[196:199], v[72:75]
	ds_read_b128 v[212:215], v174 offset:34816
	v_mfma_f32_16x16x32_bf16 v[68:71], v[232:235], v[196:199], v[68:71]
	ds_read_b128 v[216:219], v174 offset:36864
	v_mfma_f32_16x16x32_bf16 v[64:67], v[236:239], v[196:199], v[64:67]
	ds_read_b128 v[220:223], v174 offset:38912
	v_mfma_f32_16x16x32_bf16 v[44:47], v[224:227], v[200:203], v[44:47]
	v_mfma_f32_16x16x32_bf16 v[40:43], v[228:231], v[200:203], v[40:43]
	v_mfma_f32_16x16x32_bf16 v[36:39], v[232:235], v[200:203], v[36:39]
	v_mfma_f32_16x16x32_bf16 v[32:35], v[236:239], v[200:203], v[32:35]
	v_mfma_f32_16x16x32_bf16 v[12:15], v[224:227], v[204:207], v[12:15]
	v_mfma_f32_16x16x32_bf16 v[8:11], v[228:231], v[204:207], v[8:11]
	v_mfma_f32_16x16x32_bf16 v[4:7], v[232:235], v[204:207], v[4:7]
	v_mfma_f32_16x16x32_bf16 v[0:3], v[236:239], v[204:207], v[0:3]
	s_waitcnt lgkmcnt(0)
	v_mfma_f32_16x16x32_bf16 v[124:127], v[208:211], v[176:179], v[124:127]
	ds_read_b128 v[224:227], v174 offset:40960
	v_mfma_f32_16x16x32_bf16 v[120:123], v[212:215], v[176:179], v[120:123]
	ds_read_b128 v[228:231], v174 offset:43008
	v_mfma_f32_16x16x32_bf16 v[116:119], v[216:219], v[176:179], v[116:119]
	ds_read_b128 v[232:235], v174 offset:45056
	v_mfma_f32_16x16x32_bf16 v[112:115], v[220:223], v[176:179], v[112:115]
	ds_read_b128 v[236:239], v174 offset:47104
	v_mfma_f32_16x16x32_bf16 v[92:95], v[208:211], v[180:183], v[92:95]
	v_mfma_f32_16x16x32_bf16 v[88:91], v[212:215], v[180:183], v[88:91]
	v_mfma_f32_16x16x32_bf16 v[84:87], v[216:219], v[180:183], v[84:87]
	v_mfma_f32_16x16x32_bf16 v[80:83], v[220:223], v[180:183], v[80:83]
	v_mfma_f32_16x16x32_bf16 v[60:63], v[208:211], v[184:187], v[60:63]
	v_mfma_f32_16x16x32_bf16 v[56:59], v[212:215], v[184:187], v[56:59]
	v_mfma_f32_16x16x32_bf16 v[52:55], v[216:219], v[184:187], v[52:55]
	v_mfma_f32_16x16x32_bf16 v[48:51], v[220:223], v[184:187], v[48:51]
	v_mfma_f32_16x16x32_bf16 v[28:31], v[208:211], v[188:191], v[28:31]
	v_mfma_f32_16x16x32_bf16 v[24:27], v[212:215], v[188:191], v[24:27]
	v_mfma_f32_16x16x32_bf16 v[20:23], v[216:219], v[188:191], v[20:23]
	v_mfma_f32_16x16x32_bf16 v[16:19], v[220:223], v[188:191], v[16:19]
	s_waitcnt lgkmcnt(0)
	v_mfma_f32_16x16x32_bf16 v[108:111], v[224:227], v[176:179], v[108:111]
	ds_read_b128 v[192:195], v173 offset:0
	v_mfma_f32_16x16x32_bf16 v[104:107], v[228:231], v[176:179], v[104:107]
	ds_read_b128 v[196:199], v173 offset:2048
	v_mfma_f32_16x16x32_bf16 v[100:103], v[232:235], v[176:179], v[100:103]
	ds_read_b128 v[200:203], v173 offset:4096
	v_mfma_f32_16x16x32_bf16 v[96:99], v[236:239], v[176:179], v[96:99]
	ds_read_b128 v[204:207], v173 offset:6144
	v_mfma_f32_16x16x32_bf16 v[76:79], v[224:227], v[180:183], v[76:79]
	ds_read_b128 v[208:211], v175 offset:32768
	v_mfma_f32_16x16x32_bf16 v[72:75], v[228:231], v[180:183], v[72:75]
	ds_read_b128 v[212:215], v175 offset:34816
	v_mfma_f32_16x16x32_bf16 v[68:71], v[232:235], v[180:183], v[68:71]
	ds_read_b128 v[216:219], v175 offset:36864
	v_mfma_f32_16x16x32_bf16 v[64:67], v[236:239], v[180:183], v[64:67]
	ds_read_b128 v[220:223], v175 offset:38912
	v_mfma_f32_16x16x32_bf16 v[44:47], v[224:227], v[184:187], v[44:47]
	v_mfma_f32_16x16x32_bf16 v[40:43], v[228:231], v[184:187], v[40:43]
	v_mfma_f32_16x16x32_bf16 v[36:39], v[232:235], v[184:187], v[36:39]
	v_mfma_f32_16x16x32_bf16 v[32:35], v[236:239], v[184:187], v[32:35]
	v_mfma_f32_16x16x32_bf16 v[12:15], v[224:227], v[188:191], v[12:15]
	v_mfma_f32_16x16x32_bf16 v[8:11], v[228:231], v[188:191], v[8:11]
	v_mfma_f32_16x16x32_bf16 v[4:7], v[232:235], v[188:191], v[4:7]
	v_mfma_f32_16x16x32_bf16 v[0:3], v[236:239], v[188:191], v[0:3]
	s_waitcnt lgkmcnt(0)
	v_mfma_f32_16x16x32_bf16 v[124:127], v[208:211], v[192:195], v[124:127]
	ds_read_b128 v[224:227], v175 offset:40960
	v_mfma_f32_16x16x32_bf16 v[120:123], v[212:215], v[192:195], v[120:123]
	ds_read_b128 v[228:231], v175 offset:43008
	v_mfma_f32_16x16x32_bf16 v[116:119], v[216:219], v[192:195], v[116:119]
	ds_read_b128 v[232:235], v175 offset:45056
	v_mfma_f32_16x16x32_bf16 v[112:115], v[220:223], v[192:195], v[112:115]
	ds_read_b128 v[236:239], v175 offset:47104
	v_mfma_f32_16x16x32_bf16 v[92:95], v[208:211], v[196:199], v[92:95]
	v_mfma_f32_16x16x32_bf16 v[88:91], v[212:215], v[196:199], v[88:91]
	v_mfma_f32_16x16x32_bf16 v[84:87], v[216:219], v[196:199], v[84:87]
	v_mfma_f32_16x16x32_bf16 v[80:83], v[220:223], v[196:199], v[80:83]
	v_mfma_f32_16x16x32_bf16 v[60:63], v[208:211], v[200:203], v[60:63]
	v_mfma_f32_16x16x32_bf16 v[56:59], v[212:215], v[200:203], v[56:59]
	v_mfma_f32_16x16x32_bf16 v[52:55], v[216:219], v[200:203], v[52:55]
	v_mfma_f32_16x16x32_bf16 v[48:51], v[220:223], v[200:203], v[48:51]
	v_mfma_f32_16x16x32_bf16 v[28:31], v[208:211], v[204:207], v[28:31]
	v_mfma_f32_16x16x32_bf16 v[24:27], v[212:215], v[204:207], v[24:27]
	v_mfma_f32_16x16x32_bf16 v[20:23], v[216:219], v[204:207], v[20:23]
	v_mfma_f32_16x16x32_bf16 v[16:19], v[220:223], v[204:207], v[16:19]
	s_waitcnt lgkmcnt(0)
	s_barrier
	v_mfma_f32_16x16x32_bf16 v[108:111], v[224:227], v[192:195], v[108:111]
	v_mfma_f32_16x16x32_bf16 v[104:107], v[228:231], v[192:195], v[104:107]
	v_mfma_f32_16x16x32_bf16 v[100:103], v[232:235], v[192:195], v[100:103]
	v_mfma_f32_16x16x32_bf16 v[96:99], v[236:239], v[192:195], v[96:99]
	v_mfma_f32_16x16x32_bf16 v[76:79], v[224:227], v[196:199], v[76:79]
	v_mfma_f32_16x16x32_bf16 v[72:75], v[228:231], v[196:199], v[72:75]
	v_mfma_f32_16x16x32_bf16 v[68:71], v[232:235], v[196:199], v[68:71]
	v_mfma_f32_16x16x32_bf16 v[64:67], v[236:239], v[196:199], v[64:67]
	v_mfma_f32_16x16x32_bf16 v[44:47], v[224:227], v[200:203], v[44:47]
	v_mfma_f32_16x16x32_bf16 v[40:43], v[228:231], v[200:203], v[40:43]
	v_mfma_f32_16x16x32_bf16 v[36:39], v[232:235], v[200:203], v[36:39]
	v_mfma_f32_16x16x32_bf16 v[32:35], v[236:239], v[200:203], v[32:35]
	v_mfma_f32_16x16x32_bf16 v[12:15], v[224:227], v[204:207], v[12:15]
	v_mfma_f32_16x16x32_bf16 v[8:11], v[228:231], v[204:207], v[8:11]
	v_mfma_f32_16x16x32_bf16 v[4:7], v[232:235], v[204:207], v[4:7]
	v_mfma_f32_16x16x32_bf16 v[0:3], v[236:239], v[204:207], v[0:3]
	s_nop 7
	s_nop 3
	s_branch .LBB0_1093

.Lgemm_p9_loop:
	v_mfma_f32_16x16x32_bf16 v[108:111], v[224:227], v[192:195], v[108:111]
	ds_read_b128 v[176:179], v172 offset:32768
	s_mov_b32 m0, s101
	v_mfma_f32_16x16x32_bf16 v[104:107], v[228:231], v[192:195], v[104:107]
	ds_read_b128 v[180:183], v172 offset:34816
	global_load_lds_dwordx4 v[138:139], off
	v_lshl_add_u64 v[138:139], v[138:139], 0, s[34:35]
	v_mfma_f32_16x16x32_bf16 v[100:103], v[232:235], v[192:195], v[100:103]
	ds_read_b128 v[184:187], v172 offset:36864
	s_add_u32 m0, s101, 0x2000
	v_mfma_f32_16x16x32_bf16 v[96:99], v[236:239], v[192:195], v[96:99]
	ds_read_b128 v[188:191], v172 offset:38912
	global_load_lds_dwordx4 v[140:141], off
	v_lshl_add_u64 v[140:141], v[140:141], 0, s[34:35]
	v_mfma_f32_16x16x32_bf16 v[76:79], v[224:227], v[196:199], v[76:79]
	ds_read_b128 v[208:211], v174 offset:32768
	s_add_u32 m0, s101, 0x4000
	v_mfma_f32_16x16x32_bf16 v[72:75], v[228:231], v[196:199], v[72:75]
	ds_read_b128 v[212:215], v174 offset:34816
	global_load_lds_dwordx4 v[250:251], off
	v_lshl_add_u64 v[250:251], v[250:251], 0, s[34:35]
	v_mfma_f32_16x16x32_bf16 v[68:71], v[232:235], v[196:199], v[68:71]
	ds_read_b128 v[216:219], v174 offset:36864
	s_add_u32 m0, s101, 0x6000
	v_mfma_f32_16x16x32_bf16 v[64:67], v[236:239], v[196:199], v[64:67]
	ds_read_b128 v[220:223], v174 offset:38912
	global_load_lds_dwordx4 v[252:253], off
	v_lshl_add_u64 v[252:253], v[252:253], 0, s[34:35]
	v_mfma_f32_16x16x32_bf16 v[44:47], v[224:227], v[200:203], v[44:47]
	v_mfma_f32_16x16x32_bf16 v[40:43], v[228:231], v[200:203], v[40:43]
	v_mfma_f32_16x16x32_bf16 v[36:39], v[232:235], v[200:203], v[36:39]
	v_mfma_f32_16x16x32_bf16 v[32:35], v[236:239], v[200:203], v[32:35]
	v_mfma_f32_16x16x32_bf16 v[12:15], v[224:227], v[204:207], v[12:15]
	v_mfma_f32_16x16x32_bf16 v[8:11], v[228:231], v[204:207], v[8:11]
	v_mfma_f32_16x16x32_bf16 v[4:7], v[232:235], v[204:207], v[4:7]
	v_mfma_f32_16x16x32_bf16 v[0:3], v[236:239], v[204:207], v[0:3]
	s_waitcnt lgkmcnt(0)
	v_mfma_f32_16x16x32_bf16 v[124:127], v[208:211], v[176:179], v[124:127]
	ds_read_b128 v[224:227], v174 offset:40960
	v_mfma_f32_16x16x32_bf16 v[120:123], v[212:215], v[176:179], v[120:123]
	ds_read_b128 v[228:231], v174 offset:43008
	v_mfma_f32_16x16x32_bf16 v[116:119], v[216:219], v[176:179], v[116:119]
	ds_read_b128 v[232:235], v174 offset:45056
	v_mfma_f32_16x16x32_bf16 v[112:115], v[220:223], v[176:179], v[112:115]
	ds_read_b128 v[236:239], v174 offset:47104
	v_mfma_f32_16x16x32_bf16 v[92:95], v[208:211], v[180:183], v[92:95]
	s_mov_b32 m0, s100
	v_mfma_f32_16x16x32_bf16 v[88:91], v[212:215], v[180:183], v[88:91]
	global_load_lds_dwordx4 v[240:241], off
	v_lshl_add_u64 v[240:241], v[240:241], 0, s[34:35]
	v_mfma_f32_16x16x32_bf16 v[84:87], v[216:219], v[180:183], v[84:87]
	s_add_u32 m0, s100, 0x2000
	v_mfma_f32_16x16x32_bf16 v[80:83], v[220:223], v[180:183], v[80:83]
	global_load_lds_dwordx4 v[242:243], off
	v_lshl_add_u64 v[242:243], v[242:243], 0, s[34:35]
	v_mfma_f32_16x16x32_bf16 v[60:63], v[208:211], v[184:187], v[60:63]
	s_add_u32 m0, s100, 0x4000
	v_mfma_f32_16x16x32_bf16 v[56:59], v[212:215], v[184:187], v[56:59]
	global_load_lds_dwordx4 v[244:245], off
	v_lshl_add_u64 v[244:245], v[244:245], 0, s[34:35]
	v_mfma_f32_16x16x32_bf16 v[52:55], v[216:219], v[184:187], v[52:55]
	s_add_u32 m0, s100, 0x6000
	v_mfma_f32_16x16x32_bf16 v[48:51], v[220:223], v[184:187], v[48:51]
	global_load_lds_dwordx4 v[246:247], off
	v_lshl_add_u64 v[246:247], v[246:247], 0, s[34:35]
	v_mfma_f32_16x16x32_bf16 v[28:31], v[208:211], v[188:191], v[28:31]
	v_mfma_f32_16x16x32_bf16 v[24:27], v[212:215], v[188:191], v[24:27]
	v_mfma_f32_16x16x32_bf16 v[20:23], v[216:219], v[188:191], v[20:23]
	v_mfma_f32_16x16x32_bf16 v[16:19], v[220:223], v[188:191], v[16:19]
	s_waitcnt lgkmcnt(0)
	v_mfma_f32_16x16x32_bf16 v[108:111], v[224:227], v[176:179], v[108:111]
	ds_read_b128 v[192:195], v173 offset:32768
	v_mfma_f32_16x16x32_bf16 v[104:107], v[228:231], v[176:179], v[104:107]
	ds_read_b128 v[196:199], v173 offset:34816
	v_mfma_f32_16x16x32_bf16 v[100:103], v[232:235], v[176:179], v[100:103]
	ds_read_b128 v[200:203], v173 offset:36864
	v_mfma_f32_16x16x32_bf16 v[96:99], v[236:239], v[176:179], v[96:99]
	ds_read_b128 v[204:207], v173 offset:38912
	v_mfma_f32_16x16x32_bf16 v[76:79], v[224:227], v[180:183], v[76:79]
	ds_read_b128 v[208:211], v175 offset:32768
	v_mfma_f32_16x16x32_bf16 v[72:75], v[228:231], v[180:183], v[72:75]
	ds_read_b128 v[212:215], v175 offset:34816
	v_mfma_f32_16x16x32_bf16 v[68:71], v[232:235], v[180:183], v[68:71]
	ds_read_b128 v[216:219], v175 offset:36864
	v_mfma_f32_16x16x32_bf16 v[64:67], v[236:239], v[180:183], v[64:67]
	ds_read_b128 v[220:223], v175 offset:38912
	v_mfma_f32_16x16x32_bf16 v[44:47], v[224:227], v[184:187], v[44:47]
	v_mfma_f32_16x16x32_bf16 v[40:43], v[228:231], v[184:187], v[40:43]
	v_mfma_f32_16x16x32_bf16 v[36:39], v[232:235], v[184:187], v[36:39]
	v_mfma_f32_16x16x32_bf16 v[32:35], v[236:239], v[184:187], v[32:35]
	v_mfma_f32_16x16x32_bf16 v[12:15], v[224:227], v[188:191], v[12:15]
	v_mfma_f32_16x16x32_bf16 v[8:11], v[228:231], v[188:191], v[8:11]
	v_mfma_f32_16x16x32_bf16 v[4:7], v[232:235], v[188:191], v[4:7]
	v_mfma_f32_16x16x32_bf16 v[0:3], v[236:239], v[188:191], v[0:3]
	s_waitcnt lgkmcnt(0)
	v_mfma_f32_16x16x32_bf16 v[124:127], v[208:211], v[192:195], v[124:127]
	ds_read_b128 v[224:227], v175 offset:40960
	v_mfma_f32_16x16x32_bf16 v[120:123], v[212:215], v[192:195], v[120:123]
	ds_read_b128 v[228:231], v175 offset:43008
	v_mfma_f32_16x16x32_bf16 v[116:119], v[216:219], v[192:195], v[116:119]
	ds_read_b128 v[232:235], v175 offset:45056
	v_mfma_f32_16x16x32_bf16 v[112:115], v[220:223], v[192:195], v[112:115]
	ds_read_b128 v[236:239], v175 offset:47104
	v_mfma_f32_16x16x32_bf16 v[92:95], v[208:211], v[196:199], v[92:95]
	v_mfma_f32_16x16x32_bf16 v[88:91], v[212:215], v[196:199], v[88:91]
	v_mfma_f32_16x16x32_bf16 v[84:87], v[216:219], v[196:199], v[84:87]
	v_mfma_f32_16x16x32_bf16 v[80:83], v[220:223], v[196:199], v[80:83]
	v_mfma_f32_16x16x32_bf16 v[60:63], v[208:211], v[200:203], v[60:63]
	v_mfma_f32_16x16x32_bf16 v[56:59], v[212:215], v[200:203], v[56:59]
	v_mfma_f32_16x16x32_bf16 v[52:55], v[216:219], v[200:203], v[52:55]
	v_mfma_f32_16x16x32_bf16 v[48:51], v[220:223], v[200:203], v[48:51]
	v_mfma_f32_16x16x32_bf16 v[28:31], v[208:211], v[204:207], v[28:31]
	v_mfma_f32_16x16x32_bf16 v[24:27], v[212:215], v[204:207], v[24:27]
	v_mfma_f32_16x16x32_bf16 v[20:23], v[216:219], v[204:207], v[20:23]
	v_mfma_f32_16x16x32_bf16 v[16:19], v[220:223], v[204:207], v[16:19]
	s_waitcnt lgkmcnt(0)
	s_waitcnt vmcnt(4)
	s_barrier
	v_mfma_f32_16x16x32_bf16 v[108:111], v[224:227], v[192:195], v[108:111]
	ds_read_b128 v[176:179], v254 offset:0
	s_add_u32 m0, s101, 0x8000
	v_mfma_f32_16x16x32_bf16 v[104:107], v[228:231], v[192:195], v[104:107]
	ds_read_b128 v[180:183], v254 offset:2048
	global_load_lds_dwordx4 v[138:139], off
	v_lshl_add_u64 v[138:139], v[138:139], 0, s[34:35]
	v_mfma_f32_16x16x32_bf16 v[100:103], v[232:235], v[192:195], v[100:103]
	ds_read_b128 v[184:187], v254 offset:4096
	s_add_u32 m0, s101, 0xa000
	v_mfma_f32_16x16x32_bf16 v[96:99], v[236:239], v[192:195], v[96:99]
	ds_read_b128 v[188:191], v254 offset:6144
	global_load_lds_dwordx4 v[140:141], off
	v_lshl_add_u64 v[140:141], v[140:141], 0, s[34:35]
	v_mfma_f32_16x16x32_bf16 v[76:79], v[224:227], v[196:199], v[76:79]
	ds_read_b128 v[208:211], v174 offset:0
	s_add_u32 m0, s101, 0xc000
	v_mfma_f32_16x16x32_bf16 v[72:75], v[228:231], v[196:199], v[72:75]
	ds_read_b128 v[212:215], v174 offset:2048
	global_load_lds_dwordx4 v[250:251], off
	v_lshl_add_u64 v[250:251], v[250:251], 0, s[34:35]
	v_mfma_f32_16x16x32_bf16 v[68:71], v[232:235], v[196:199], v[68:71]
	ds_read_b128 v[216:219], v174 offset:4096
	s_add_u32 m0, s101, 0xe000
	v_mfma_f32_16x16x32_bf16 v[64:67], v[236:239], v[196:199], v[64:67]
	ds_read_b128 v[220:223], v174 offset:6144
	global_load_lds_dwordx4 v[252:253], off
	v_lshl_add_u64 v[252:253], v[252:253], 0, s[34:35]
	v_mfma_f32_16x16x32_bf16 v[44:47], v[224:227], v[200:203], v[44:47]
	v_mfma_f32_16x16x32_bf16 v[40:43], v[228:231], v[200:203], v[40:43]
	v_mfma_f32_16x16x32_bf16 v[36:39], v[232:235], v[200:203], v[36:39]
	v_mfma_f32_16x16x32_bf16 v[32:35], v[236:239], v[200:203], v[32:35]
	v_mfma_f32_16x16x32_bf16 v[12:15], v[224:227], v[204:207], v[12:15]
	v_mfma_f32_16x16x32_bf16 v[8:11], v[228:231], v[204:207], v[8:11]
	v_mfma_f32_16x16x32_bf16 v[4:7], v[232:235], v[204:207], v[4:7]
	v_mfma_f32_16x16x32_bf16 v[0:3], v[236:239], v[204:207], v[0:3]
	s_waitcnt lgkmcnt(0)
	v_mfma_f32_16x16x32_bf16 v[124:127], v[208:211], v[176:179], v[124:127]
	ds_read_b128 v[224:227], v174 offset:8192
	v_mfma_f32_16x16x32_bf16 v[120:123], v[212:215], v[176:179], v[120:123]
	ds_read_b128 v[228:231], v174 offset:10240
	v_mfma_f32_16x16x32_bf16 v[116:119], v[216:219], v[176:179], v[116:119]
	ds_read_b128 v[232:235], v174 offset:12288
	v_mfma_f32_16x16x32_bf16 v[112:115], v[220:223], v[176:179], v[112:115]
	ds_read_b128 v[236:239], v174 offset:14336
	v_mfma_f32_16x16x32_bf16 v[92:95], v[208:211], v[180:183], v[92:95]
	s_add_u32 m0, s100, 0x8000
	v_mfma_f32_16x16x32_bf16 v[88:91], v[212:215], v[180:183], v[88:91]
	global_load_lds_dwordx4 v[240:241], off
	v_lshl_add_u64 v[240:241], v[240:241], 0, s[34:35]
	v_mfma_f32_16x16x32_bf16 v[84:87], v[216:219], v[180:183], v[84:87]
	s_add_u32 m0, s100, 0xa000
	v_mfma_f32_16x16x32_bf16 v[80:83], v[220:223], v[180:183], v[80:83]
	global_load_lds_dwordx4 v[242:243], off
	v_lshl_add_u64 v[242:243], v[242:243], 0, s[34:35]
	v_mfma_f32_16x16x32_bf16 v[60:63], v[208:211], v[184:187], v[60:63]
	s_add_u32 m0, s100, 0xc000
	v_mfma_f32_16x16x32_bf16 v[56:59], v[212:215], v[184:187], v[56:59]
	global_load_lds_dwordx4 v[244:245], off
	v_lshl_add_u64 v[244:245], v[244:245], 0, s[34:35]
	v_mfma_f32_16x16x32_bf16 v[52:55], v[216:219], v[184:187], v[52:55]
	s_add_u32 m0, s100, 0xe000
	v_mfma_f32_16x16x32_bf16 v[48:51], v[220:223], v[184:187], v[48:51]
	global_load_lds_dwordx4 v[246:247], off
	v_lshl_add_u64 v[246:247], v[246:247], 0, s[34:35]
	v_mfma_f32_16x16x32_bf16 v[28:31], v[208:211], v[188:191], v[28:31]
	v_mfma_f32_16x16x32_bf16 v[24:27], v[212:215], v[188:191], v[24:27]
	v_mfma_f32_16x16x32_bf16 v[20:23], v[216:219], v[188:191], v[20:23]
	v_mfma_f32_16x16x32_bf16 v[16:19], v[220:223], v[188:191], v[16:19]
	s_waitcnt lgkmcnt(0)
	v_mfma_f32_16x16x32_bf16 v[108:111], v[224:227], v[176:179], v[108:111]
	ds_read_b128 v[192:195], v255 offset:0
	v_mfma_f32_16x16x32_bf16 v[104:107], v[228:231], v[176:179], v[104:107]
	ds_read_b128 v[196:199], v255 offset:2048
	v_mfma_f32_16x16x32_bf16 v[100:103], v[232:235], v[176:179], v[100:103]
	ds_read_b128 v[200:203], v255 offset:4096
	v_mfma_f32_16x16x32_bf16 v[96:99], v[236:239], v[176:179], v[96:99]
	ds_read_b128 v[204:207], v255 offset:6144
	v_mfma_f32_16x16x32_bf16 v[76:79], v[224:227], v[180:183], v[76:79]
	ds_read_b128 v[208:211], v175 offset:0
	v_mfma_f32_16x16x32_bf16 v[72:75], v[228:231], v[180:183], v[72:75]
	ds_read_b128 v[212:215], v175 offset:2048
	v_mfma_f32_16x16x32_bf16 v[68:71], v[232:235], v[180:183], v[68:71]
	ds_read_b128 v[216:219], v175 offset:4096
	v_mfma_f32_16x16x32_bf16 v[64:67], v[236:239], v[180:183], v[64:67]
	ds_read_b128 v[220:223], v175 offset:6144
	v_mfma_f32_16x16x32_bf16 v[44:47], v[224:227], v[184:187], v[44:47]
	v_mfma_f32_16x16x32_bf16 v[40:43], v[228:231], v[184:187], v[40:43]
	v_mfma_f32_16x16x32_bf16 v[36:39], v[232:235], v[184:187], v[36:39]
	v_mfma_f32_16x16x32_bf16 v[32:35], v[236:239], v[184:187], v[32:35]
	v_mfma_f32_16x16x32_bf16 v[12:15], v[224:227], v[188:191], v[12:15]
	v_mfma_f32_16x16x32_bf16 v[8:11], v[228:231], v[188:191], v[8:11]
	v_mfma_f32_16x16x32_bf16 v[4:7], v[232:235], v[188:191], v[4:7]
	v_mfma_f32_16x16x32_bf16 v[0:3], v[236:239], v[188:191], v[0:3]
	s_waitcnt lgkmcnt(0)
	v_mfma_f32_16x16x32_bf16 v[124:127], v[208:211], v[192:195], v[124:127]
	ds_read_b128 v[224:227], v175 offset:8192
	v_mfma_f32_16x16x32_bf16 v[120:123], v[212:215], v[192:195], v[120:123]
	ds_read_b128 v[228:231], v175 offset:10240
	v_mfma_f32_16x16x32_bf16 v[116:119], v[216:219], v[192:195], v[116:119]
	ds_read_b128 v[232:235], v175 offset:12288
	v_mfma_f32_16x16x32_bf16 v[112:115], v[220:223], v[192:195], v[112:115]
	ds_read_b128 v[236:239], v175 offset:14336
	v_mfma_f32_16x16x32_bf16 v[92:95], v[208:211], v[196:199], v[92:95]
	v_mfma_f32_16x16x32_bf16 v[88:91], v[212:215], v[196:199], v[88:91]
	v_mfma_f32_16x16x32_bf16 v[84:87], v[216:219], v[196:199], v[84:87]
	v_mfma_f32_16x16x32_bf16 v[80:83], v[220:223], v[196:199], v[80:83]
	v_mfma_f32_16x16x32_bf16 v[60:63], v[208:211], v[200:203], v[60:63]
	v_mfma_f32_16x16x32_bf16 v[56:59], v[212:215], v[200:203], v[56:59]
	v_mfma_f32_16x16x32_bf16 v[52:55], v[216:219], v[200:203], v[52:55]
	v_mfma_f32_16x16x32_bf16 v[48:51], v[220:223], v[200:203], v[48:51]
	v_mfma_f32_16x16x32_bf16 v[28:31], v[208:211], v[204:207], v[28:31]
	v_mfma_f32_16x16x32_bf16 v[24:27], v[212:215], v[204:207], v[24:27]
	v_mfma_f32_16x16x32_bf16 v[20:23], v[216:219], v[204:207], v[20:23]
	v_mfma_f32_16x16x32_bf16 v[16:19], v[220:223], v[204:207], v[16:19]
	s_waitcnt lgkmcnt(0)
	s_waitcnt vmcnt(4)
	s_barrier
	v_mfma_f32_16x16x32_bf16 v[108:111], v[224:227], v[192:195], v[108:111]
	ds_read_b128 v[176:179], v172 offset:0
	s_mov_b32 m0, s101
	v_mfma_f32_16x16x32_bf16 v[104:107], v[228:231], v[192:195], v[104:107]
	ds_read_b128 v[180:183], v172 offset:2048
	global_load_lds_dwordx4 v[138:139], off
	v_lshl_add_u64 v[138:139], v[138:139], 0, s[34:35]
	v_mfma_f32_16x16x32_bf16 v[100:103], v[232:235], v[192:195], v[100:103]
	ds_read_b128 v[184:187], v172 offset:4096
	s_add_u32 m0, s101, 0x2000
	v_mfma_f32_16x16x32_bf16 v[96:99], v[236:239], v[192:195], v[96:99]
	ds_read_b128 v[188:191], v172 offset:6144
	global_load_lds_dwordx4 v[140:141], off
	v_lshl_add_u64 v[140:141], v[140:141], 0, s[34:35]
	v_mfma_f32_16x16x32_bf16 v[76:79], v[224:227], v[196:199], v[76:79]
	ds_read_b128 v[208:211], v174 offset:32768
	s_add_u32 m0, s101, 0x4000
	v_mfma_f32_16x16x32_bf16 v[72:75], v[228:231], v[196:199], v[72:75]
	ds_read_b128 v[212:215], v174 offset:34816
	global_load_lds_dwordx4 v[250:251], off
	v_lshl_add_u64 v[250:251], v[250:251], 0, s[34:35]
	v_mfma_f32_16x16x32_bf16 v[68:71], v[232:235], v[196:199], v[68:71]
	ds_read_b128 v[216:219], v174 offset:36864
	s_add_u32 m0, s101, 0x6000
	v_mfma_f32_16x16x32_bf16 v[64:67], v[236:239], v[196:199], v[64:67]
	ds_read_b128 v[220:223], v174 offset:38912
	global_load_lds_dwordx4 v[252:253], off
	v_lshl_add_u64 v[252:253], v[252:253], 0, s[34:35]
	v_mfma_f32_16x16x32_bf16 v[44:47], v[224:227], v[200:203], v[44:47]
	v_mfma_f32_16x16x32_bf16 v[40:43], v[228:231], v[200:203], v[40:43]
	v_mfma_f32_16x16x32_bf16 v[36:39], v[232:235], v[200:203], v[36:39]
	v_mfma_f32_16x16x32_bf16 v[32:35], v[236:239], v[200:203], v[32:35]
	v_mfma_f32_16x16x32_bf16 v[12:15], v[224:227], v[204:207], v[12:15]
	v_mfma_f32_16x16x32_bf16 v[8:11], v[228:231], v[204:207], v[8:11]
	v_mfma_f32_16x16x32_bf16 v[4:7], v[232:235], v[204:207], v[4:7]
	v_mfma_f32_16x16x32_bf16 v[0:3], v[236:239], v[204:207], v[0:3]
	s_waitcnt lgkmcnt(0)
	v_mfma_f32_16x16x32_bf16 v[124:127], v[208:211], v[176:179], v[124:127]
	ds_read_b128 v[224:227], v174 offset:40960
	v_mfma_f32_16x16x32_bf16 v[120:123], v[212:215], v[176:179], v[120:123]
	ds_read_b128 v[228:231], v174 offset:43008
	v_mfma_f32_16x16x32_bf16 v[116:119], v[216:219], v[176:179], v[116:119]
	ds_read_b128 v[232:235], v174 offset:45056
	v_mfma_f32_16x16x32_bf16 v[112:115], v[220:223], v[176:179], v[112:115]
	ds_read_b128 v[236:239], v174 offset:47104
	v_mfma_f32_16x16x32_bf16 v[92:95], v[208:211], v[180:183], v[92:95]
	s_add_u32 m0, s100, 0x20000
	v_mfma_f32_16x16x32_bf16 v[88:91], v[212:215], v[180:183], v[88:91]
	global_load_lds_dwordx4 v[240:241], off
	v_lshl_add_u64 v[240:241], v[240:241], 0, s[34:35]
	v_mfma_f32_16x16x32_bf16 v[84:87], v[216:219], v[180:183], v[84:87]
	s_add_u32 m0, s100, 0x22000
	v_mfma_f32_16x16x32_bf16 v[80:83], v[220:223], v[180:183], v[80:83]
	global_load_lds_dwordx4 v[242:243], off
	v_lshl_add_u64 v[242:243], v[242:243], 0, s[34:35]
	v_mfma_f32_16x16x32_bf16 v[60:63], v[208:211], v[184:187], v[60:63]
	s_add_u32 m0, s100, 0x24000
	v_mfma_f32_16x16x32_bf16 v[56:59], v[212:215], v[184:187], v[56:59]
	global_load_lds_dwordx4 v[244:245], off
	v_lshl_add_u64 v[244:245], v[244:245], 0, s[34:35]
	v_mfma_f32_16x16x32_bf16 v[52:55], v[216:219], v[184:187], v[52:55]
	s_add_u32 m0, s100, 0x26000
	v_mfma_f32_16x16x32_bf16 v[48:51], v[220:223], v[184:187], v[48:51]
	global_load_lds_dwordx4 v[246:247], off
	v_lshl_add_u64 v[246:247], v[246:247], 0, s[34:35]
	v_mfma_f32_16x16x32_bf16 v[28:31], v[208:211], v[188:191], v[28:31]
	v_mfma_f32_16x16x32_bf16 v[24:27], v[212:215], v[188:191], v[24:27]
	v_mfma_f32_16x16x32_bf16 v[20:23], v[216:219], v[188:191], v[20:23]
	v_mfma_f32_16x16x32_bf16 v[16:19], v[220:223], v[188:191], v[16:19]
	s_waitcnt lgkmcnt(0)
	v_mfma_f32_16x16x32_bf16 v[108:111], v[224:227], v[176:179], v[108:111]
	ds_read_b128 v[192:195], v173 offset:0
	v_mfma_f32_16x16x32_bf16 v[104:107], v[228:231], v[176:179], v[104:107]
	ds_read_b128 v[196:199], v173 offset:2048
	v_mfma_f32_16x16x32_bf16 v[100:103], v[232:235], v[176:179], v[100:103]
	ds_read_b128 v[200:203], v173 offset:4096
	v_mfma_f32_16x16x32_bf16 v[96:99], v[236:239], v[176:179], v[96:99]
	ds_read_b128 v[204:207], v173 offset:6144
	v_mfma_f32_16x16x32_bf16 v[76:79], v[224:227], v[180:183], v[76:79]
	ds_read_b128 v[208:211], v175 offset:32768
	v_mfma_f32_16x16x32_bf16 v[72:75], v[228:231], v[180:183], v[72:75]
	ds_read_b128 v[212:215], v175 offset:34816
	v_mfma_f32_16x16x32_bf16 v[68:71], v[232:235], v[180:183], v[68:71]
	ds_read_b128 v[216:219], v175 offset:36864
	v_mfma_f32_16x16x32_bf16 v[64:67], v[236:239], v[180:183], v[64:67]
	ds_read_b128 v[220:223], v175 offset:38912
	v_mfma_f32_16x16x32_bf16 v[44:47], v[224:227], v[184:187], v[44:47]
	v_mfma_f32_16x16x32_bf16 v[40:43], v[228:231], v[184:187], v[40:43]
	v_mfma_f32_16x16x32_bf16 v[36:39], v[232:235], v[184:187], v[36:39]
	v_mfma_f32_16x16x32_bf16 v[32:35], v[236:239], v[184:187], v[32:35]
	v_mfma_f32_16x16x32_bf16 v[12:15], v[224:227], v[188:191], v[12:15]
	v_mfma_f32_16x16x32_bf16 v[8:11], v[228:231], v[188:191], v[8:11]
	v_mfma_f32_16x16x32_bf16 v[4:7], v[232:235], v[188:191], v[4:7]
	v_mfma_f32_16x16x32_bf16 v[0:3], v[236:239], v[188:191], v[0:3]
	s_waitcnt lgkmcnt(0)
	v_mfma_f32_16x16x32_bf16 v[124:127], v[208:211], v[192:195], v[124:127]
	ds_read_b128 v[224:227], v175 offset:40960
	v_mfma_f32_16x16x32_bf16 v[120:123], v[212:215], v[192:195], v[120:123]
	ds_read_b128 v[228:231], v175 offset:43008
	v_mfma_f32_16x16x32_bf16 v[116:119], v[216:219], v[192:195], v[116:119]
	ds_read_b128 v[232:235], v175 offset:45056
	v_mfma_f32_16x16x32_bf16 v[112:115], v[220:223], v[192:195], v[112:115]
	ds_read_b128 v[236:239], v175 offset:47104
	v_mfma_f32_16x16x32_bf16 v[92:95], v[208:211], v[196:199], v[92:95]
	v_mfma_f32_16x16x32_bf16 v[88:91], v[212:215], v[196:199], v[88:91]
	v_mfma_f32_16x16x32_bf16 v[84:87], v[216:219], v[196:199], v[84:87]
	v_mfma_f32_16x16x32_bf16 v[80:83], v[220:223], v[196:199], v[80:83]
	v_mfma_f32_16x16x32_bf16 v[60:63], v[208:211], v[200:203], v[60:63]
	v_mfma_f32_16x16x32_bf16 v[56:59], v[212:215], v[200:203], v[56:59]
	v_mfma_f32_16x16x32_bf16 v[52:55], v[216:219], v[200:203], v[52:55]
	v_mfma_f32_16x16x32_bf16 v[48:51], v[220:223], v[200:203], v[48:51]
	v_mfma_f32_16x16x32_bf16 v[28:31], v[208:211], v[204:207], v[28:31]
	v_mfma_f32_16x16x32_bf16 v[24:27], v[212:215], v[204:207], v[24:27]
	v_mfma_f32_16x16x32_bf16 v[20:23], v[216:219], v[204:207], v[20:23]
	v_mfma_f32_16x16x32_bf16 v[16:19], v[220:223], v[204:207], v[16:19]
	s_waitcnt lgkmcnt(0)
	s_waitcnt vmcnt(4)
	s_barrier
	v_mfma_f32_16x16x32_bf16 v[108:111], v[224:227], v[192:195], v[108:111]
	ds_read_b128 v[176:179], v172 offset:32768
	s_add_u32 m0, s101, 0x8000
	v_mfma_f32_16x16x32_bf16 v[104:107], v[228:231], v[192:195], v[104:107]
	ds_read_b128 v[180:183], v172 offset:34816
	global_load_lds_dwordx4 v[138:139], off
	v_lshl_add_u64 v[138:139], v[138:139], 0, s[34:35]
	v_mfma_f32_16x16x32_bf16 v[100:103], v[232:235], v[192:195], v[100:103]
	ds_read_b128 v[184:187], v172 offset:36864
	s_add_u32 m0, s101, 0xa000
	v_mfma_f32_16x16x32_bf16 v[96:99], v[236:239], v[192:195], v[96:99]
	ds_read_b128 v[188:191], v172 offset:38912
	global_load_lds_dwordx4 v[140:141], off
	v_lshl_add_u64 v[140:141], v[140:141], 0, s[34:35]
	v_mfma_f32_16x16x32_bf16 v[76:79], v[224:227], v[196:199], v[76:79]
	ds_read_b128 v[208:211], v174 offset:0
	s_add_u32 m0, s101, 0xc000
	v_mfma_f32_16x16x32_bf16 v[72:75], v[228:231], v[196:199], v[72:75]
	ds_read_b128 v[212:215], v174 offset:2048
	global_load_lds_dwordx4 v[250:251], off
	v_lshl_add_u64 v[250:251], v[250:251], 0, s[34:35]
	v_mfma_f32_16x16x32_bf16 v[68:71], v[232:235], v[196:199], v[68:71]
	ds_read_b128 v[216:219], v174 offset:4096
	s_add_u32 m0, s101, 0xe000
	v_mfma_f32_16x16x32_bf16 v[64:67], v[236:239], v[196:199], v[64:67]
	ds_read_b128 v[220:223], v174 offset:6144
	global_load_lds_dwordx4 v[252:253], off
	v_lshl_add_u64 v[252:253], v[252:253], 0, s[34:35]
	v_mfma_f32_16x16x32_bf16 v[44:47], v[224:227], v[200:203], v[44:47]
	v_mfma_f32_16x16x32_bf16 v[40:43], v[228:231], v[200:203], v[40:43]
	v_mfma_f32_16x16x32_bf16 v[36:39], v[232:235], v[200:203], v[36:39]
	v_mfma_f32_16x16x32_bf16 v[32:35], v[236:239], v[200:203], v[32:35]
	v_mfma_f32_16x16x32_bf16 v[12:15], v[224:227], v[204:207], v[12:15]
	v_mfma_f32_16x16x32_bf16 v[8:11], v[228:231], v[204:207], v[8:11]
	v_mfma_f32_16x16x32_bf16 v[4:7], v[232:235], v[204:207], v[4:7]
	v_mfma_f32_16x16x32_bf16 v[0:3], v[236:239], v[204:207], v[0:3]
	s_waitcnt lgkmcnt(0)
	v_mfma_f32_16x16x32_bf16 v[124:127], v[208:211], v[176:179], v[124:127]
	ds_read_b128 v[224:227], v174 offset:8192
	v_mfma_f32_16x16x32_bf16 v[120:123], v[212:215], v[176:179], v[120:123]
	ds_read_b128 v[228:231], v174 offset:10240
	v_mfma_f32_16x16x32_bf16 v[116:119], v[216:219], v[176:179], v[116:119]
	ds_read_b128 v[232:235], v174 offset:12288
	v_mfma_f32_16x16x32_bf16 v[112:115], v[220:223], v[176:179], v[112:115]
	ds_read_b128 v[236:239], v174 offset:14336
	v_mfma_f32_16x16x32_bf16 v[92:95], v[208:211], v[180:183], v[92:95]
	s_mov_b32 m0, s100
	v_mfma_f32_16x16x32_bf16 v[88:91], v[212:215], v[180:183], v[88:91]
	global_load_lds_dwordx4 v[240:241], off
	v_lshl_add_u64 v[240:241], v[240:241], 0, s[34:35]
	v_mfma_f32_16x16x32_bf16 v[84:87], v[216:219], v[180:183], v[84:87]
	s_add_u32 m0, s100, 0x2000
	v_mfma_f32_16x16x32_bf16 v[80:83], v[220:223], v[180:183], v[80:83]
	global_load_lds_dwordx4 v[242:243], off
	v_lshl_add_u64 v[242:243], v[242:243], 0, s[34:35]
	v_mfma_f32_16x16x32_bf16 v[60:63], v[208:211], v[184:187], v[60:63]
	s_add_u32 m0, s100, 0x4000
	v_mfma_f32_16x16x32_bf16 v[56:59], v[212:215], v[184:187], v[56:59]
	global_load_lds_dwordx4 v[244:245], off
	v_lshl_add_u64 v[244:245], v[244:245], 0, s[34:35]
	v_mfma_f32_16x16x32_bf16 v[52:55], v[216:219], v[184:187], v[52:55]
	s_add_u32 m0, s100, 0x6000
	v_mfma_f32_16x16x32_bf16 v[48:51], v[220:223], v[184:187], v[48:51]
	global_load_lds_dwordx4 v[246:247], off
	v_lshl_add_u64 v[246:247], v[246:247], 0, s[34:35]
	v_mfma_f32_16x16x32_bf16 v[28:31], v[208:211], v[188:191], v[28:31]
	v_mfma_f32_16x16x32_bf16 v[24:27], v[212:215], v[188:191], v[24:27]
	v_mfma_f32_16x16x32_bf16 v[20:23], v[216:219], v[188:191], v[20:23]
	v_mfma_f32_16x16x32_bf16 v[16:19], v[220:223], v[188:191], v[16:19]
	s_waitcnt lgkmcnt(0)
	v_mfma_f32_16x16x32_bf16 v[108:111], v[224:227], v[176:179], v[108:111]
	ds_read_b128 v[192:195], v173 offset:32768
	v_mfma_f32_16x16x32_bf16 v[104:107], v[228:231], v[176:179], v[104:107]
	ds_read_b128 v[196:199], v173 offset:34816
	v_mfma_f32_16x16x32_bf16 v[100:103], v[232:235], v[176:179], v[100:103]
	ds_read_b128 v[200:203], v173 offset:36864
	v_mfma_f32_16x16x32_bf16 v[96:99], v[236:239], v[176:179], v[96:99]
	ds_read_b128 v[204:207], v173 offset:38912
	v_mfma_f32_16x16x32_bf16 v[76:79], v[224:227], v[180:183], v[76:79]
	ds_read_b128 v[208:211], v175 offset:0
	v_mfma_f32_16x16x32_bf16 v[72:75], v[228:231], v[180:183], v[72:75]
	ds_read_b128 v[212:215], v175 offset:2048
	v_mfma_f32_16x16x32_bf16 v[68:71], v[232:235], v[180:183], v[68:71]
	ds_read_b128 v[216:219], v175 offset:4096
	v_mfma_f32_16x16x32_bf16 v[64:67], v[236:239], v[180:183], v[64:67]
	ds_read_b128 v[220:223], v175 offset:6144
	v_mfma_f32_16x16x32_bf16 v[44:47], v[224:227], v[184:187], v[44:47]
	v_mfma_f32_16x16x32_bf16 v[40:43], v[228:231], v[184:187], v[40:43]
	v_mfma_f32_16x16x32_bf16 v[36:39], v[232:235], v[184:187], v[36:39]
	v_mfma_f32_16x16x32_bf16 v[32:35], v[236:239], v[184:187], v[32:35]
	v_mfma_f32_16x16x32_bf16 v[12:15], v[224:227], v[188:191], v[12:15]
	v_mfma_f32_16x16x32_bf16 v[8:11], v[228:231], v[188:191], v[8:11]
	v_mfma_f32_16x16x32_bf16 v[4:7], v[232:235], v[188:191], v[4:7]
	v_mfma_f32_16x16x32_bf16 v[0:3], v[236:239], v[188:191], v[0:3]
	s_waitcnt lgkmcnt(0)
	v_mfma_f32_16x16x32_bf16 v[124:127], v[208:211], v[192:195], v[124:127]
	ds_read_b128 v[224:227], v175 offset:8192
	v_mfma_f32_16x16x32_bf16 v[120:123], v[212:215], v[192:195], v[120:123]
	ds_read_b128 v[228:231], v175 offset:10240
	v_mfma_f32_16x16x32_bf16 v[116:119], v[216:219], v[192:195], v[116:119]
	ds_read_b128 v[232:235], v175 offset:12288
	v_mfma_f32_16x16x32_bf16 v[112:115], v[220:223], v[192:195], v[112:115]
	ds_read_b128 v[236:239], v175 offset:14336
	v_mfma_f32_16x16x32_bf16 v[92:95], v[208:211], v[196:199], v[92:95]
	v_mfma_f32_16x16x32_bf16 v[88:91], v[212:215], v[196:199], v[88:91]
	v_mfma_f32_16x16x32_bf16 v[84:87], v[216:219], v[196:199], v[84:87]
	v_mfma_f32_16x16x32_bf16 v[80:83], v[220:223], v[196:199], v[80:83]
	v_mfma_f32_16x16x32_bf16 v[60:63], v[208:211], v[200:203], v[60:63]
	v_mfma_f32_16x16x32_bf16 v[56:59], v[212:215], v[200:203], v[56:59]
	v_mfma_f32_16x16x32_bf16 v[52:55], v[216:219], v[200:203], v[52:55]
	v_mfma_f32_16x16x32_bf16 v[48:51], v[220:223], v[200:203], v[48:51]
	v_mfma_f32_16x16x32_bf16 v[28:31], v[208:211], v[204:207], v[28:31]
	v_mfma_f32_16x16x32_bf16 v[24:27], v[212:215], v[204:207], v[24:27]
	v_mfma_f32_16x16x32_bf16 v[20:23], v[216:219], v[204:207], v[20:23]
	v_mfma_f32_16x16x32_bf16 v[16:19], v[220:223], v[204:207], v[16:19]
	s_waitcnt lgkmcnt(0)
	s_waitcnt vmcnt(4)
	s_barrier
	v_mfma_f32_16x16x32_bf16 v[108:111], v[224:227], v[192:195], v[108:111]
	ds_read_b128 v[176:179], v254 offset:0
	s_mov_b32 m0, s101
	v_mfma_f32_16x16x32_bf16 v[104:107], v[228:231], v[192:195], v[104:107]
	ds_read_b128 v[180:183], v254 offset:2048
	global_load_lds_dwordx4 v[138:139], off
	v_lshl_add_u64 v[138:139], v[138:139], 0, s[34:35]
	v_mfma_f32_16x16x32_bf16 v[100:103], v[232:235], v[192:195], v[100:103]
	ds_read_b128 v[184:187], v254 offset:4096
	s_add_u32 m0, s101, 0x2000
	v_mfma_f32_16x16x32_bf16 v[96:99], v[236:239], v[192:195], v[96:99]
	ds_read_b128 v[188:191], v254 offset:6144
	global_load_lds_dwordx4 v[140:141], off
	v_lshl_add_u64 v[140:141], v[140:141], 0, s[34:35]
	v_mfma_f32_16x16x32_bf16 v[76:79], v[224:227], v[196:199], v[76:79]
	ds_read_b128 v[208:211], v174 offset:32768
	s_add_u32 m0, s101, 0x4000
	v_mfma_f32_16x16x32_bf16 v[72:75], v[228:231], v[196:199], v[72:75]
	ds_read_b128 v[212:215], v174 offset:34816
	global_load_lds_dwordx4 v[250:251], off
	v_lshl_add_u64 v[250:251], v[250:251], 0, s[34:35]
	v_mfma_f32_16x16x32_bf16 v[68:71], v[232:235], v[196:199], v[68:71]
	ds_read_b128 v[216:219], v174 offset:36864
	s_add_u32 m0, s101, 0x6000
	v_mfma_f32_16x16x32_bf16 v[64:67], v[236:239], v[196:199], v[64:67]
	ds_read_b128 v[220:223], v174 offset:38912
	global_load_lds_dwordx4 v[252:253], off
	v_lshl_add_u64 v[252:253], v[252:253], 0, s[34:35]
	v_mfma_f32_16x16x32_bf16 v[44:47], v[224:227], v[200:203], v[44:47]
	v_mfma_f32_16x16x32_bf16 v[40:43], v[228:231], v[200:203], v[40:43]
	v_mfma_f32_16x16x32_bf16 v[36:39], v[232:235], v[200:203], v[36:39]
	v_mfma_f32_16x16x32_bf16 v[32:35], v[236:239], v[200:203], v[32:35]
	v_mfma_f32_16x16x32_bf16 v[12:15], v[224:227], v[204:207], v[12:15]
	v_mfma_f32_16x16x32_bf16 v[8:11], v[228:231], v[204:207], v[8:11]
	v_mfma_f32_16x16x32_bf16 v[4:7], v[232:235], v[204:207], v[4:7]
	v_mfma_f32_16x16x32_bf16 v[0:3], v[236:239], v[204:207], v[0:3]
	s_waitcnt lgkmcnt(0)
	v_mfma_f32_16x16x32_bf16 v[124:127], v[208:211], v[176:179], v[124:127]
	ds_read_b128 v[224:227], v174 offset:40960
	v_mfma_f32_16x16x32_bf16 v[120:123], v[212:215], v[176:179], v[120:123]
	ds_read_b128 v[228:231], v174 offset:43008
	v_mfma_f32_16x16x32_bf16 v[116:119], v[216:219], v[176:179], v[116:119]
	ds_read_b128 v[232:235], v174 offset:45056
	v_mfma_f32_16x16x32_bf16 v[112:115], v[220:223], v[176:179], v[112:115]
	ds_read_b128 v[236:239], v174 offset:47104
	v_mfma_f32_16x16x32_bf16 v[92:95], v[208:211], v[180:183], v[92:95]
	s_add_u32 m0, s100, 0x8000
	v_mfma_f32_16x16x32_bf16 v[88:91], v[212:215], v[180:183], v[88:91]
	global_load_lds_dwordx4 v[240:241], off
	v_lshl_add_u64 v[240:241], v[240:241], 0, s[34:35]
	v_mfma_f32_16x16x32_bf16 v[84:87], v[216:219], v[180:183], v[84:87]
	s_add_u32 m0, s100, 0xa000
	v_mfma_f32_16x16x32_bf16 v[80:83], v[220:223], v[180:183], v[80:83]
	global_load_lds_dwordx4 v[242:243], off
	v_lshl_add_u64 v[242:243], v[242:243], 0, s[34:35]
	v_mfma_f32_16x16x32_bf16 v[60:63], v[208:211], v[184:187], v[60:63]
	s_add_u32 m0, s100, 0xc000
	v_mfma_f32_16x16x32_bf16 v[56:59], v[212:215], v[184:187], v[56:59]
	global_load_lds_dwordx4 v[244:245], off
	v_lshl_add_u64 v[244:245], v[244:245], 0, s[34:35]
	v_mfma_f32_16x16x32_bf16 v[52:55], v[216:219], v[184:187], v[52:55]
	s_add_u32 m0, s100, 0xe000
	v_mfma_f32_16x16x32_bf16 v[48:51], v[220:223], v[184:187], v[48:51]
	global_load_lds_dwordx4 v[246:247], off
	v_lshl_add_u64 v[246:247], v[246:247], 0, s[34:35]
	v_mfma_f32_16x16x32_bf16 v[28:31], v[208:211], v[188:191], v[28:31]
	v_mfma_f32_16x16x32_bf16 v[24:27], v[212:215], v[188:191], v[24:27]
	v_mfma_f32_16x16x32_bf16 v[20:23], v[216:219], v[188:191], v[20:23]
	v_mfma_f32_16x16x32_bf16 v[16:19], v[220:223], v[188:191], v[16:19]
	s_waitcnt lgkmcnt(0)
	v_mfma_f32_16x16x32_bf16 v[108:111], v[224:227], v[176:179], v[108:111]
	ds_read_b128 v[192:195], v255 offset:0
	v_mfma_f32_16x16x32_bf16 v[104:107], v[228:231], v[176:179], v[104:107]
	ds_read_b128 v[196:199], v255 offset:2048
	v_mfma_f32_16x16x32_bf16 v[100:103], v[232:235], v[176:179], v[100:103]
	ds_read_b128 v[200:203], v255 offset:4096
	v_mfma_f32_16x16x32_bf16 v[96:99], v[236:239], v[176:179], v[96:99]
	ds_read_b128 v[204:207], v255 offset:6144
	v_mfma_f32_16x16x32_bf16 v[76:79], v[224:227], v[180:183], v[76:79]
	ds_read_b128 v[208:211], v175 offset:32768
	v_mfma_f32_16x16x32_bf16 v[72:75], v[228:231], v[180:183], v[72:75]
	ds_read_b128 v[212:215], v175 offset:34816
	v_mfma_f32_16x16x32_bf16 v[68:71], v[232:235], v[180:183], v[68:71]
	ds_read_b128 v[216:219], v175 offset:36864
	v_mfma_f32_16x16x32_bf16 v[64:67], v[236:239], v[180:183], v[64:67]
	ds_read_b128 v[220:223], v175 offset:38912
	v_mfma_f32_16x16x32_bf16 v[44:47], v[224:227], v[184:187], v[44:47]
	v_mfma_f32_16x16x32_bf16 v[40:43], v[228:231], v[184:187], v[40:43]
	v_mfma_f32_16x16x32_bf16 v[36:39], v[232:235], v[184:187], v[36:39]
	v_mfma_f32_16x16x32_bf16 v[32:35], v[236:239], v[184:187], v[32:35]
	v_mfma_f32_16x16x32_bf16 v[12:15], v[224:227], v[188:191], v[12:15]
	v_mfma_f32_16x16x32_bf16 v[8:11], v[228:231], v[188:191], v[8:11]
	v_mfma_f32_16x16x32_bf16 v[4:7], v[232:235], v[188:191], v[4:7]
	v_mfma_f32_16x16x32_bf16 v[0:3], v[236:239], v[188:191], v[0:3]
	s_waitcnt lgkmcnt(0)
	v_mfma_f32_16x16x32_bf16 v[124:127], v[208:211], v[192:195], v[124:127]
	ds_read_b128 v[224:227], v175 offset:40960
	v_mfma_f32_16x16x32_bf16 v[120:123], v[212:215], v[192:195], v[120:123]
	ds_read_b128 v[228:231], v175 offset:43008
	v_mfma_f32_16x16x32_bf16 v[116:119], v[216:219], v[192:195], v[116:119]
	ds_read_b128 v[232:235], v175 offset:45056
	v_mfma_f32_16x16x32_bf16 v[112:115], v[220:223], v[192:195], v[112:115]
	ds_read_b128 v[236:239], v175 offset:47104
	v_mfma_f32_16x16x32_bf16 v[92:95], v[208:211], v[196:199], v[92:95]
	v_mfma_f32_16x16x32_bf16 v[88:91], v[212:215], v[196:199], v[88:91]
	v_mfma_f32_16x16x32_bf16 v[84:87], v[216:219], v[196:199], v[84:87]
	v_mfma_f32_16x16x32_bf16 v[80:83], v[220:223], v[196:199], v[80:83]
	v_mfma_f32_16x16x32_bf16 v[60:63], v[208:211], v[200:203], v[60:63]
	v_mfma_f32_16x16x32_bf16 v[56:59], v[212:215], v[200:203], v[56:59]
	v_mfma_f32_16x16x32_bf16 v[52:55], v[216:219], v[200:203], v[52:55]
	v_mfma_f32_16x16x32_bf16 v[48:51], v[220:223], v[200:203], v[48:51]
	v_mfma_f32_16x16x32_bf16 v[28:31], v[208:211], v[204:207], v[28:31]
	v_mfma_f32_16x16x32_bf16 v[24:27], v[212:215], v[204:207], v[24:27]
	v_mfma_f32_16x16x32_bf16 v[20:23], v[216:219], v[204:207], v[20:23]
	v_mfma_f32_16x16x32_bf16 v[16:19], v[220:223], v[204:207], v[16:19]
	s_waitcnt lgkmcnt(0)
	s_waitcnt vmcnt(4)
	s_barrier
	v_mfma_f32_16x16x32_bf16 v[108:111], v[224:227], v[192:195], v[108:111]
	ds_read_b128 v[176:179], v172 offset:0
	s_add_u32 m0, s101, 0x8000
	v_mfma_f32_16x16x32_bf16 v[104:107], v[228:231], v[192:195], v[104:107]
	ds_read_b128 v[180:183], v172 offset:2048
	global_load_lds_dwordx4 v[138:139], off
	v_lshl_add_u64 v[138:139], v[138:139], 0, s[34:35]
	v_mfma_f32_16x16x32_bf16 v[100:103], v[232:235], v[192:195], v[100:103]
	ds_read_b128 v[184:187], v172 offset:4096
	s_add_u32 m0, s101, 0xa000
	v_mfma_f32_16x16x32_bf16 v[96:99], v[236:239], v[192:195], v[96:99]
	ds_read_b128 v[188:191], v172 offset:6144
	global_load_lds_dwordx4 v[140:141], off
	v_lshl_add_u64 v[140:141], v[140:141], 0, s[34:35]
	v_mfma_f32_16x16x32_bf16 v[76:79], v[224:227], v[196:199], v[76:79]
	ds_read_b128 v[208:211], v174 offset:0
	s_add_u32 m0, s101, 0xc000
	v_mfma_f32_16x16x32_bf16 v[72:75], v[228:231], v[196:199], v[72:75]
	ds_read_b128 v[212:215], v174 offset:2048
	global_load_lds_dwordx4 v[250:251], off
	v_lshl_add_u64 v[250:251], v[250:251], 0, s[34:35]
	v_mfma_f32_16x16x32_bf16 v[68:71], v[232:235], v[196:199], v[68:71]
	ds_read_b128 v[216:219], v174 offset:4096
	s_add_u32 m0, s101, 0xe000
	v_mfma_f32_16x16x32_bf16 v[64:67], v[236:239], v[196:199], v[64:67]
	ds_read_b128 v[220:223], v174 offset:6144
	global_load_lds_dwordx4 v[252:253], off
	v_lshl_add_u64 v[252:253], v[252:253], 0, s[34:35]
	v_mfma_f32_16x16x32_bf16 v[44:47], v[224:227], v[200:203], v[44:47]
	v_mfma_f32_16x16x32_bf16 v[40:43], v[228:231], v[200:203], v[40:43]
	v_mfma_f32_16x16x32_bf16 v[36:39], v[232:235], v[200:203], v[36:39]
	v_mfma_f32_16x16x32_bf16 v[32:35], v[236:239], v[200:203], v[32:35]
	v_mfma_f32_16x16x32_bf16 v[12:15], v[224:227], v[204:207], v[12:15]
	v_mfma_f32_16x16x32_bf16 v[8:11], v[228:231], v[204:207], v[8:11]
	v_mfma_f32_16x16x32_bf16 v[4:7], v[232:235], v[204:207], v[4:7]
	v_mfma_f32_16x16x32_bf16 v[0:3], v[236:239], v[204:207], v[0:3]
	s_waitcnt lgkmcnt(0)
	v_mfma_f32_16x16x32_bf16 v[124:127], v[208:211], v[176:179], v[124:127]
	ds_read_b128 v[224:227], v174 offset:8192
	v_mfma_f32_16x16x32_bf16 v[120:123], v[212:215], v[176:179], v[120:123]
	ds_read_b128 v[228:231], v174 offset:10240
	v_mfma_f32_16x16x32_bf16 v[116:119], v[216:219], v[176:179], v[116:119]
	ds_read_b128 v[232:235], v174 offset:12288
	v_mfma_f32_16x16x32_bf16 v[112:115], v[220:223], v[176:179], v[112:115]
	ds_read_b128 v[236:239], v174 offset:14336
	v_mfma_f32_16x16x32_bf16 v[92:95], v[208:211], v[180:183], v[92:95]
	s_add_u32 m0, s100, 0x20000
	v_mfma_f32_16x16x32_bf16 v[88:91], v[212:215], v[180:183], v[88:91]
	global_load_lds_dwordx4 v[240:241], off
	v_lshl_add_u64 v[240:241], v[240:241], 0, s[34:35]
	v_mfma_f32_16x16x32_bf16 v[84:87], v[216:219], v[180:183], v[84:87]
	s_add_u32 m0, s100, 0x22000
	v_mfma_f32_16x16x32_bf16 v[80:83], v[220:223], v[180:183], v[80:83]
	global_load_lds_dwordx4 v[242:243], off
	v_lshl_add_u64 v[242:243], v[242:243], 0, s[34:35]
	v_mfma_f32_16x16x32_bf16 v[60:63], v[208:211], v[184:187], v[60:63]
	s_add_u32 m0, s100, 0x24000
	v_mfma_f32_16x16x32_bf16 v[56:59], v[212:215], v[184:187], v[56:59]
	global_load_lds_dwordx4 v[244:245], off
	v_lshl_add_u64 v[244:245], v[244:245], 0, s[34:35]
	v_mfma_f32_16x16x32_bf16 v[52:55], v[216:219], v[184:187], v[52:55]
	s_add_u32 m0, s100, 0x26000
	v_mfma_f32_16x16x32_bf16 v[48:51], v[220:223], v[184:187], v[48:51]
	global_load_lds_dwordx4 v[246:247], off
	v_lshl_add_u64 v[246:247], v[246:247], 0, s[34:35]
	v_mfma_f32_16x16x32_bf16 v[28:31], v[208:211], v[188:191], v[28:31]
	v_mfma_f32_16x16x32_bf16 v[24:27], v[212:215], v[188:191], v[24:27]
	v_mfma_f32_16x16x32_bf16 v[20:23], v[216:219], v[188:191], v[20:23]
	v_mfma_f32_16x16x32_bf16 v[16:19], v[220:223], v[188:191], v[16:19]
	s_waitcnt lgkmcnt(0)
	v_mfma_f32_16x16x32_bf16 v[108:111], v[224:227], v[176:179], v[108:111]
	ds_read_b128 v[192:195], v173 offset:0
	v_mfma_f32_16x16x32_bf16 v[104:107], v[228:231], v[176:179], v[104:107]
	ds_read_b128 v[196:199], v173 offset:2048
	v_mfma_f32_16x16x32_bf16 v[100:103], v[232:235], v[176:179], v[100:103]
	ds_read_b128 v[200:203], v173 offset:4096
	v_mfma_f32_16x16x32_bf16 v[96:99], v[236:239], v[176:179], v[96:99]
	ds_read_b128 v[204:207], v173 offset:6144
	v_mfma_f32_16x16x32_bf16 v[76:79], v[224:227], v[180:183], v[76:79]
	ds_read_b128 v[208:211], v175 offset:0
	v_mfma_f32_16x16x32_bf16 v[72:75], v[228:231], v[180:183], v[72:75]
	ds_read_b128 v[212:215], v175 offset:2048
	v_mfma_f32_16x16x32_bf16 v[68:71], v[232:235], v[180:183], v[68:71]
	ds_read_b128 v[216:219], v175 offset:4096
	v_mfma_f32_16x16x32_bf16 v[64:67], v[236:239], v[180:183], v[64:67]
	ds_read_b128 v[220:223], v175 offset:6144
	v_mfma_f32_16x16x32_bf16 v[44:47], v[224:227], v[184:187], v[44:47]
	v_mfma_f32_16x16x32_bf16 v[40:43], v[228:231], v[184:187], v[40:43]
	v_mfma_f32_16x16x32_bf16 v[36:39], v[232:235], v[184:187], v[36:39]
	v_mfma_f32_16x16x32_bf16 v[32:35], v[236:239], v[184:187], v[32:35]
	v_mfma_f32_16x16x32_bf16 v[12:15], v[224:227], v[188:191], v[12:15]
	v_mfma_f32_16x16x32_bf16 v[8:11], v[228:231], v[188:191], v[8:11]
	v_mfma_f32_16x16x32_bf16 v[4:7], v[232:235], v[188:191], v[4:7]
	v_mfma_f32_16x16x32_bf16 v[0:3], v[236:239], v[188:191], v[0:3]
	s_waitcnt lgkmcnt(0)
	v_mfma_f32_16x16x32_bf16 v[124:127], v[208:211], v[192:195], v[124:127]
	ds_read_b128 v[224:227], v175 offset:8192
	v_mfma_f32_16x16x32_bf16 v[120:123], v[212:215], v[192:195], v[120:123]
	ds_read_b128 v[228:231], v175 offset:10240
	v_mfma_f32_16x16x32_bf16 v[116:119], v[216:219], v[192:195], v[116:119]
	ds_read_b128 v[232:235], v175 offset:12288
	v_mfma_f32_16x16x32_bf16 v[112:115], v[220:223], v[192:195], v[112:115]
	ds_read_b128 v[236:239], v175 offset:14336
	v_mfma_f32_16x16x32_bf16 v[92:95], v[208:211], v[196:199], v[92:95]
	v_mfma_f32_16x16x32_bf16 v[88:91], v[212:215], v[196:199], v[88:91]
	v_mfma_f32_16x16x32_bf16 v[84:87], v[216:219], v[196:199], v[84:87]
	v_mfma_f32_16x16x32_bf16 v[80:83], v[220:223], v[196:199], v[80:83]
	v_mfma_f32_16x16x32_bf16 v[60:63], v[208:211], v[200:203], v[60:63]
	v_mfma_f32_16x16x32_bf16 v[56:59], v[212:215], v[200:203], v[56:59]
	v_mfma_f32_16x16x32_bf16 v[52:55], v[216:219], v[200:203], v[52:55]
	v_mfma_f32_16x16x32_bf16 v[48:51], v[220:223], v[200:203], v[48:51]
	v_mfma_f32_16x16x32_bf16 v[28:31], v[208:211], v[204:207], v[28:31]
	v_mfma_f32_16x16x32_bf16 v[24:27], v[212:215], v[204:207], v[24:27]
	v_mfma_f32_16x16x32_bf16 v[20:23], v[216:219], v[204:207], v[20:23]
	v_mfma_f32_16x16x32_bf16 v[16:19], v[220:223], v[204:207], v[16:19]
	s_waitcnt lgkmcnt(0)
	s_waitcnt vmcnt(4)
	s_barrier
	s_add_i32 s44, s44, -1
	s_cmp_lg_u32 s44, 0
	s_cbranch_scc1 .Lgemm_p9_loop
	v_mfma_f32_16x16x32_bf16 v[108:111], v[224:227], v[192:195], v[108:111]
	ds_read_b128 v[176:179], v172 offset:32768
	s_mov_b32 m0, s101
	v_mfma_f32_16x16x32_bf16 v[104:107], v[228:231], v[192:195], v[104:107]
	ds_read_b128 v[180:183], v172 offset:34816
	global_load_lds_dwordx4 v[138:139], off
	v_lshl_add_u64 v[138:139], v[138:139], 0, s[34:35]
	v_mfma_f32_16x16x32_bf16 v[100:103], v[232:235], v[192:195], v[100:103]
	ds_read_b128 v[184:187], v172 offset:36864
	s_add_u32 m0, s101, 0x2000
	v_mfma_f32_16x16x32_bf16 v[96:99], v[236:239], v[192:195], v[96:99]
	ds_read_b128 v[188:191], v172 offset:38912
	global_load_lds_dwordx4 v[140:141], off
	v_lshl_add_u64 v[140:141], v[140:141], 0, s[34:35]
	v_mfma_f32_16x16x32_bf16 v[76:79], v[224:227], v[196:199], v[76:79]
	ds_read_b128 v[208:211], v174 offset:32768
	s_add_u32 m0, s101, 0x4000
	v_mfma_f32_16x16x32_bf16 v[72:75], v[228:231], v[196:199], v[72:75]
	ds_read_b128 v[212:215], v174 offset:34816
	global_load_lds_dwordx4 v[250:251], off
	v_lshl_add_u64 v[250:251], v[250:251], 0, s[34:35]
	v_mfma_f32_16x16x32_bf16 v[68:71], v[232:235], v[196:199], v[68:71]
	ds_read_b128 v[216:219], v174 offset:36864
	s_add_u32 m0, s101, 0x6000
	v_mfma_f32_16x16x32_bf16 v[64:67], v[236:239], v[196:199], v[64:67]
	ds_read_b128 v[220:223], v174 offset:38912
	global_load_lds_dwordx4 v[252:253], off
	v_lshl_add_u64 v[252:253], v[252:253], 0, s[34:35]
	v_mfma_f32_16x16x32_bf16 v[44:47], v[224:227], v[200:203], v[44:47]
	v_mfma_f32_16x16x32_bf16 v[40:43], v[228:231], v[200:203], v[40:43]
	v_mfma_f32_16x16x32_bf16 v[36:39], v[232:235], v[200:203], v[36:39]
	v_mfma_f32_16x16x32_bf16 v[32:35], v[236:239], v[200:203], v[32:35]
	v_mfma_f32_16x16x32_bf16 v[12:15], v[224:227], v[204:207], v[12:15]
	v_mfma_f32_16x16x32_bf16 v[8:11], v[228:231], v[204:207], v[8:11]
	v_mfma_f32_16x16x32_bf16 v[4:7], v[232:235], v[204:207], v[4:7]
	v_mfma_f32_16x16x32_bf16 v[0:3], v[236:239], v[204:207], v[0:3]
	s_waitcnt lgkmcnt(0)
	v_mfma_f32_16x16x32_bf16 v[124:127], v[208:211], v[176:179], v[124:127]
	ds_read_b128 v[224:227], v174 offset:40960
	v_mfma_f32_16x16x32_bf16 v[120:123], v[212:215], v[176:179], v[120:123]
	ds_read_b128 v[228:231], v174 offset:43008
	v_mfma_f32_16x16x32_bf16 v[116:119], v[216:219], v[176:179], v[116:119]
	ds_read_b128 v[232:235], v174 offset:45056
	v_mfma_f32_16x16x32_bf16 v[112:115], v[220:223], v[176:179], v[112:115]
	ds_read_b128 v[236:239], v174 offset:47104
	v_mfma_f32_16x16x32_bf16 v[92:95], v[208:211], v[180:183], v[92:95]
	s_mov_b32 m0, s100
	v_mfma_f32_16x16x32_bf16 v[88:91], v[212:215], v[180:183], v[88:91]
	global_load_lds_dwordx4 v[240:241], off
	v_lshl_add_u64 v[240:241], v[240:241], 0, s[34:35]
	v_mfma_f32_16x16x32_bf16 v[84:87], v[216:219], v[180:183], v[84:87]
	s_add_u32 m0, s100, 0x2000
	v_mfma_f32_16x16x32_bf16 v[80:83], v[220:223], v[180:183], v[80:83]
	global_load_lds_dwordx4 v[242:243], off
	v_lshl_add_u64 v[242:243], v[242:243], 0, s[34:35]
	v_mfma_f32_16x16x32_bf16 v[60:63], v[208:211], v[184:187], v[60:63]
	s_add_u32 m0, s100, 0x4000
	v_mfma_f32_16x16x32_bf16 v[56:59], v[212:215], v[184:187], v[56:59]
	global_load_lds_dwordx4 v[244:245], off
	v_lshl_add_u64 v[244:245], v[244:245], 0, s[34:35]
	v_mfma_f32_16x16x32_bf16 v[52:55], v[216:219], v[184:187], v[52:55]
	s_add_u32 m0, s100, 0x6000
	v_mfma_f32_16x16x32_bf16 v[48:51], v[220:223], v[184:187], v[48:51]
	global_load_lds_dwordx4 v[246:247], off
	v_lshl_add_u64 v[246:247], v[246:247], 0, s[34:35]
	v_mfma_f32_16x16x32_bf16 v[28:31], v[208:211], v[188:191], v[28:31]
	v_mfma_f32_16x16x32_bf16 v[24:27], v[212:215], v[188:191], v[24:27]
	v_mfma_f32_16x16x32_bf16 v[20:23], v[216:219], v[188:191], v[20:23]
	v_mfma_f32_16x16x32_bf16 v[16:19], v[220:223], v[188:191], v[16:19]
	s_waitcnt lgkmcnt(0)
	v_mfma_f32_16x16x32_bf16 v[108:111], v[224:227], v[176:179], v[108:111]
	ds_read_b128 v[192:195], v173 offset:32768
	v_mfma_f32_16x16x32_bf16 v[104:107], v[228:231], v[176:179], v[104:107]
	ds_read_b128 v[196:199], v173 offset:34816
	v_mfma_f32_16x16x32_bf16 v[100:103], v[232:235], v[176:179], v[100:103]
	ds_read_b128 v[200:203], v173 offset:36864
	v_mfma_f32_16x16x32_bf16 v[96:99], v[236:239], v[176:179], v[96:99]
	ds_read_b128 v[204:207], v173 offset:38912
	v_mfma_f32_16x16x32_bf16 v[76:79], v[224:227], v[180:183], v[76:79]
	ds_read_b128 v[208:211], v175 offset:32768
	v_mfma_f32_16x16x32_bf16 v[72:75], v[228:231], v[180:183], v[72:75]
	ds_read_b128 v[212:215], v175 offset:34816
	v_mfma_f32_16x16x32_bf16 v[68:71], v[232:235], v[180:183], v[68:71]
	ds_read_b128 v[216:219], v175 offset:36864
	v_mfma_f32_16x16x32_bf16 v[64:67], v[236:239], v[180:183], v[64:67]
	ds_read_b128 v[220:223], v175 offset:38912
	v_mfma_f32_16x16x32_bf16 v[44:47], v[224:227], v[184:187], v[44:47]
	v_mfma_f32_16x16x32_bf16 v[40:43], v[228:231], v[184:187], v[40:43]
	v_mfma_f32_16x16x32_bf16 v[36:39], v[232:235], v[184:187], v[36:39]
	v_mfma_f32_16x16x32_bf16 v[32:35], v[236:239], v[184:187], v[32:35]
	v_mfma_f32_16x16x32_bf16 v[12:15], v[224:227], v[188:191], v[12:15]
	v_mfma_f32_16x16x32_bf16 v[8:11], v[228:231], v[188:191], v[8:11]
	v_mfma_f32_16x16x32_bf16 v[4:7], v[232:235], v[188:191], v[4:7]
	v_mfma_f32_16x16x32_bf16 v[0:3], v[236:239], v[188:191], v[0:3]
	s_waitcnt lgkmcnt(0)
	v_mfma_f32_16x16x32_bf16 v[124:127], v[208:211], v[192:195], v[124:127]
	ds_read_b128 v[224:227], v175 offset:40960
	v_mfma_f32_16x16x32_bf16 v[120:123], v[212:215], v[192:195], v[120:123]
	ds_read_b128 v[228:231], v175 offset:43008
	v_mfma_f32_16x16x32_bf16 v[116:119], v[216:219], v[192:195], v[116:119]
	ds_read_b128 v[232:235], v175 offset:45056
	v_mfma_f32_16x16x32_bf16 v[112:115], v[220:223], v[192:195], v[112:115]
	ds_read_b128 v[236:239], v175 offset:47104
	v_mfma_f32_16x16x32_bf16 v[92:95], v[208:211], v[196:199], v[92:95]
	v_mfma_f32_16x16x32_bf16 v[88:91], v[212:215], v[196:199], v[88:91]
	v_mfma_f32_16x16x32_bf16 v[84:87], v[216:219], v[196:199], v[84:87]
	v_mfma_f32_16x16x32_bf16 v[80:83], v[220:223], v[196:199], v[80:83]
	v_mfma_f32_16x16x32_bf16 v[60:63], v[208:211], v[200:203], v[60:63]
	v_mfma_f32_16x16x32_bf16 v[56:59], v[212:215], v[200:203], v[56:59]
	v_mfma_f32_16x16x32_bf16 v[52:55], v[216:219], v[200:203], v[52:55]
	v_mfma_f32_16x16x32_bf16 v[48:51], v[220:223], v[200:203], v[48:51]
	v_mfma_f32_16x16x32_bf16 v[28:31], v[208:211], v[204:207], v[28:31]
	v_mfma_f32_16x16x32_bf16 v[24:27], v[212:215], v[204:207], v[24:27]
	v_mfma_f32_16x16x32_bf16 v[20:23], v[216:219], v[204:207], v[20:23]
	v_mfma_f32_16x16x32_bf16 v[16:19], v[220:223], v[204:207], v[16:19]
	s_waitcnt lgkmcnt(0)
	s_waitcnt vmcnt(4)
	s_barrier
	v_mfma_f32_16x16x32_bf16 v[108:111], v[224:227], v[192:195], v[108:111]
	ds_read_b128 v[176:179], v254 offset:0
	s_add_u32 m0, s101, 0x8000
	v_mfma_f32_16x16x32_bf16 v[104:107], v[228:231], v[192:195], v[104:107]
	ds_read_b128 v[180:183], v254 offset:2048
	global_load_lds_dwordx4 v[138:139], off
	v_lshl_add_u64 v[138:139], v[138:139], 0, s[34:35]
	v_mfma_f32_16x16x32_bf16 v[100:103], v[232:235], v[192:195], v[100:103]
	ds_read_b128 v[184:187], v254 offset:4096
	s_add_u32 m0, s101, 0xa000
	v_mfma_f32_16x16x32_bf16 v[96:99], v[236:239], v[192:195], v[96:99]
	ds_read_b128 v[188:191], v254 offset:6144
	global_load_lds_dwordx4 v[140:141], off
	v_lshl_add_u64 v[140:141], v[140:141], 0, s[34:35]
	v_mfma_f32_16x16x32_bf16 v[76:79], v[224:227], v[196:199], v[76:79]
	ds_read_b128 v[208:211], v174 offset:0
	s_add_u32 m0, s101, 0xc000
	v_mfma_f32_16x16x32_bf16 v[72:75], v[228:231], v[196:199], v[72:75]
	ds_read_b128 v[212:215], v174 offset:2048
	global_load_lds_dwordx4 v[250:251], off
	v_lshl_add_u64 v[250:251], v[250:251], 0, s[34:35]
	v_mfma_f32_16x16x32_bf16 v[68:71], v[232:235], v[196:199], v[68:71]
	ds_read_b128 v[216:219], v174 offset:4096
	s_add_u32 m0, s101, 0xe000
	v_mfma_f32_16x16x32_bf16 v[64:67], v[236:239], v[196:199], v[64:67]
	ds_read_b128 v[220:223], v174 offset:6144
	global_load_lds_dwordx4 v[252:253], off
	v_lshl_add_u64 v[252:253], v[252:253], 0, s[34:35]
	v_mfma_f32_16x16x32_bf16 v[44:47], v[224:227], v[200:203], v[44:47]
	v_mfma_f32_16x16x32_bf16 v[40:43], v[228:231], v[200:203], v[40:43]
	v_mfma_f32_16x16x32_bf16 v[36:39], v[232:235], v[200:203], v[36:39]
	v_mfma_f32_16x16x32_bf16 v[32:35], v[236:239], v[200:203], v[32:35]
	v_mfma_f32_16x16x32_bf16 v[12:15], v[224:227], v[204:207], v[12:15]
	v_mfma_f32_16x16x32_bf16 v[8:11], v[228:231], v[204:207], v[8:11]
	v_mfma_f32_16x16x32_bf16 v[4:7], v[232:235], v[204:207], v[4:7]
	v_mfma_f32_16x16x32_bf16 v[0:3], v[236:239], v[204:207], v[0:3]
	s_waitcnt lgkmcnt(0)
	v_mfma_f32_16x16x32_bf16 v[124:127], v[208:211], v[176:179], v[124:127]
	ds_read_b128 v[224:227], v174 offset:8192
	v_mfma_f32_16x16x32_bf16 v[120:123], v[212:215], v[176:179], v[120:123]
	ds_read_b128 v[228:231], v174 offset:10240
	v_mfma_f32_16x16x32_bf16 v[116:119], v[216:219], v[176:179], v[116:119]
	ds_read_b128 v[232:235], v174 offset:12288
	v_mfma_f32_16x16x32_bf16 v[112:115], v[220:223], v[176:179], v[112:115]
	ds_read_b128 v[236:239], v174 offset:14336
	v_mfma_f32_16x16x32_bf16 v[92:95], v[208:211], v[180:183], v[92:95]
	v_mfma_f32_16x16x32_bf16 v[88:91], v[212:215], v[180:183], v[88:91]
	v_mfma_f32_16x16x32_bf16 v[84:87], v[216:219], v[180:183], v[84:87]
	v_mfma_f32_16x16x32_bf16 v[80:83], v[220:223], v[180:183], v[80:83]
	v_mfma_f32_16x16x32_bf16 v[60:63], v[208:211], v[184:187], v[60:63]
	v_mfma_f32_16x16x32_bf16 v[56:59], v[212:215], v[184:187], v[56:59]
	v_mfma_f32_16x16x32_bf16 v[52:55], v[216:219], v[184:187], v[52:55]
	v_mfma_f32_16x16x32_bf16 v[48:51], v[220:223], v[184:187], v[48:51]
	v_mfma_f32_16x16x32_bf16 v[28:31], v[208:211], v[188:191], v[28:31]
	v_mfma_f32_16x16x32_bf16 v[24:27], v[212:215], v[188:191], v[24:27]
	v_mfma_f32_16x16x32_bf16 v[20:23], v[216:219], v[188:191], v[20:23]
	v_mfma_f32_16x16x32_bf16 v[16:19], v[220:223], v[188:191], v[16:19]
	s_waitcnt lgkmcnt(0)
	v_mfma_f32_16x16x32_bf16 v[108:111], v[224:227], v[176:179], v[108:111]
	ds_read_b128 v[192:195], v255 offset:0
	v_mfma_f32_16x16x32_bf16 v[104:107], v[228:231], v[176:179], v[104:107]
	ds_read_b128 v[196:199], v255 offset:2048
	v_mfma_f32_16x16x32_bf16 v[100:103], v[232:235], v[176:179], v[100:103]
	ds_read_b128 v[200:203], v255 offset:4096
	v_mfma_f32_16x16x32_bf16 v[96:99], v[236:239], v[176:179], v[96:99]
	ds_read_b128 v[204:207], v255 offset:6144
	v_mfma_f32_16x16x32_bf16 v[76:79], v[224:227], v[180:183], v[76:79]
	ds_read_b128 v[208:211], v175 offset:0
	v_mfma_f32_16x16x32_bf16 v[72:75], v[228:231], v[180:183], v[72:75]
	ds_read_b128 v[212:215], v175 offset:2048
	v_mfma_f32_16x16x32_bf16 v[68:71], v[232:235], v[180:183], v[68:71]
	ds_read_b128 v[216:219], v175 offset:4096
	v_mfma_f32_16x16x32_bf16 v[64:67], v[236:239], v[180:183], v[64:67]
	ds_read_b128 v[220:223], v175 offset:6144
	v_mfma_f32_16x16x32_bf16 v[44:47], v[224:227], v[184:187], v[44:47]
	v_mfma_f32_16x16x32_bf16 v[40:43], v[228:231], v[184:187], v[40:43]
	v_mfma_f32_16x16x32_bf16 v[36:39], v[232:235], v[184:187], v[36:39]
	v_mfma_f32_16x16x32_bf16 v[32:35], v[236:239], v[184:187], v[32:35]
	v_mfma_f32_16x16x32_bf16 v[12:15], v[224:227], v[188:191], v[12:15]
	v_mfma_f32_16x16x32_bf16 v[8:11], v[228:231], v[188:191], v[8:11]
	v_mfma_f32_16x16x32_bf16 v[4:7], v[232:235], v[188:191], v[4:7]
	v_mfma_f32_16x16x32_bf16 v[0:3], v[236:239], v[188:191], v[0:3]
	s_waitcnt lgkmcnt(0)
	v_mfma_f32_16x16x32_bf16 v[124:127], v[208:211], v[192:195], v[124:127]
	ds_read_b128 v[224:227], v175 offset:8192
	v_mfma_f32_16x16x32_bf16 v[120:123], v[212:215], v[192:195], v[120:123]
	ds_read_b128 v[228:231], v175 offset:10240
	v_mfma_f32_16x16x32_bf16 v[116:119], v[216:219], v[192:195], v[116:119]
	ds_read_b128 v[232:235], v175 offset:12288
	v_mfma_f32_16x16x32_bf16 v[112:115], v[220:223], v[192:195], v[112:115]
	ds_read_b128 v[236:239], v175 offset:14336
	v_mfma_f32_16x16x32_bf16 v[92:95], v[208:211], v[196:199], v[92:95]
	v_mfma_f32_16x16x32_bf16 v[88:91], v[212:215], v[196:199], v[88:91]
	v_mfma_f32_16x16x32_bf16 v[84:87], v[216:219], v[196:199], v[84:87]
	v_mfma_f32_16x16x32_bf16 v[80:83], v[220:223], v[196:199], v[80:83]
	v_mfma_f32_16x16x32_bf16 v[60:63], v[208:211], v[200:203], v[60:63]
	v_mfma_f32_16x16x32_bf16 v[56:59], v[212:215], v[200:203], v[56:59]
	v_mfma_f32_16x16x32_bf16 v[52:55], v[216:219], v[200:203], v[52:55]
	v_mfma_f32_16x16x32_bf16 v[48:51], v[220:223], v[200:203], v[48:51]
	v_mfma_f32_16x16x32_bf16 v[28:31], v[208:211], v[204:207], v[28:31]
	v_mfma_f32_16x16x32_bf16 v[24:27], v[212:215], v[204:207], v[24:27]
	v_mfma_f32_16x16x32_bf16 v[20:23], v[216:219], v[204:207], v[20:23]
	v_mfma_f32_16x16x32_bf16 v[16:19], v[220:223], v[204:207], v[16:19]
	s_waitcnt lgkmcnt(0)
	s_waitcnt vmcnt(0)
	s_barrier
	v_mfma_f32_16x16x32_bf16 v[108:111], v[224:227], v[192:195], v[108:111]
	ds_read_b128 v[176:179], v172 offset:0
	v_mfma_f32_16x16x32_bf16 v[104:107], v[228:231], v[192:195], v[104:107]
	ds_read_b128 v[180:183], v172 offset:2048
	v_mfma_f32_16x16x32_bf16 v[100:103], v[232:235], v[192:195], v[100:103]
	ds_read_b128 v[184:187], v172 offset:4096
	v_mfma_f32_16x16x32_bf16 v[96:99], v[236:239], v[192:195], v[96:99]
	ds_read_b128 v[188:191], v172 offset:6144
	v_mfma_f32_16x16x32_bf16 v[76:79], v[224:227], v[196:199], v[76:79]
	ds_read_b128 v[208:211], v174 offset:32768
	v_mfma_f32_16x16x32_bf16 v[72:75], v[228:231], v[196:199], v[72:75]
	ds_read_b128 v[212:215], v174 offset:34816
	v_mfma_f32_16x16x32_bf16 v[68:71], v[232:235], v[196:199], v[68:71]
	ds_read_b128 v[216:219], v174 offset:36864
	v_mfma_f32_16x16x32_bf16 v[64:67], v[236:239], v[196:199], v[64:67]
	ds_read_b128 v[220:223], v174 offset:38912
	v_mfma_f32_16x16x32_bf16 v[44:47], v[224:227], v[200:203], v[44:47]
	v_mfma_f32_16x16x32_bf16 v[40:43], v[228:231], v[200:203], v[40:43]
	v_mfma_f32_16x16x32_bf16 v[36:39], v[232:235], v[200:203], v[36:39]
	v_mfma_f32_16x16x32_bf16 v[32:35], v[236:239], v[200:203], v[32:35]
	v_mfma_f32_16x16x32_bf16 v[12:15], v[224:227], v[204:207], v[12:15]
	v_mfma_f32_16x16x32_bf16 v[8:11], v[228:231], v[204:207], v[8:11]
	v_mfma_f32_16x16x32_bf16 v[4:7], v[232:235], v[204:207], v[4:7]
	v_mfma_f32_16x16x32_bf16 v[0:3], v[236:239], v[204:207], v[0:3]
	s_waitcnt lgkmcnt(0)
	v_mfma_f32_16x16x32_bf16 v[124:127], v[208:211], v[176:179], v[124:127]
	ds_read_b128 v[224:227], v174 offset:40960
	v_mfma_f32_16x16x32_bf16 v[120:123], v[212:215], v[176:179], v[120:123]
	ds_read_b128 v[228:231], v174 offset:43008
	v_mfma_f32_16x16x32_bf16 v[116:119], v[216:219], v[176:179], v[116:119]
	ds_read_b128 v[232:235], v174 offset:45056
	v_mfma_f32_16x16x32_bf16 v[112:115], v[220:223], v[176:179], v[112:115]
	ds_read_b128 v[236:239], v174 offset:47104
	v_mfma_f32_16x16x32_bf16 v[92:95], v[208:211], v[180:183], v[92:95]
	v_mfma_f32_16x16x32_bf16 v[88:91], v[212:215], v[180:183], v[88:91]
	v_mfma_f32_16x16x32_bf16 v[84:87], v[216:219], v[180:183], v[84:87]
	v_mfma_f32_16x16x32_bf16 v[80:83], v[220:223], v[180:183], v[80:83]
	v_mfma_f32_16x16x32_bf16 v[60:63], v[208:211], v[184:187], v[60:63]
	v_mfma_f32_16x16x32_bf16 v[56:59], v[212:215], v[184:187], v[56:59]
	v_mfma_f32_16x16x32_bf16 v[52:55], v[216:219], v[184:187], v[52:55]
	v_mfma_f32_16x16x32_bf16 v[48:51], v[220:223], v[184:187], v[48:51]
	v_mfma_f32_16x16x32_bf16 v[28:31], v[208:211], v[188:191], v[28:31]
	v_mfma_f32_16x16x32_bf16 v[24:27], v[212:215], v[188:191], v[24:27]
	v_mfma_f32_16x16x32_bf16 v[20:23], v[216:219], v[188:191], v[20:23]
	v_mfma_f32_16x16x32_bf16 v[16:19], v[220:223], v[188:191], v[16:19]
	s_waitcnt lgkmcnt(0)
	v_mfma_f32_16x16x32_bf16 v[108:111], v[224:227], v[176:179], v[108:111]
	ds_read_b128 v[192:195], v173 offset:0
	v_mfma_f32_16x16x32_bf16 v[104:107], v[228:231], v[176:179], v[104:107]
	ds_read_b128 v[196:199], v173 offset:2048
	v_mfma_f32_16x16x32_bf16 v[100:103], v[232:235], v[176:179], v[100:103]
	ds_read_b128 v[200:203], v173 offset:4096
	v_mfma_f32_16x16x32_bf16 v[96:99], v[236:239], v[176:179], v[96:99]
	ds_read_b128 v[204:207], v173 offset:6144
	v_mfma_f32_16x16x32_bf16 v[76:79], v[224:227], v[180:183], v[76:79]
	ds_read_b128 v[208:211], v175 offset:32768
	v_mfma_f32_16x16x32_bf16 v[72:75], v[228:231], v[180:183], v[72:75]
	ds_read_b128 v[212:215], v175 offset:34816
	v_mfma_f32_16x16x32_bf16 v[68:71], v[232:235], v[180:183], v[68:71]
	ds_read_b128 v[216:219], v175 offset:36864
	v_mfma_f32_16x16x32_bf16 v[64:67], v[236:239], v[180:183], v[64:67]
	ds_read_b128 v[220:223], v175 offset:38912
	v_mfma_f32_16x16x32_bf16 v[44:47], v[224:227], v[184:187], v[44:47]
	v_mfma_f32_16x16x32_bf16 v[40:43], v[228:231], v[184:187], v[40:43]
	v_mfma_f32_16x16x32_bf16 v[36:39], v[232:235], v[184:187], v[36:39]
	v_mfma_f32_16x16x32_bf16 v[32:35], v[236:239], v[184:187], v[32:35]
	v_mfma_f32_16x16x32_bf16 v[12:15], v[224:227], v[188:191], v[12:15]
	v_mfma_f32_16x16x32_bf16 v[8:11], v[228:231], v[188:191], v[8:11]
	v_mfma_f32_16x16x32_bf16 v[4:7], v[232:235], v[188:191], v[4:7]
	v_mfma_f32_16x16x32_bf16 v[0:3], v[236:239], v[188:191], v[0:3]
	s_waitcnt lgkmcnt(0)
	v_mfma_f32_16x16x32_bf16 v[124:127], v[208:211], v[192:195], v[124:127]
	ds_read_b128 v[224:227], v175 offset:40960
	v_mfma_f32_16x16x32_bf16 v[120:123], v[212:215], v[192:195], v[120:123]
	ds_read_b128 v[228:231], v175 offset:43008
	v_mfma_f32_16x16x32_bf16 v[116:119], v[216:219], v[192:195], v[116:119]
	ds_read_b128 v[232:235], v175 offset:45056
	v_mfma_f32_16x16x32_bf16 v[112:115], v[220:223], v[192:195], v[112:115]
	ds_read_b128 v[236:239], v175 offset:47104
	v_mfma_f32_16x16x32_bf16 v[92:95], v[208:211], v[196:199], v[92:95]
	v_mfma_f32_16x16x32_bf16 v[88:91], v[212:215], v[196:199], v[88:91]
	v_mfma_f32_16x16x32_bf16 v[84:87], v[216:219], v[196:199], v[84:87]
	v_mfma_f32_16x16x32_bf16 v[80:83], v[220:223], v[196:199], v[80:83]
	v_mfma_f32_16x16x32_bf16 v[60:63], v[208:211], v[200:203], v[60:63]
	v_mfma_f32_16x16x32_bf16 v[56:59], v[212:215], v[200:203], v[56:59]
	v_mfma_f32_16x16x32_bf16 v[52:55], v[216:219], v[200:203], v[52:55]
	v_mfma_f32_16x16x32_bf16 v[48:51], v[220:223], v[200:203], v[48:51]
	v_mfma_f32_16x16x32_bf16 v[28:31], v[208:211], v[204:207], v[28:31]
	v_mfma_f32_16x16x32_bf16 v[24:27], v[212:215], v[204:207], v[24:27]
	v_mfma_f32_16x16x32_bf16 v[20:23], v[216:219], v[204:207], v[20:23]
	v_mfma_f32_16x16x32_bf16 v[16:19], v[220:223], v[204:207], v[16:19]
	s_waitcnt lgkmcnt(0)
	s_barrier
	v_mfma_f32_16x16x32_bf16 v[108:111], v[224:227], v[192:195], v[108:111]
	v_mfma_f32_16x16x32_bf16 v[104:107], v[228:231], v[192:195], v[104:107]
	v_mfma_f32_16x16x32_bf16 v[100:103], v[232:235], v[192:195], v[100:103]
	v_mfma_f32_16x16x32_bf16 v[96:99], v[236:239], v[192:195], v[96:99]
	v_mfma_f32_16x16x32_bf16 v[76:79], v[224:227], v[196:199], v[76:79]
	v_mfma_f32_16x16x32_bf16 v[72:75], v[228:231], v[196:199], v[72:75]
	v_mfma_f32_16x16x32_bf16 v[68:71], v[232:235], v[196:199], v[68:71]
	v_mfma_f32_16x16x32_bf16 v[64:67], v[236:239], v[196:199], v[64:67]
	v_mfma_f32_16x16x32_bf16 v[44:47], v[224:227], v[200:203], v[44:47]
	v_mfma_f32_16x16x32_bf16 v[40:43], v[228:231], v[200:203], v[40:43]
	v_mfma_f32_16x16x32_bf16 v[36:39], v[232:235], v[200:203], v[36:39]
	v_mfma_f32_16x16x32_bf16 v[32:35], v[236:239], v[200:203], v[32:35]
	v_mfma_f32_16x16x32_bf16 v[12:15], v[224:227], v[204:207], v[12:15]
	v_mfma_f32_16x16x32_bf16 v[8:11], v[228:231], v[204:207], v[8:11]
	v_mfma_f32_16x16x32_bf16 v[4:7], v[232:235], v[204:207], v[4:7]
	v_mfma_f32_16x16x32_bf16 v[0:3], v[236:239], v[204:207], v[0:3]
	s_nop 7
	s_nop 3
	s_branch .LBB0_1124
